# combined: accumulate-chain MFMA order + matrix-pipe hand-over (prio/barrier placement) + FU staging loads 4/4
# speedup vs baseline: 1.0104x; 1.0104x over previous
; #define PG8_STAGE(bufoff, gbase, voff) do { _Pragma("unroll") for (int _i = 0; _i < 2; ++_i) \
;         __builtin_amdgcn_global_load_lds((const unsigned*)((const char*)(gbase) + (voff)[_i]), (PG8_LAS unsigned*)(lds + (bufoff) + ldsw + _i * 8192), 16, 0, AUX_A); } while (0)
; #define PG8_STAGEB(bufoff, gbase, voff) do { _Pragma("unroll") for (int _i = 0; _i < 2; ++_i) \
;         __builtin_amdgcn_global_load_lds((const unsigned*)((const char*)(gbase) + (voff)[_i]), (PG8_LAS unsigned*)(lds + (bufoff) + ldsw + _i * 8192), 16, 0, AUX_B); } while (0)
; #define PG8_LDA(dst, b, h) do { _Pragma("unroll") for (int m = 0; m < 4; ++m) _Pragma("unroll") for (int k = 0; k < 2; ++k) dst[m][k] = *(const PG8_LAS bf16x8*)(lds + PG8_SA(b, h) + aoff + m * 2048 + k * 1024); } while (0)
; #define PG8_LDB(dst, b, h) do { _Pragma("unroll") for (int n = 0; n < 2; ++n) _Pragma("unroll") for (int k = 0; k < 2; ++k) dst[n][k] = *(const PG8_LAS bf16x8*)(lds + PG8_SB(b, h) + boff + n * 2048 + k * 1024); } while (0)
; #define PG8_WAIT_V(n) asm volatile("s_waitcnt vmcnt(" #n ")" ::: "memory")
; #define PG8_WAIT_L(n) asm volatile("s_waitcnt lgkmcnt(" #n ")" ::: "memory")
; #define PG8_BAR __builtin_amdgcn_s_barrier()
; #define PG8_SCHED __builtin_amdgcn_sched_barrier(0)
; template <class Epi, class Sched, bool ALIGN_EPI = false, bool SP2 = false>
; __device__ __forceinline__ void gemm_phase(PG8_LAS unsigned char* lds, const Gemm g, const Sched& S, const Epi& E) {
;     ...
;         for (int t = 0; t < nt; t += 2) {
;             const bool last = (t == nt - 2);
;             const char* a1 = PG8_KP(cA, t + 1, rot, nt);
;             const char* a2 = last ? nAr : PG8_KP(cA, t + 2, rot, nt); const char* b2 = last ? nBr : PG8_KP(cB, t + 2, rot, nt);
;             const char* a3 = a2 + kstep; const char* b3 = b2 + kstep;
;             if (last && has_next) S.a_ready(nxt);
;             if constexpr (SP2) {
;             PG8_LDB(B0, 0, 0); PG8_LDB(B1, 0, 1); PG8_SCHED; PG8_LDA(At, 0, 0); PG8_STAGE(PG8_SA(1, 1), a1 + hstep, voffA);
;             PG8_WAIT_V(8); PG8_WAIT_L(0); PG8_BAR; PG8_MMA(0, 0, At, B0); PG8_MMA(0, 1, At, B1); PG8_BAR; PG8_SCHED;
;             PG8_LDA(At, 0, 1); PG8_STAGEB(PG8_SB(0, 0), b2, voffB); PG8_STAGEB(PG8_SB(0, 1), b2 + hstep, voffB); PG8_STAGE(PG8_SA(0, 0), a2, voffA);
.LBB0_270:
	s_add_i32 s81, s29, 2
	s_cmp_lt_u32 s29, 30
	s_cselect_b32 s0, 0, 0xffffffe0
	s_add_i32 s0, s81, s0
	s_ashr_i32 s1, s0, 31
	s_lshl_b64 s[0:1], s[0:1], 7
	s_add_u32 s42, s40, s0
	s_addc_u32 s43, s41, s1
	s_add_u32 s0, s38, s0
	s_addc_u32 s1, s39, s1
	s_cmp_eq_u32 s29, 30
	s_cselect_b32 s59, s49, s43
	s_cselect_b32 s58, s51, s42
	s_cselect_b32 s61, vcc_lo, s1
	s_cselect_b32 s60, vcc_hi, s0
	s_add_i32 s43, 0, 0x10000
	s_add_i32 s97, s43, s70
	s_add_i32 s46, 0, 0x14000
	s_add_i32 m0, s96, 0xc000
	s_add_i32 s69, s96, 0xe000
	s_add_i32 s84, s97, 0x2000
	s_add_u32 s62, s60, 0x80000
	s_addc_u32 s63, s61, 0
	s_add_i32 s4, s46, s70
	v_add_u32_e32 v148, s43, v221
	v_add_u32_e32 v164, s46, v221
	s_add_i32 s5, s4, 0x2000
	s_add_i32 s1, 0, 0x18000
	s_add_i32 s47, 0, 0x1c000
	ds_read_b128 v[136:139], v148
	ds_read_b128 v[140:143], v148 offset:1024
	ds_read_b128 v[144:147], v148 offset:2048
	ds_read_b128 v[148:151], v148 offset:3072
	ds_read_b128 v[152:155], v164
	ds_read_b128 v[156:159], v164 offset:1024
	ds_read_b128 v[160:163], v164 offset:2048
	ds_read_b128 v[164:167], v164 offset:3072
	s_add_u32 s56, s58, 0x80000
	s_addc_u32 s57, s59, 0
	s_add_i32 s0, s1, s70
	s_add_i32 s89, s0, 0x2000
	s_add_u32 s42, s60, 0x80080
	s_addc_u32 s43, s61, 0
	s_add_i32 s46, s47, s70
	s_add_i32 s92, s46, 0x2000
	s_cmp_gt_u32 s29, 29
	ds_read_b128 v[192:195], v222
	ds_read_b128 v[196:199], v222 offset:1024
	ds_read_b128 v[200:203], v222 offset:2048
	ds_read_b128 v[224:227], v222 offset:3072
	ds_read_b128 v[228:231], v222 offset:4096
	ds_read_b128 v[232:235], v222 offset:5120
	ds_read_b128 v[236:239], v222 offset:6144
	ds_read_b128 v[240:243], v222 offset:7168
	global_load_lds_dwordx4 v[134:135], off
	s_mov_b32 m0, s69
	s_nop 0
	global_load_lds_dwordx4 v[132:133], off
	s_waitcnt vmcnt(8)
	s_waitcnt lgkmcnt(0)
	s_setprio 1
	s_barrier
	v_mfma_f32_16x16x32_bf16 v[128:131], v[136:139], v[192:195], v[128:131]
	v_mfma_f32_16x16x32_bf16 v[128:131], v[140:143], v[196:199], v[128:131]
	v_mfma_f32_16x16x32_bf16 v[124:127], v[144:147], v[192:195], v[124:127]
	v_mfma_f32_16x16x32_bf16 v[124:127], v[148:151], v[196:199], v[124:127]
	v_mfma_f32_16x16x32_bf16 v[112:115], v[136:139], v[200:203], v[112:115]
	v_mfma_f32_16x16x32_bf16 v[112:115], v[140:143], v[224:227], v[112:115]
	v_mfma_f32_16x16x32_bf16 v[108:111], v[144:147], v[200:203], v[108:111]
	v_mfma_f32_16x16x32_bf16 v[108:111], v[148:151], v[224:227], v[108:111]
	v_mfma_f32_16x16x32_bf16 v[94:97], v[136:139], v[228:231], v[94:97]
	v_mfma_f32_16x16x32_bf16 v[94:97], v[140:143], v[232:235], v[94:97]
	v_mfma_f32_16x16x32_bf16 v[90:93], v[144:147], v[228:231], v[90:93]
	v_mfma_f32_16x16x32_bf16 v[90:93], v[148:151], v[232:235], v[90:93]
	v_mfma_f32_16x16x32_bf16 v[78:81], v[136:139], v[236:239], v[78:81]
	v_mfma_f32_16x16x32_bf16 v[78:81], v[140:143], v[240:243], v[78:81]
	v_mfma_f32_16x16x32_bf16 v[74:77], v[144:147], v[236:239], v[74:77]
	v_mfma_f32_16x16x32_bf16 v[74:77], v[148:151], v[240:243], v[74:77]
	s_setprio 0
	s_setprio 1
	v_mfma_f32_16x16x32_bf16 v[120:123], v[152:155], v[192:195], v[120:123]
	v_mfma_f32_16x16x32_bf16 v[120:123], v[156:159], v[196:199], v[120:123]
	v_mfma_f32_16x16x32_bf16 v[116:119], v[160:163], v[192:195], v[116:119]
	v_mfma_f32_16x16x32_bf16 v[116:119], v[164:167], v[196:199], v[116:119]
	v_mfma_f32_16x16x32_bf16 v[104:107], v[152:155], v[200:203], v[104:107]
	v_mfma_f32_16x16x32_bf16 v[104:107], v[156:159], v[224:227], v[104:107]
	v_mfma_f32_16x16x32_bf16 v[100:103], v[160:163], v[200:203], v[100:103]
	v_mfma_f32_16x16x32_bf16 v[100:103], v[164:167], v[224:227], v[100:103]
	v_mfma_f32_16x16x32_bf16 v[86:89], v[152:155], v[228:231], v[86:89]
	v_mfma_f32_16x16x32_bf16 v[86:89], v[156:159], v[232:235], v[86:89]
	v_mfma_f32_16x16x32_bf16 v[82:85], v[160:163], v[228:231], v[82:85]
	v_mfma_f32_16x16x32_bf16 v[82:85], v[164:167], v[232:235], v[82:85]
	v_mfma_f32_16x16x32_bf16 v[70:73], v[152:155], v[236:239], v[70:73]
	v_mfma_f32_16x16x32_bf16 v[70:73], v[156:159], v[240:243], v[70:73]
	s_setprio 2
	s_barrier
	v_mfma_f32_16x16x32_bf16 v[66:69], v[160:163], v[236:239], v[66:69]
	v_mfma_f32_16x16x32_bf16 v[66:69], v[164:167], v[240:243], v[66:69]
	s_setprio 0
	s_mov_b32 m0, s97
	v_lshl_add_u64 v[244:245], s[60:61], 0, v[184:185]
	ds_read_b128 v[192:195], v222 offset:16384
	ds_read_b128 v[196:199], v222 offset:17408
	ds_read_b128 v[200:203], v222 offset:18432
	ds_read_b128 v[224:227], v222 offset:19456
	ds_read_b128 v[228:231], v222 offset:20480
	ds_read_b128 v[232:235], v222 offset:21504
	ds_read_b128 v[236:239], v222 offset:22528
	ds_read_b128 v[240:243], v222 offset:23552
	global_load_lds_dwordx4 v[244:245], off
	v_lshl_add_u64 v[246:247], s[60:61], 0, v[180:181]
	s_mov_b32 m0, s84
	v_lshl_add_u64 v[212:213], s[62:63], 0, v[184:185]
	global_load_lds_dwordx4 v[246:247], off
	s_mov_b32 m0, s4
	v_lshl_add_u64 v[172:173], s[58:59], 0, v[182:183]
	global_load_lds_dwordx4 v[212:213], off
	v_lshl_add_u64 v[212:213], s[62:63], 0, v[180:181]
	s_mov_b32 m0, s5
	s_nop 0
	global_load_lds_dwordx4 v[212:213], off
	v_lshl_add_u64 v[212:213], s[58:59], 0, v[186:187]
	s_mov_b32 m0, s96
	s_nop 0
	global_load_lds_dwordx4 v[212:213], off
	s_mov_b32 m0, s71
	s_nop 0
	global_load_lds_dwordx4 v[172:173], off
	s_waitcnt vmcnt(8)
	s_waitcnt lgkmcnt(0)
	s_setprio 1
	s_barrier
; #define PG8_STAGE(bufoff, gbase, voff) do { _Pragma("unroll") for (int _i = 0; _i < 2; ++_i) \
;         __builtin_amdgcn_global_load_lds((const unsigned*)((const char*)(gbase) + (voff)[_i]), (PG8_LAS unsigned*)(lds + (bufoff) + ldsw + _i * 8192), 16, 0, AUX_A); } while (0)
; #define PG8_LDA(dst, b, h) do { _Pragma("unroll") for (int m = 0; m < 4; ++m) _Pragma("unroll") for (int k = 0; k < 2; ++k) dst[m][k] = *(const PG8_LAS bf16x8*)(lds + PG8_SA(b, h) + aoff + m * 2048 + k * 1024); } while (0)
; #define PG8_LDB(dst, b, h) do { _Pragma("unroll") for (int n = 0; n < 2; ++n) _Pragma("unroll") for (int k = 0; k < 2; ++k) dst[n][k] = *(const PG8_LAS bf16x8*)(lds + PG8_SB(b, h) + boff + n * 2048 + k * 1024); } while (0)
; #define PG8_MMA(ai, bj, At, Bt) do { __builtin_amdgcn_s_setprio(1); _Pragma("unroll") for (int m = 0; m < 4; ++m) _Pragma("unroll") for (int n = 0; n < 2; ++n) _Pragma("unroll") for (int k = 0; k < 2; ++k) \
;         acc[ai][bj][m][n] = __builtin_amdgcn_mfma_f32_16x16x32_bf16(Bt[n][k], At[m][k], acc[ai][bj][m][n], 0, 0, 0); __builtin_amdgcn_s_setprio(0); } while (0)
; #define PG8_WAIT_V(n) asm volatile("s_waitcnt vmcnt(" #n ")" ::: "memory")
; #define PG8_WAIT_L(n) asm volatile("s_waitcnt lgkmcnt(" #n ")" ::: "memory")
; #define PG8_BAR __builtin_amdgcn_s_barrier()
; #define PG8_SCHED __builtin_amdgcn_sched_barrier(0)
; template <class Epi, class Sched, bool ALIGN_EPI = false, bool SP2 = false>
; __device__ __forceinline__ void gemm_phase(PG8_LAS unsigned char* lds, const Gemm g, const Sched& S, const Epi& E) {
;     ...
;             PG8_WAIT_V(8); PG8_WAIT_L(0); PG8_BAR; PG8_MMA(1, 0, At, B0); PG8_MMA(1, 1, At, B1); PG8_BAR; PG8_SCHED;
;             PG8_LDB(B0, 1, 0); PG8_LDB(B1, 1, 1); PG8_SCHED; PG8_LDA(At, 1, 0); PG8_STAGE(PG8_SA(0, 1), a2 + hstep, voffA);
;             PG8_WAIT_V(8); PG8_WAIT_L(0); PG8_BAR; PG8_MMA(0, 0, At, B0); PG8_MMA(0, 1, At, B1); PG8_BAR; PG8_SCHED;
	v_mfma_f32_16x16x32_bf16 v[62:65], v[136:139], v[192:195], v[62:65]
	v_mfma_f32_16x16x32_bf16 v[62:65], v[140:143], v[196:199], v[62:65]
	v_mfma_f32_16x16x32_bf16 v[58:61], v[144:147], v[192:195], v[58:61]
	v_mfma_f32_16x16x32_bf16 v[58:61], v[148:151], v[196:199], v[58:61]
	v_mfma_f32_16x16x32_bf16 v[46:49], v[136:139], v[200:203], v[46:49]
	v_mfma_f32_16x16x32_bf16 v[46:49], v[140:143], v[224:227], v[46:49]
	v_mfma_f32_16x16x32_bf16 v[42:45], v[144:147], v[200:203], v[42:45]
	v_mfma_f32_16x16x32_bf16 v[42:45], v[148:151], v[224:227], v[42:45]
	v_mfma_f32_16x16x32_bf16 v[30:33], v[136:139], v[228:231], v[30:33]
	v_mfma_f32_16x16x32_bf16 v[30:33], v[140:143], v[232:235], v[30:33]
	v_mfma_f32_16x16x32_bf16 v[26:29], v[144:147], v[228:231], v[26:29]
	v_mfma_f32_16x16x32_bf16 v[26:29], v[148:151], v[232:235], v[26:29]
	v_mfma_f32_16x16x32_bf16 v[14:17], v[136:139], v[236:239], v[14:17]
	v_mfma_f32_16x16x32_bf16 v[14:17], v[140:143], v[240:243], v[14:17]
	v_mfma_f32_16x16x32_bf16 v[10:13], v[144:147], v[236:239], v[10:13]
	v_mfma_f32_16x16x32_bf16 v[10:13], v[148:151], v[240:243], v[10:13]
	s_setprio 0
	s_setprio 1
	v_mfma_f32_16x16x32_bf16 v[54:57], v[152:155], v[192:195], v[54:57]
	v_mfma_f32_16x16x32_bf16 v[54:57], v[156:159], v[196:199], v[54:57]
	v_mfma_f32_16x16x32_bf16 v[50:53], v[160:163], v[192:195], v[50:53]
	v_mfma_f32_16x16x32_bf16 v[50:53], v[164:167], v[196:199], v[50:53]
	v_mfma_f32_16x16x32_bf16 v[38:41], v[152:155], v[200:203], v[38:41]
	v_mfma_f32_16x16x32_bf16 v[38:41], v[156:159], v[224:227], v[38:41]
	v_mfma_f32_16x16x32_bf16 v[34:37], v[160:163], v[200:203], v[34:37]
	v_mfma_f32_16x16x32_bf16 v[34:37], v[164:167], v[224:227], v[34:37]
	v_mfma_f32_16x16x32_bf16 v[22:25], v[152:155], v[228:231], v[22:25]
	v_mfma_f32_16x16x32_bf16 v[22:25], v[156:159], v[232:235], v[22:25]
	v_mfma_f32_16x16x32_bf16 v[18:21], v[160:163], v[228:231], v[18:21]
	v_mfma_f32_16x16x32_bf16 v[18:21], v[164:167], v[232:235], v[18:21]
	v_mfma_f32_16x16x32_bf16 v[6:9], v[152:155], v[236:239], v[6:9]
	v_mfma_f32_16x16x32_bf16 v[6:9], v[156:159], v[240:243], v[6:9]
	s_setprio 2
	s_barrier
	v_mfma_f32_16x16x32_bf16 v[2:5], v[160:163], v[236:239], v[2:5]
	v_mfma_f32_16x16x32_bf16 v[2:5], v[164:167], v[240:243], v[2:5]
	s_setprio 0
	v_add_u32_e32 v148, s1, v221
	v_add_u32_e32 v164, s47, v221
	ds_read_b128 v[136:139], v148
	ds_read_b128 v[140:143], v148 offset:1024
	ds_read_b128 v[144:147], v148 offset:2048
	ds_read_b128 v[148:151], v148 offset:3072
	ds_read_b128 v[152:155], v164
	ds_read_b128 v[156:159], v164 offset:1024
	ds_read_b128 v[160:163], v164 offset:2048
	ds_read_b128 v[164:167], v164 offset:3072
	s_mov_b32 m0, s33
	v_lshl_add_u64 v[168:169], s[56:57], 0, v[186:187]
	ds_read_b128 v[192:195], v222 offset:32768
	ds_read_b128 v[196:199], v222 offset:33792
	ds_read_b128 v[200:203], v222 offset:34816
	ds_read_b128 v[224:227], v222 offset:35840
	ds_read_b128 v[228:231], v222 offset:36864
	ds_read_b128 v[232:235], v222 offset:37888
	ds_read_b128 v[236:239], v222 offset:38912
	ds_read_b128 v[240:243], v222 offset:39936
	global_load_lds_dwordx4 v[168:169], off
	v_lshl_add_u64 v[168:169], s[56:57], 0, v[182:183]
	s_mov_b32 m0, s30
	s_nop 0
	global_load_lds_dwordx4 v[168:169], off
	s_waitcnt vmcnt(8)
	s_waitcnt lgkmcnt(0)
	s_setprio 1
	s_barrier
	v_mfma_f32_16x16x32_bf16 v[128:131], v[136:139], v[192:195], v[128:131]
	v_mfma_f32_16x16x32_bf16 v[128:131], v[140:143], v[196:199], v[128:131]
	v_mfma_f32_16x16x32_bf16 v[124:127], v[144:147], v[192:195], v[124:127]
	v_mfma_f32_16x16x32_bf16 v[124:127], v[148:151], v[196:199], v[124:127]
	v_mfma_f32_16x16x32_bf16 v[112:115], v[136:139], v[200:203], v[112:115]
	v_mfma_f32_16x16x32_bf16 v[112:115], v[140:143], v[224:227], v[112:115]
	v_mfma_f32_16x16x32_bf16 v[108:111], v[144:147], v[200:203], v[108:111]
	v_mfma_f32_16x16x32_bf16 v[108:111], v[148:151], v[224:227], v[108:111]
	v_mfma_f32_16x16x32_bf16 v[94:97], v[136:139], v[228:231], v[94:97]
	v_mfma_f32_16x16x32_bf16 v[94:97], v[140:143], v[232:235], v[94:97]
	v_mfma_f32_16x16x32_bf16 v[90:93], v[144:147], v[228:231], v[90:93]
	v_mfma_f32_16x16x32_bf16 v[90:93], v[148:151], v[232:235], v[90:93]
	v_mfma_f32_16x16x32_bf16 v[78:81], v[136:139], v[236:239], v[78:81]
	v_mfma_f32_16x16x32_bf16 v[78:81], v[140:143], v[240:243], v[78:81]
	v_mfma_f32_16x16x32_bf16 v[74:77], v[144:147], v[236:239], v[74:77]
	v_mfma_f32_16x16x32_bf16 v[74:77], v[148:151], v[240:243], v[74:77]
	s_setprio 0
	s_setprio 1
	v_mfma_f32_16x16x32_bf16 v[120:123], v[152:155], v[192:195], v[120:123]
	v_mfma_f32_16x16x32_bf16 v[120:123], v[156:159], v[196:199], v[120:123]
	v_mfma_f32_16x16x32_bf16 v[116:119], v[160:163], v[192:195], v[116:119]
	v_mfma_f32_16x16x32_bf16 v[116:119], v[164:167], v[196:199], v[116:119]
	v_mfma_f32_16x16x32_bf16 v[104:107], v[152:155], v[200:203], v[104:107]
	v_mfma_f32_16x16x32_bf16 v[104:107], v[156:159], v[224:227], v[104:107]
	v_mfma_f32_16x16x32_bf16 v[100:103], v[160:163], v[200:203], v[100:103]
	v_mfma_f32_16x16x32_bf16 v[100:103], v[164:167], v[224:227], v[100:103]
	v_mfma_f32_16x16x32_bf16 v[86:89], v[152:155], v[228:231], v[86:89]
	v_mfma_f32_16x16x32_bf16 v[86:89], v[156:159], v[232:235], v[86:89]
	v_mfma_f32_16x16x32_bf16 v[82:85], v[160:163], v[228:231], v[82:85]
	v_mfma_f32_16x16x32_bf16 v[82:85], v[164:167], v[232:235], v[82:85]
	v_mfma_f32_16x16x32_bf16 v[70:73], v[152:155], v[236:239], v[70:73]
	v_mfma_f32_16x16x32_bf16 v[70:73], v[156:159], v[240:243], v[70:73]
	s_setprio 2
	s_barrier
; #define PG8_STAGE(bufoff, gbase, voff) do { _Pragma("unroll") for (int _i = 0; _i < 2; ++_i) \
;         __builtin_amdgcn_global_load_lds((const unsigned*)((const char*)(gbase) + (voff)[_i]), (PG8_LAS unsigned*)(lds + (bufoff) + ldsw + _i * 8192), 16, 0, AUX_A); } while (0)
; #define PG8_STAGEB(bufoff, gbase, voff) do { _Pragma("unroll") for (int _i = 0; _i < 2; ++_i) \
;         __builtin_amdgcn_global_load_lds((const unsigned*)((const char*)(gbase) + (voff)[_i]), (PG8_LAS unsigned*)(lds + (bufoff) + ldsw + _i * 8192), 16, 0, AUX_B); } while (0)
; #define PG8_LDA(dst, b, h) do { _Pragma("unroll") for (int m = 0; m < 4; ++m) _Pragma("unroll") for (int k = 0; k < 2; ++k) dst[m][k] = *(const PG8_LAS bf16x8*)(lds + PG8_SA(b, h) + aoff + m * 2048 + k * 1024); } while (0)
; #define PG8_MMA(ai, bj, At, Bt) do { __builtin_amdgcn_s_setprio(1); _Pragma("unroll") for (int m = 0; m < 4; ++m) _Pragma("unroll") for (int n = 0; n < 2; ++n) _Pragma("unroll") for (int k = 0; k < 2; ++k) \
;         acc[ai][bj][m][n] = __builtin_amdgcn_mfma_f32_16x16x32_bf16(Bt[n][k], At[m][k], acc[ai][bj][m][n], 0, 0, 0); __builtin_amdgcn_s_setprio(0); } while (0)
; #define PG8_WAIT_V(n) asm volatile("s_waitcnt vmcnt(" #n ")" ::: "memory")
; #define PG8_WAIT_L(n) asm volatile("s_waitcnt lgkmcnt(" #n ")" ::: "memory")
; #define PG8_BAR __builtin_amdgcn_s_barrier()
; #define PG8_SCHED __builtin_amdgcn_sched_barrier(0)
; template <class Epi, class Sched, bool ALIGN_EPI = false, bool SP2 = false>
; __device__ __forceinline__ void gemm_phase(PG8_LAS unsigned char* lds, const Gemm g, const Sched& S, const Epi& E) {
;     ...
;             PG8_WAIT_V(8); PG8_WAIT_L(0); PG8_BAR; PG8_MMA(0, 0, At, B0); PG8_MMA(0, 1, At, B1); PG8_BAR; PG8_SCHED;
;             PG8_LDA(At, 1, 1); PG8_STAGEB(PG8_SB(1, 0), b3, voffB); PG8_STAGEB(PG8_SB(1, 1), b3 + hstep, voffB); PG8_STAGE(PG8_SA(1, 0), a3, voffA);
;             PG8_WAIT_V(8); PG8_WAIT_L(0); PG8_BAR; PG8_MMA(1, 0, At, B0); PG8_MMA(1, 1, At, B1); PG8_BAR; PG8_SCHED;
	v_mfma_f32_16x16x32_bf16 v[66:69], v[160:163], v[236:239], v[66:69]
	v_mfma_f32_16x16x32_bf16 v[66:69], v[164:167], v[240:243], v[66:69]
	s_setprio 0
	s_mov_b32 m0, s0
	v_lshl_add_u64 v[168:169], v[244:245], 0, s[76:77]
	ds_read_b128 v[192:195], v222 offset:49152
	ds_read_b128 v[196:199], v222 offset:50176
	ds_read_b128 v[200:203], v222 offset:51200
	ds_read_b128 v[224:227], v222 offset:52224
	ds_read_b128 v[228:231], v222 offset:53248
	ds_read_b128 v[232:235], v222 offset:54272
	ds_read_b128 v[236:239], v222 offset:55296
	ds_read_b128 v[240:243], v222 offset:56320
	global_load_lds_dwordx4 v[168:169], off
	v_lshl_add_u64 v[168:169], v[246:247], 0, s[76:77]
	s_mov_b32 m0, s89
	s_nop 0
	global_load_lds_dwordx4 v[168:169], off
	v_lshl_add_u64 v[168:169], s[42:43], 0, v[184:185]
	s_mov_b32 m0, s46
	s_nop 0
	global_load_lds_dwordx4 v[168:169], off
	v_lshl_add_u64 v[168:169], s[42:43], 0, v[180:181]
	s_mov_b32 m0, s92
	s_nop 0
	global_load_lds_dwordx4 v[168:169], off
	v_lshl_add_u64 v[168:169], v[212:213], 0, s[76:77]
	s_mov_b32 m0, s90
	s_nop 0
	global_load_lds_dwordx4 v[168:169], off
	v_lshl_add_u64 v[168:169], v[172:173], 0, s[76:77]
	s_mov_b32 m0, s91
	s_nop 0
	global_load_lds_dwordx4 v[168:169], off
	s_waitcnt vmcnt(8)
	s_waitcnt lgkmcnt(0)
	s_setprio 1
	s_barrier
	v_mfma_f32_16x16x32_bf16 v[62:65], v[136:139], v[192:195], v[62:65]
	v_mfma_f32_16x16x32_bf16 v[62:65], v[140:143], v[196:199], v[62:65]
	v_mfma_f32_16x16x32_bf16 v[58:61], v[144:147], v[192:195], v[58:61]
	v_mfma_f32_16x16x32_bf16 v[58:61], v[148:151], v[196:199], v[58:61]
	v_mfma_f32_16x16x32_bf16 v[46:49], v[136:139], v[200:203], v[46:49]
	v_mfma_f32_16x16x32_bf16 v[46:49], v[140:143], v[224:227], v[46:49]
	v_mfma_f32_16x16x32_bf16 v[42:45], v[144:147], v[200:203], v[42:45]
	v_mfma_f32_16x16x32_bf16 v[42:45], v[148:151], v[224:227], v[42:45]
	v_mfma_f32_16x16x32_bf16 v[30:33], v[136:139], v[228:231], v[30:33]
	v_mfma_f32_16x16x32_bf16 v[30:33], v[140:143], v[232:235], v[30:33]
	v_mfma_f32_16x16x32_bf16 v[26:29], v[144:147], v[228:231], v[26:29]
	v_mfma_f32_16x16x32_bf16 v[26:29], v[148:151], v[232:235], v[26:29]
	v_mfma_f32_16x16x32_bf16 v[14:17], v[136:139], v[236:239], v[14:17]
	v_mfma_f32_16x16x32_bf16 v[14:17], v[140:143], v[240:243], v[14:17]
	v_mfma_f32_16x16x32_bf16 v[10:13], v[144:147], v[236:239], v[10:13]
	v_mfma_f32_16x16x32_bf16 v[10:13], v[148:151], v[240:243], v[10:13]
	s_setprio 0
	s_setprio 1
	v_mfma_f32_16x16x32_bf16 v[54:57], v[152:155], v[192:195], v[54:57]
	v_mfma_f32_16x16x32_bf16 v[54:57], v[156:159], v[196:199], v[54:57]
	v_mfma_f32_16x16x32_bf16 v[50:53], v[160:163], v[192:195], v[50:53]
	v_mfma_f32_16x16x32_bf16 v[50:53], v[164:167], v[196:199], v[50:53]
	v_mfma_f32_16x16x32_bf16 v[38:41], v[152:155], v[200:203], v[38:41]
	v_mfma_f32_16x16x32_bf16 v[38:41], v[156:159], v[224:227], v[38:41]
	v_mfma_f32_16x16x32_bf16 v[34:37], v[160:163], v[200:203], v[34:37]
	v_mfma_f32_16x16x32_bf16 v[34:37], v[164:167], v[224:227], v[34:37]
	v_mfma_f32_16x16x32_bf16 v[22:25], v[152:155], v[228:231], v[22:25]
	v_mfma_f32_16x16x32_bf16 v[22:25], v[156:159], v[232:235], v[22:25]
	v_mfma_f32_16x16x32_bf16 v[18:21], v[160:163], v[228:231], v[18:21]
	v_mfma_f32_16x16x32_bf16 v[18:21], v[164:167], v[232:235], v[18:21]
	v_mfma_f32_16x16x32_bf16 v[6:9], v[152:155], v[236:239], v[6:9]
	v_mfma_f32_16x16x32_bf16 v[6:9], v[156:159], v[240:243], v[6:9]
	s_setprio 2
	s_barrier
	v_mfma_f32_16x16x32_bf16 v[2:5], v[160:163], v[236:239], v[2:5]
	v_mfma_f32_16x16x32_bf16 v[2:5], v[164:167], v[240:243], v[2:5]
	s_setprio 0
	v_lshl_add_u64 v[132:133], v[132:133], 0, s[86:87]
	v_lshl_add_u64 v[134:135], v[134:135], 0, s[86:87]
	s_mov_b32 s29, s81
	s_cbranch_scc0 .LBB0_270
	s_and_b64 vcc, exec, s[10:11]
	s_cbranch_vccz .LBB0_273
	s_barrier

; #define PG8_STAGE(bufoff, gbase, voff) do { _Pragma("unroll") for (int _i = 0; _i < 2; ++_i) \
;         __builtin_amdgcn_global_load_lds((const unsigned*)((const char*)(gbase) + (voff)[_i]), (PG8_LAS unsigned*)(lds + (bufoff) + ldsw + _i * 8192), 16, 0, AUX_A); } while (0)
; #define PG8_STAGEB(bufoff, gbase, voff) do { _Pragma("unroll") for (int _i = 0; _i < 2; ++_i) \
;         __builtin_amdgcn_global_load_lds((const unsigned*)((const char*)(gbase) + (voff)[_i]), (PG8_LAS unsigned*)(lds + (bufoff) + ldsw + _i * 8192), 16, 0, AUX_B); } while (0)
; #define PG8_LDA(dst, b, h) do { _Pragma("unroll") for (int m = 0; m < 4; ++m) _Pragma("unroll") for (int k = 0; k < 2; ++k) dst[m][k] = *(const PG8_LAS bf16x8*)(lds + PG8_SA(b, h) + aoff + m * 2048 + k * 1024); } while (0)
; #define PG8_LDB(dst, b, h) do { _Pragma("unroll") for (int n = 0; n < 2; ++n) _Pragma("unroll") for (int k = 0; k < 2; ++k) dst[n][k] = *(const PG8_LAS bf16x8*)(lds + PG8_SB(b, h) + boff + n * 2048 + k * 1024); } while (0)
; #define PG8_WAIT_V(n) asm volatile("s_waitcnt vmcnt(" #n ")" ::: "memory")
; #define PG8_WAIT_L(n) asm volatile("s_waitcnt lgkmcnt(" #n ")" ::: "memory")
; #define PG8_BAR __builtin_amdgcn_s_barrier()
; #define PG8_SCHED __builtin_amdgcn_sched_barrier(0)
; template <class Epi, class Sched, bool ALIGN_EPI = false, bool SP2 = false>
; __device__ __forceinline__ void gemm_phase(PG8_LAS unsigned char* lds, const Gemm g, const Sched& S, const Epi& E) {
;     ...
;         for (int t = 0; t < nt; t += 2) {
;             const bool last = (t == nt - 2);
;             const char* a1 = PG8_KP(cA, t + 1, rot, nt);
;             const char* a2 = last ? nAr : PG8_KP(cA, t + 2, rot, nt); const char* b2 = last ? nBr : PG8_KP(cB, t + 2, rot, nt);
;             const char* a3 = a2 + kstep; const char* b3 = b2 + kstep;
;             if (last && has_next) S.a_ready(nxt);
;             if constexpr (SP2) {
;             PG8_LDB(B0, 0, 0); PG8_LDB(B1, 0, 1); PG8_SCHED; PG8_LDA(At, 0, 0); PG8_STAGE(PG8_SA(1, 1), a1 + hstep, voffA);
;             PG8_WAIT_V(8); PG8_WAIT_L(0); PG8_BAR; PG8_MMA(0, 0, At, B0); PG8_MMA(0, 1, At, B1); PG8_BAR; PG8_SCHED;
;             PG8_LDA(At, 0, 1); PG8_STAGEB(PG8_SB(0, 0), b2, voffB); PG8_STAGEB(PG8_SB(0, 1), b2 + hstep, voffB); PG8_STAGE(PG8_SA(0, 0), a2, voffA);
.LBB0_936:
	s_add_i32 s81, s29, 2
	s_cmp_lt_u32 s29, 14
	s_cselect_b32 s0, 0, -16
	s_add_i32 s0, s81, s0
	s_ashr_i32 s1, s0, 31
	s_lshl_b64 s[0:1], s[0:1], 7
	s_add_u32 s2, s64, s0
	s_addc_u32 s46, s65, s1
	s_add_u32 s0, s26, s0
	s_addc_u32 s1, s27, s1
	s_cmp_eq_u32 s29, 14
	s_cselect_b32 s57, s15, s46
	s_cselect_b32 s56, s17, s2
	s_cselect_b32 s59, s43, s1
	s_cselect_b32 s58, s78, s0
	s_add_i32 s2, 0, 0x10000
	s_add_i32 s83, s2, s33
	s_add_i32 s46, 0, 0x14000
	s_add_i32 m0, s25, 0xc000
	s_add_i32 s82, s25, 0xe000
	s_add_i32 s84, s83, 0x2000
	s_add_u32 s60, s58, 0x40000
	s_addc_u32 s61, s59, 0
	s_add_i32 s88, s46, s33
	v_add_u32_e32 v160, s2, v99
	v_add_u32_e32 v166, s46, v99
	s_add_i32 s89, s88, 0x2000
	s_add_i32 s90, 0, 0x18000
	s_add_i32 s91, 0, 0x1c000
	ds_read_b128 v[22:25], v160
	ds_read_b128 v[34:37], v160 offset:1024
	ds_read_b128 v[38:41], v160 offset:2048
	ds_read_b128 v[160:163], v160 offset:3072
	ds_read_b128 v[180:183], v166
	ds_read_b128 v[184:187], v166 offset:1024
	ds_read_b128 v[188:191], v166 offset:2048
	ds_read_b128 v[192:195], v166 offset:3072
	s_add_u32 s54, s56, 0x40000
	s_addc_u32 s55, s57, 0
	s_add_i32 s1, s90, s33
	s_add_i32 s0, s1, 0x2000
	s_add_u32 s52, s58, 0x40080
	s_addc_u32 s53, s59, 0
	s_add_i32 s47, s91, s33
	s_add_i32 s46, s47, 0x2000
	s_cmp_gt_u32 s29, 13
	ds_read_b128 v[196:199], v165
	ds_read_b128 v[200:203], v165 offset:1024
	ds_read_b128 v[222:225], v165 offset:2048
	ds_read_b128 v[226:229], v165 offset:3072
	ds_read_b128 v[230:233], v165 offset:4096
	ds_read_b128 v[234:237], v165 offset:5120
	ds_read_b128 v[238:241], v165 offset:6144
	ds_read_b128 v[242:245], v165 offset:7168
	global_load_lds_dwordx4 v[16:17], off
	s_mov_b32 m0, s82
	s_nop 0
	global_load_lds_dwordx4 v[14:15], off
	s_waitcnt vmcnt(8)
	s_waitcnt lgkmcnt(0)
	s_setprio 1
	s_barrier
	v_mfma_f32_16x16x32_bf16 v[144:147], v[22:25], v[196:199], v[144:147]
	v_mfma_f32_16x16x32_bf16 v[144:147], v[34:37], v[200:203], v[144:147]
	v_mfma_f32_16x16x32_bf16 v[140:143], v[38:41], v[196:199], v[140:143]
	v_mfma_f32_16x16x32_bf16 v[140:143], v[160:163], v[200:203], v[140:143]
	v_mfma_f32_16x16x32_bf16 v[128:131], v[22:25], v[222:225], v[128:131]
	v_mfma_f32_16x16x32_bf16 v[128:131], v[34:37], v[226:229], v[128:131]
	v_mfma_f32_16x16x32_bf16 v[124:127], v[38:41], v[222:225], v[124:127]
	v_mfma_f32_16x16x32_bf16 v[124:127], v[160:163], v[226:229], v[124:127]
	v_mfma_f32_16x16x32_bf16 v[112:115], v[22:25], v[230:233], v[112:115]
	v_mfma_f32_16x16x32_bf16 v[112:115], v[34:37], v[234:237], v[112:115]
	v_mfma_f32_16x16x32_bf16 v[108:111], v[38:41], v[230:233], v[108:111]
	v_mfma_f32_16x16x32_bf16 v[108:111], v[160:163], v[234:237], v[108:111]
	v_mfma_f32_16x16x32_bf16 v[94:97], v[22:25], v[238:241], v[94:97]
	v_mfma_f32_16x16x32_bf16 v[94:97], v[34:37], v[242:245], v[94:97]
	v_mfma_f32_16x16x32_bf16 v[90:93], v[38:41], v[238:241], v[90:93]
	v_mfma_f32_16x16x32_bf16 v[90:93], v[160:163], v[242:245], v[90:93]
	s_setprio 0
	s_setprio 1
	v_mfma_f32_16x16x32_bf16 v[136:139], v[180:183], v[196:199], v[136:139]
	v_mfma_f32_16x16x32_bf16 v[136:139], v[184:187], v[200:203], v[136:139]
	v_mfma_f32_16x16x32_bf16 v[132:135], v[188:191], v[196:199], v[132:135]
	v_mfma_f32_16x16x32_bf16 v[132:135], v[192:195], v[200:203], v[132:135]
	v_mfma_f32_16x16x32_bf16 v[120:123], v[180:183], v[222:225], v[120:123]
	v_mfma_f32_16x16x32_bf16 v[120:123], v[184:187], v[226:229], v[120:123]
	v_mfma_f32_16x16x32_bf16 v[116:119], v[188:191], v[222:225], v[116:119]
	v_mfma_f32_16x16x32_bf16 v[116:119], v[192:195], v[226:229], v[116:119]
	v_mfma_f32_16x16x32_bf16 v[104:107], v[180:183], v[230:233], v[104:107]
	v_mfma_f32_16x16x32_bf16 v[104:107], v[184:187], v[234:237], v[104:107]
	v_mfma_f32_16x16x32_bf16 v[100:103], v[188:191], v[230:233], v[100:103]
	v_mfma_f32_16x16x32_bf16 v[100:103], v[192:195], v[234:237], v[100:103]
	v_mfma_f32_16x16x32_bf16 v[86:89], v[180:183], v[238:241], v[86:89]
	v_mfma_f32_16x16x32_bf16 v[86:89], v[184:187], v[242:245], v[86:89]
	s_setprio 2
	s_barrier
	v_mfma_f32_16x16x32_bf16 v[82:85], v[188:191], v[238:241], v[82:85]
	v_mfma_f32_16x16x32_bf16 v[82:85], v[192:195], v[242:245], v[82:85]
	s_setprio 0
	s_mov_b32 m0, s83
	v_lshl_add_u64 v[166:167], s[58:59], 0, v[150:151]
	ds_read_b128 v[196:199], v165 offset:16384
	ds_read_b128 v[200:203], v165 offset:17408
	ds_read_b128 v[222:225], v165 offset:18432
	ds_read_b128 v[226:229], v165 offset:19456
	ds_read_b128 v[230:233], v165 offset:20480
	ds_read_b128 v[234:237], v165 offset:21504
	ds_read_b128 v[238:241], v165 offset:22528
	ds_read_b128 v[242:245], v165 offset:23552
	global_load_lds_dwordx4 v[166:167], off
	v_lshl_add_u64 v[168:169], s[58:59], 0, v[154:155]
	s_mov_b32 m0, s84
	v_lshl_add_u64 v[172:173], s[60:61], 0, v[150:151]
	global_load_lds_dwordx4 v[168:169], off
	s_mov_b32 m0, s88
	v_lshl_add_u64 v[212:213], s[56:57], 0, v[152:153]
	global_load_lds_dwordx4 v[172:173], off
	v_lshl_add_u64 v[172:173], s[60:61], 0, v[154:155]
	s_mov_b32 m0, s89
	s_nop 0
	global_load_lds_dwordx4 v[172:173], off
	v_lshl_add_u64 v[172:173], s[56:57], 0, v[148:149]
	s_mov_b32 m0, s25
	s_nop 0
	global_load_lds_dwordx4 v[172:173], off
	s_mov_b32 m0, s62
	s_nop 0
	global_load_lds_dwordx4 v[212:213], off
	s_waitcnt vmcnt(8)
	s_waitcnt lgkmcnt(0)
	s_setprio 1
	s_barrier
; #define PG8_STAGE(bufoff, gbase, voff) do { _Pragma("unroll") for (int _i = 0; _i < 2; ++_i) \
;         __builtin_amdgcn_global_load_lds((const unsigned*)((const char*)(gbase) + (voff)[_i]), (PG8_LAS unsigned*)(lds + (bufoff) + ldsw + _i * 8192), 16, 0, AUX_A); } while (0)
; #define PG8_LDA(dst, b, h) do { _Pragma("unroll") for (int m = 0; m < 4; ++m) _Pragma("unroll") for (int k = 0; k < 2; ++k) dst[m][k] = *(const PG8_LAS bf16x8*)(lds + PG8_SA(b, h) + aoff + m * 2048 + k * 1024); } while (0)
; #define PG8_LDB(dst, b, h) do { _Pragma("unroll") for (int n = 0; n < 2; ++n) _Pragma("unroll") for (int k = 0; k < 2; ++k) dst[n][k] = *(const PG8_LAS bf16x8*)(lds + PG8_SB(b, h) + boff + n * 2048 + k * 1024); } while (0)
; #define PG8_MMA(ai, bj, At, Bt) do { __builtin_amdgcn_s_setprio(1); _Pragma("unroll") for (int m = 0; m < 4; ++m) _Pragma("unroll") for (int n = 0; n < 2; ++n) _Pragma("unroll") for (int k = 0; k < 2; ++k) \
;         acc[ai][bj][m][n] = __builtin_amdgcn_mfma_f32_16x16x32_bf16(Bt[n][k], At[m][k], acc[ai][bj][m][n], 0, 0, 0); __builtin_amdgcn_s_setprio(0); } while (0)
; #define PG8_WAIT_V(n) asm volatile("s_waitcnt vmcnt(" #n ")" ::: "memory")
; #define PG8_WAIT_L(n) asm volatile("s_waitcnt lgkmcnt(" #n ")" ::: "memory")
; #define PG8_BAR __builtin_amdgcn_s_barrier()
; #define PG8_SCHED __builtin_amdgcn_sched_barrier(0)
; template <class Epi, class Sched, bool ALIGN_EPI = false, bool SP2 = false>
; __device__ __forceinline__ void gemm_phase(PG8_LAS unsigned char* lds, const Gemm g, const Sched& S, const Epi& E) {
;     ...
;             PG8_WAIT_V(8); PG8_WAIT_L(0); PG8_BAR; PG8_MMA(1, 0, At, B0); PG8_MMA(1, 1, At, B1); PG8_BAR; PG8_SCHED;
;             PG8_LDB(B0, 1, 0); PG8_LDB(B1, 1, 1); PG8_SCHED; PG8_LDA(At, 1, 0); PG8_STAGE(PG8_SA(0, 1), a2 + hstep, voffA);
;             PG8_WAIT_V(8); PG8_WAIT_L(0); PG8_BAR; PG8_MMA(0, 0, At, B0); PG8_MMA(0, 1, At, B1); PG8_BAR; PG8_SCHED;
	v_mfma_f32_16x16x32_bf16 v[78:81], v[22:25], v[196:199], v[78:81]
	v_mfma_f32_16x16x32_bf16 v[78:81], v[34:37], v[200:203], v[78:81]
	v_mfma_f32_16x16x32_bf16 v[74:77], v[38:41], v[196:199], v[74:77]
	v_mfma_f32_16x16x32_bf16 v[74:77], v[160:163], v[200:203], v[74:77]
	v_mfma_f32_16x16x32_bf16 v[62:65], v[22:25], v[222:225], v[62:65]
	v_mfma_f32_16x16x32_bf16 v[62:65], v[34:37], v[226:229], v[62:65]
	v_mfma_f32_16x16x32_bf16 v[58:61], v[38:41], v[222:225], v[58:61]
	v_mfma_f32_16x16x32_bf16 v[58:61], v[160:163], v[226:229], v[58:61]
	v_mfma_f32_16x16x32_bf16 v[46:49], v[22:25], v[230:233], v[46:49]
	v_mfma_f32_16x16x32_bf16 v[46:49], v[34:37], v[234:237], v[46:49]
	v_mfma_f32_16x16x32_bf16 v[42:45], v[38:41], v[230:233], v[42:45]
	v_mfma_f32_16x16x32_bf16 v[42:45], v[160:163], v[234:237], v[42:45]
	v_mfma_f32_16x16x32_bf16 v[18:21], v[22:25], v[238:241], v[18:21]
	v_mfma_f32_16x16x32_bf16 v[18:21], v[34:37], v[242:245], v[18:21]
	v_mfma_f32_16x16x32_bf16 v[10:13], v[38:41], v[238:241], v[10:13]
	v_mfma_f32_16x16x32_bf16 v[10:13], v[160:163], v[242:245], v[10:13]
	s_setprio 0
	s_setprio 1
	v_mfma_f32_16x16x32_bf16 v[50:53], v[188:191], v[222:225], v[50:53]
	v_mfma_f32_16x16x32_bf16 v[30:33], v[180:183], v[230:233], v[30:33]
	v_mfma_f32_16x16x32_bf16 v[26:29], v[188:191], v[230:233], v[26:29]
	v_mfma_f32_16x16x32_bf16 v[6:9], v[180:183], v[238:241], v[6:9]
	v_mfma_f32_16x16x32_bf16 v[2:5], v[188:191], v[238:241], v[2:5]
	v_mfma_f32_16x16x32_bf16 v[22:25], v[180:183], v[196:199], v[70:73]
	v_mfma_f32_16x16x32_bf16 v[34:37], v[188:191], v[196:199], v[66:69]
	v_mfma_f32_16x16x32_bf16 v[38:41], v[180:183], v[222:225], v[54:57]
	v_mfma_f32_16x16x32_bf16 v[50:53], v[192:195], v[226:229], v[50:53]
	v_mfma_f32_16x16x32_bf16 v[30:33], v[184:187], v[234:237], v[30:33]
	v_mfma_f32_16x16x32_bf16 v[26:29], v[192:195], v[234:237], v[26:29]
	v_mfma_f32_16x16x32_bf16 v[6:9], v[184:187], v[242:245], v[6:9]
	v_mfma_f32_16x16x32_bf16 v[2:5], v[192:195], v[242:245], v[2:5]
	v_mfma_f32_16x16x32_bf16 v[22:25], v[184:187], v[200:203], v[22:25]
	s_setprio 2
	s_barrier
	v_mfma_f32_16x16x32_bf16 v[34:37], v[192:195], v[200:203], v[34:37]
	v_mfma_f32_16x16x32_bf16 v[38:41], v[184:187], v[226:229], v[38:41]
	s_setprio 0
	v_add_u32_e32 v160, s90, v99
	v_add_u32_e32 v192, s91, v99
	ds_read_b128 v[54:57], v160
	ds_read_b128 v[66:69], v160 offset:1024
	ds_read_b128 v[70:73], v160 offset:2048
	ds_read_b128 v[160:163], v160 offset:3072
	ds_read_b128 v[180:183], v192
	ds_read_b128 v[184:187], v192 offset:1024
	ds_read_b128 v[188:191], v192 offset:2048
	ds_read_b128 v[192:195], v192 offset:3072
	s_mov_b32 m0, s63
	v_lshl_add_u64 v[246:247], s[54:55], 0, v[148:149]
	ds_read_b128 v[196:199], v165 offset:32768
	ds_read_b128 v[200:203], v165 offset:33792
	ds_read_b128 v[222:225], v165 offset:34816
	ds_read_b128 v[226:229], v165 offset:35840
	ds_read_b128 v[230:233], v165 offset:36864
	ds_read_b128 v[234:237], v165 offset:37888
	ds_read_b128 v[238:241], v165 offset:38912
	ds_read_b128 v[242:245], v165 offset:39936
	global_load_lds_dwordx4 v[246:247], off
	v_lshl_add_u64 v[246:247], s[54:55], 0, v[152:153]
	s_mov_b32 m0, s69
	s_nop 0
	global_load_lds_dwordx4 v[246:247], off
	s_waitcnt vmcnt(8)
	s_waitcnt lgkmcnt(0)
	s_setprio 1
	s_barrier
	v_mfma_f32_16x16x32_bf16 v[144:147], v[54:57], v[196:199], v[144:147]
	v_mfma_f32_16x16x32_bf16 v[144:147], v[66:69], v[200:203], v[144:147]
	v_mfma_f32_16x16x32_bf16 v[140:143], v[70:73], v[196:199], v[140:143]
	v_mfma_f32_16x16x32_bf16 v[140:143], v[160:163], v[200:203], v[140:143]
	v_mfma_f32_16x16x32_bf16 v[128:131], v[54:57], v[222:225], v[128:131]
	v_mfma_f32_16x16x32_bf16 v[128:131], v[66:69], v[226:229], v[128:131]
	v_mfma_f32_16x16x32_bf16 v[124:127], v[70:73], v[222:225], v[124:127]
	v_mfma_f32_16x16x32_bf16 v[124:127], v[160:163], v[226:229], v[124:127]
	v_mfma_f32_16x16x32_bf16 v[112:115], v[54:57], v[230:233], v[112:115]
	v_mfma_f32_16x16x32_bf16 v[112:115], v[66:69], v[234:237], v[112:115]
	v_mfma_f32_16x16x32_bf16 v[108:111], v[70:73], v[230:233], v[108:111]
	v_mfma_f32_16x16x32_bf16 v[108:111], v[160:163], v[234:237], v[108:111]
	v_mfma_f32_16x16x32_bf16 v[94:97], v[54:57], v[238:241], v[94:97]
	v_mfma_f32_16x16x32_bf16 v[94:97], v[66:69], v[242:245], v[94:97]
	v_mfma_f32_16x16x32_bf16 v[90:93], v[70:73], v[238:241], v[90:93]
	v_mfma_f32_16x16x32_bf16 v[90:93], v[160:163], v[242:245], v[90:93]
	s_setprio 0
	s_setprio 1
	v_mfma_f32_16x16x32_bf16 v[136:139], v[180:183], v[196:199], v[136:139]
	v_mfma_f32_16x16x32_bf16 v[136:139], v[184:187], v[200:203], v[136:139]
	v_mfma_f32_16x16x32_bf16 v[132:135], v[188:191], v[196:199], v[132:135]
	v_mfma_f32_16x16x32_bf16 v[132:135], v[192:195], v[200:203], v[132:135]
	v_mfma_f32_16x16x32_bf16 v[120:123], v[180:183], v[222:225], v[120:123]
	v_mfma_f32_16x16x32_bf16 v[120:123], v[184:187], v[226:229], v[120:123]
	v_mfma_f32_16x16x32_bf16 v[116:119], v[188:191], v[222:225], v[116:119]
	v_mfma_f32_16x16x32_bf16 v[116:119], v[192:195], v[226:229], v[116:119]
	v_mfma_f32_16x16x32_bf16 v[104:107], v[180:183], v[230:233], v[104:107]
	v_mfma_f32_16x16x32_bf16 v[104:107], v[184:187], v[234:237], v[104:107]
	v_mfma_f32_16x16x32_bf16 v[100:103], v[188:191], v[230:233], v[100:103]
	v_mfma_f32_16x16x32_bf16 v[100:103], v[192:195], v[234:237], v[100:103]
	v_mfma_f32_16x16x32_bf16 v[86:89], v[180:183], v[238:241], v[86:89]
	v_mfma_f32_16x16x32_bf16 v[86:89], v[184:187], v[242:245], v[86:89]
	s_setprio 2
	s_barrier
; #define PG8_STAGE(bufoff, gbase, voff) do { _Pragma("unroll") for (int _i = 0; _i < 2; ++_i) \
;         __builtin_amdgcn_global_load_lds((const unsigned*)((const char*)(gbase) + (voff)[_i]), (PG8_LAS unsigned*)(lds + (bufoff) + ldsw + _i * 8192), 16, 0, AUX_A); } while (0)
; #define PG8_STAGEB(bufoff, gbase, voff) do { _Pragma("unroll") for (int _i = 0; _i < 2; ++_i) \
;         __builtin_amdgcn_global_load_lds((const unsigned*)((const char*)(gbase) + (voff)[_i]), (PG8_LAS unsigned*)(lds + (bufoff) + ldsw + _i * 8192), 16, 0, AUX_B); } while (0)
; #define PG8_LDA(dst, b, h) do { _Pragma("unroll") for (int m = 0; m < 4; ++m) _Pragma("unroll") for (int k = 0; k < 2; ++k) dst[m][k] = *(const PG8_LAS bf16x8*)(lds + PG8_SA(b, h) + aoff + m * 2048 + k * 1024); } while (0)
; #define PG8_MMA(ai, bj, At, Bt) do { __builtin_amdgcn_s_setprio(1); _Pragma("unroll") for (int m = 0; m < 4; ++m) _Pragma("unroll") for (int n = 0; n < 2; ++n) _Pragma("unroll") for (int k = 0; k < 2; ++k) \
;         acc[ai][bj][m][n] = __builtin_amdgcn_mfma_f32_16x16x32_bf16(Bt[n][k], At[m][k], acc[ai][bj][m][n], 0, 0, 0); __builtin_amdgcn_s_setprio(0); } while (0)
; #define PG8_WAIT_V(n) asm volatile("s_waitcnt vmcnt(" #n ")" ::: "memory")
; #define PG8_WAIT_L(n) asm volatile("s_waitcnt lgkmcnt(" #n ")" ::: "memory")
; #define PG8_BAR __builtin_amdgcn_s_barrier()
; #define PG8_SCHED __builtin_amdgcn_sched_barrier(0)
; template <class Epi, class Sched, bool ALIGN_EPI = false, bool SP2 = false>
; __device__ __forceinline__ void gemm_phase(PG8_LAS unsigned char* lds, const Gemm g, const Sched& S, const Epi& E) {
;     ...
;             PG8_WAIT_V(8); PG8_WAIT_L(0); PG8_BAR; PG8_MMA(0, 0, At, B0); PG8_MMA(0, 1, At, B1); PG8_BAR; PG8_SCHED;
;             PG8_LDA(At, 1, 1); PG8_STAGEB(PG8_SB(1, 0), b3, voffB); PG8_STAGEB(PG8_SB(1, 1), b3 + hstep, voffB); PG8_STAGE(PG8_SA(1, 0), a3, voffA);
;             PG8_WAIT_V(8); PG8_WAIT_L(0); PG8_BAR; PG8_MMA(1, 0, At, B0); PG8_MMA(1, 1, At, B1); PG8_BAR; PG8_SCHED;
	v_mfma_f32_16x16x32_bf16 v[82:85], v[188:191], v[238:241], v[82:85]
	v_mfma_f32_16x16x32_bf16 v[82:85], v[192:195], v[242:245], v[82:85]
	s_setprio 0
	s_mov_b32 m0, s1
	v_lshl_add_u64 v[166:167], v[166:167], 0, s[76:77]
	ds_read_b128 v[196:199], v165 offset:49152
	ds_read_b128 v[200:203], v165 offset:50176
	ds_read_b128 v[222:225], v165 offset:51200
	ds_read_b128 v[226:229], v165 offset:52224
	ds_read_b128 v[230:233], v165 offset:53248
	ds_read_b128 v[234:237], v165 offset:54272
	ds_read_b128 v[238:241], v165 offset:55296
	ds_read_b128 v[242:245], v165 offset:56320
	global_load_lds_dwordx4 v[166:167], off
	v_lshl_add_u64 v[166:167], v[168:169], 0, s[76:77]
	s_mov_b32 m0, s0
	s_nop 0
	global_load_lds_dwordx4 v[166:167], off
	v_lshl_add_u64 v[166:167], s[52:53], 0, v[150:151]
	s_mov_b32 m0, s47
	s_nop 0
	global_load_lds_dwordx4 v[166:167], off
	v_lshl_add_u64 v[166:167], s[52:53], 0, v[154:155]
	s_mov_b32 m0, s46
	s_nop 0
	global_load_lds_dwordx4 v[166:167], off
	v_lshl_add_u64 v[166:167], v[172:173], 0, s[76:77]
	s_mov_b32 m0, s70
	s_nop 0
	global_load_lds_dwordx4 v[166:167], off
	v_lshl_add_u64 v[166:167], v[212:213], 0, s[76:77]
	s_mov_b32 m0, s71
	s_nop 0
	global_load_lds_dwordx4 v[166:167], off
	s_waitcnt vmcnt(8)
	s_waitcnt lgkmcnt(0)
	s_setprio 1
	s_barrier
	v_mfma_f32_16x16x32_bf16 v[78:81], v[54:57], v[196:199], v[78:81]
	v_mfma_f32_16x16x32_bf16 v[78:81], v[66:69], v[200:203], v[78:81]
	v_mfma_f32_16x16x32_bf16 v[74:77], v[70:73], v[196:199], v[74:77]
	v_mfma_f32_16x16x32_bf16 v[74:77], v[160:163], v[200:203], v[74:77]
	v_mfma_f32_16x16x32_bf16 v[62:65], v[54:57], v[222:225], v[62:65]
	v_mfma_f32_16x16x32_bf16 v[62:65], v[66:69], v[226:229], v[62:65]
	v_mfma_f32_16x16x32_bf16 v[58:61], v[70:73], v[222:225], v[58:61]
	v_mfma_f32_16x16x32_bf16 v[58:61], v[160:163], v[226:229], v[58:61]
	v_mfma_f32_16x16x32_bf16 v[46:49], v[54:57], v[230:233], v[46:49]
	v_mfma_f32_16x16x32_bf16 v[46:49], v[66:69], v[234:237], v[46:49]
	v_mfma_f32_16x16x32_bf16 v[42:45], v[70:73], v[230:233], v[42:45]
	v_mfma_f32_16x16x32_bf16 v[42:45], v[160:163], v[234:237], v[42:45]
	v_mfma_f32_16x16x32_bf16 v[18:21], v[54:57], v[238:241], v[18:21]
	v_mfma_f32_16x16x32_bf16 v[18:21], v[66:69], v[242:245], v[18:21]
	v_mfma_f32_16x16x32_bf16 v[10:13], v[70:73], v[238:241], v[10:13]
	v_mfma_f32_16x16x32_bf16 v[10:13], v[160:163], v[242:245], v[10:13]
	s_setprio 0
	s_setprio 1
	v_mfma_f32_16x16x32_bf16 v[22:25], v[180:183], v[196:199], v[22:25]
	v_mfma_f32_16x16x32_bf16 v[70:73], v[184:187], v[200:203], v[22:25]
	v_mfma_f32_16x16x32_bf16 v[22:25], v[188:191], v[196:199], v[34:37]
	v_mfma_f32_16x16x32_bf16 v[66:69], v[192:195], v[200:203], v[22:25]
	v_mfma_f32_16x16x32_bf16 v[22:25], v[180:183], v[222:225], v[38:41]
	v_mfma_f32_16x16x32_bf16 v[54:57], v[184:187], v[226:229], v[22:25]
	v_mfma_f32_16x16x32_bf16 v[22:25], v[188:191], v[222:225], v[50:53]
	v_mfma_f32_16x16x32_bf16 v[50:53], v[192:195], v[226:229], v[22:25]
	v_mfma_f32_16x16x32_bf16 v[22:25], v[180:183], v[230:233], v[30:33]
	v_mfma_f32_16x16x32_bf16 v[30:33], v[184:187], v[234:237], v[22:25]
	v_mfma_f32_16x16x32_bf16 v[22:25], v[188:191], v[230:233], v[26:29]
	v_mfma_f32_16x16x32_bf16 v[6:9], v[180:183], v[238:241], v[6:9]
	v_mfma_f32_16x16x32_bf16 v[2:5], v[188:191], v[238:241], v[2:5]
	v_mfma_f32_16x16x32_bf16 v[26:29], v[192:195], v[234:237], v[22:25]
	s_setprio 2
	s_barrier
	v_mfma_f32_16x16x32_bf16 v[6:9], v[184:187], v[242:245], v[6:9]
	v_mfma_f32_16x16x32_bf16 v[2:5], v[192:195], v[242:245], v[2:5]
	s_setprio 0
	v_lshl_add_u64 v[14:15], v[14:15], 0, s[86:87]
	v_lshl_add_u64 v[16:17], v[16:17], 0, s[86:87]
	s_mov_b32 s29, s81
	s_cbranch_scc0 .LBB0_936
	s_and_b64 vcc, exec, s[12:13]
	s_cbranch_vccz .LBB0_939
	s_barrier

; #define PG8_STAGE(bufoff, gbase, voff) do { _Pragma("unroll") for (int _i = 0; _i < 2; ++_i) \
;         __builtin_amdgcn_global_load_lds((const unsigned*)((const char*)(gbase) + (voff)[_i]), (PG8_LAS unsigned*)(lds + (bufoff) + ldsw + _i * 8192), 16, 0, AUX_A); } while (0)
; #define PG8_STAGEB(bufoff, gbase, voff) do { _Pragma("unroll") for (int _i = 0; _i < 2; ++_i) \
;         __builtin_amdgcn_global_load_lds((const unsigned*)((const char*)(gbase) + (voff)[_i]), (PG8_LAS unsigned*)(lds + (bufoff) + ldsw + _i * 8192), 16, 0, AUX_B); } while (0)
; #define PG8_LDA(dst, b, h) do { _Pragma("unroll") for (int m = 0; m < 4; ++m) _Pragma("unroll") for (int k = 0; k < 2; ++k) dst[m][k] = *(const PG8_LAS bf16x8*)(lds + PG8_SA(b, h) + aoff + m * 2048 + k * 1024); } while (0)
; #define PG8_LDB(dst, b, h) do { _Pragma("unroll") for (int n = 0; n < 2; ++n) _Pragma("unroll") for (int k = 0; k < 2; ++k) dst[n][k] = *(const PG8_LAS bf16x8*)(lds + PG8_SB(b, h) + boff + n * 2048 + k * 1024); } while (0)
; #define PG8_WAIT_V(n) asm volatile("s_waitcnt vmcnt(" #n ")" ::: "memory")
; #define PG8_WAIT_L(n) asm volatile("s_waitcnt lgkmcnt(" #n ")" ::: "memory")
; #define PG8_BAR __builtin_amdgcn_s_barrier()
; #define PG8_SCHED __builtin_amdgcn_sched_barrier(0)
; template <class Epi, class Sched, bool ALIGN_EPI = false, bool SP2 = false>
; __device__ __forceinline__ void gemm_phase(PG8_LAS unsigned char* lds, const Gemm g, const Sched& S, const Epi& E) {
;     ...
;         for (int t = 0; t < nt; t += 2) {
;             const bool last = (t == nt - 2);
;             const char* a1 = PG8_KP(cA, t + 1, rot, nt);
;             const char* a2 = last ? nAr : PG8_KP(cA, t + 2, rot, nt); const char* b2 = last ? nBr : PG8_KP(cB, t + 2, rot, nt);
;             const char* a3 = a2 + kstep; const char* b3 = b2 + kstep;
;             if (last && has_next) S.a_ready(nxt);
;             if constexpr (SP2) {
;             PG8_LDB(B0, 0, 0); PG8_LDB(B1, 0, 1); PG8_SCHED; PG8_LDA(At, 0, 0); PG8_STAGE(PG8_SA(1, 1), a1 + hstep, voffA);
;             PG8_WAIT_V(8); PG8_WAIT_L(0); PG8_BAR; PG8_MMA(0, 0, At, B0); PG8_MMA(0, 1, At, B1); PG8_BAR; PG8_SCHED;
;             PG8_LDA(At, 0, 1); PG8_STAGEB(PG8_SB(0, 0), b2, voffB); PG8_STAGEB(PG8_SB(0, 1), b2 + hstep, voffB); PG8_STAGE(PG8_SA(0, 0), a2, voffA);
.LBB0_1067:
	s_add_i32 s81, s29, 2
	s_cmp_lt_u32 s29, 14
	s_cselect_b32 s0, 0, -16
	s_add_i32 s0, s81, s0
	s_ashr_i32 s1, s0, 31
	s_lshl_b64 s[0:1], s[0:1], 7
	s_add_u32 s2, s52, s0
	s_addc_u32 s46, s53, s1
	s_add_u32 s0, s42, s0
	s_addc_u32 s1, s43, s1
	s_cmp_eq_u32 s29, 14
	s_cselect_b32 s59, s15, s46
	s_cselect_b32 s58, s17, s2
	s_cselect_b32 s61, s92, s1
	s_cselect_b32 s60, s93, s0
	s_add_i32 s2, 0, 0x10000
	s_add_i32 s94, s2, s70
	s_add_i32 s46, 0, 0x14000
	s_add_i32 m0, s71, 0xc000
	s_add_i32 s84, s71, 0xe000
	s_add_i32 s95, s94, 0x2000
	s_add_u32 s62, s60, 0x40000
	v_add_u32_e32 v148, s2, v99
	s_addc_u32 s63, s61, 0
	s_add_i32 s96, s46, s70
	ds_read_b128 v[152:155], v148
	ds_read_b128 v[156:159], v148 offset:1024
	ds_read_b128 v[160:163], v148 offset:2048
	ds_read_b128 v[164:167], v148 offset:3072
	v_add_u32_e32 v148, s46, v99
	s_add_i32 s97, s96, 0x2000
	s_add_i32 vcc_lo, 0, 0x18000
	s_add_i32 vcc_hi, 0, 0x1c000
	ds_read_b128 v[180:183], v148
	ds_read_b128 v[184:187], v148 offset:1024
	ds_read_b128 v[188:191], v148 offset:2048
	ds_read_b128 v[192:195], v148 offset:3072
	s_add_u32 s56, s58, 0x40000
	s_addc_u32 s57, s59, 0
	s_add_i32 s1, vcc_lo, s70
	s_add_i32 s0, s1, 0x2000
	s_add_u32 s54, s60, 0x40080
	s_addc_u32 s55, s61, 0
	s_add_i32 s47, vcc_hi, s70
	s_add_i32 s46, s47, 0x2000
	s_cmp_gt_u32 s29, 13
	ds_read_b128 v[196:199], v151
	ds_read_b128 v[200:203], v151 offset:1024
	ds_read_b128 v[222:225], v151 offset:2048
	ds_read_b128 v[226:229], v151 offset:3072
	ds_read_b128 v[230:233], v151 offset:4096
	ds_read_b128 v[234:237], v151 offset:5120
	ds_read_b128 v[238:241], v151 offset:6144
	ds_read_b128 v[242:245], v151 offset:7168
	global_load_lds_dwordx4 v[146:147], off
	s_mov_b32 m0, s84
	s_nop 0
	global_load_lds_dwordx4 v[144:145], off
	s_waitcnt vmcnt(8)
	s_waitcnt lgkmcnt(0)
	s_setprio 1
	s_barrier
	v_mfma_f32_16x16x32_bf16 v[128:131], v[152:155], v[196:199], v[128:131]
	v_mfma_f32_16x16x32_bf16 v[128:131], v[156:159], v[200:203], v[128:131]
	v_mfma_f32_16x16x32_bf16 v[124:127], v[160:163], v[196:199], v[124:127]
	v_mfma_f32_16x16x32_bf16 v[124:127], v[164:167], v[200:203], v[124:127]
	v_mfma_f32_16x16x32_bf16 v[112:115], v[152:155], v[222:225], v[112:115]
	v_mfma_f32_16x16x32_bf16 v[112:115], v[156:159], v[226:229], v[112:115]
	v_mfma_f32_16x16x32_bf16 v[108:111], v[160:163], v[222:225], v[108:111]
	v_mfma_f32_16x16x32_bf16 v[108:111], v[164:167], v[226:229], v[108:111]
	v_mfma_f32_16x16x32_bf16 v[94:97], v[152:155], v[230:233], v[94:97]
	v_mfma_f32_16x16x32_bf16 v[94:97], v[156:159], v[234:237], v[94:97]
	v_mfma_f32_16x16x32_bf16 v[90:93], v[160:163], v[230:233], v[90:93]
	v_mfma_f32_16x16x32_bf16 v[90:93], v[164:167], v[234:237], v[90:93]
	v_mfma_f32_16x16x32_bf16 v[78:81], v[152:155], v[238:241], v[78:81]
	v_mfma_f32_16x16x32_bf16 v[78:81], v[156:159], v[242:245], v[78:81]
	v_mfma_f32_16x16x32_bf16 v[74:77], v[160:163], v[238:241], v[74:77]
	v_mfma_f32_16x16x32_bf16 v[74:77], v[164:167], v[242:245], v[74:77]
	s_setprio 0
	s_setprio 1
	v_mfma_f32_16x16x32_bf16 v[120:123], v[180:183], v[196:199], v[120:123]
	v_mfma_f32_16x16x32_bf16 v[120:123], v[184:187], v[200:203], v[120:123]
	v_mfma_f32_16x16x32_bf16 v[116:119], v[188:191], v[196:199], v[116:119]
	v_mfma_f32_16x16x32_bf16 v[116:119], v[192:195], v[200:203], v[116:119]
	v_mfma_f32_16x16x32_bf16 v[104:107], v[180:183], v[222:225], v[104:107]
	v_mfma_f32_16x16x32_bf16 v[104:107], v[184:187], v[226:229], v[104:107]
	v_mfma_f32_16x16x32_bf16 v[100:103], v[188:191], v[222:225], v[100:103]
	v_mfma_f32_16x16x32_bf16 v[100:103], v[192:195], v[226:229], v[100:103]
	v_mfma_f32_16x16x32_bf16 v[86:89], v[180:183], v[230:233], v[86:89]
	v_mfma_f32_16x16x32_bf16 v[86:89], v[184:187], v[234:237], v[86:89]
	v_mfma_f32_16x16x32_bf16 v[82:85], v[188:191], v[230:233], v[82:85]
	v_mfma_f32_16x16x32_bf16 v[82:85], v[192:195], v[234:237], v[82:85]
	v_mfma_f32_16x16x32_bf16 v[70:73], v[180:183], v[238:241], v[70:73]
	v_mfma_f32_16x16x32_bf16 v[70:73], v[184:187], v[242:245], v[70:73]
	s_setprio 2
	s_barrier
	v_mfma_f32_16x16x32_bf16 v[66:69], v[188:191], v[238:241], v[66:69]
	v_mfma_f32_16x16x32_bf16 v[66:69], v[192:195], v[242:245], v[66:69]
	s_setprio 0
	s_mov_b32 m0, s94
	v_lshl_add_u64 v[148:149], s[60:61], 0, v[136:137]
	ds_read_b128 v[196:199], v151 offset:16384
	ds_read_b128 v[200:203], v151 offset:17408
	ds_read_b128 v[222:225], v151 offset:18432
	ds_read_b128 v[226:229], v151 offset:19456
	ds_read_b128 v[230:233], v151 offset:20480
	ds_read_b128 v[234:237], v151 offset:21504
	ds_read_b128 v[238:241], v151 offset:22528
	ds_read_b128 v[242:245], v151 offset:23552
	global_load_lds_dwordx4 v[148:149], off
	v_lshl_add_u64 v[168:169], s[60:61], 0, v[132:133]
	s_mov_b32 m0, s95
	v_lshl_add_u64 v[172:173], s[62:63], 0, v[136:137]
	global_load_lds_dwordx4 v[168:169], off
	s_mov_b32 m0, s96
	v_lshl_add_u64 v[212:213], s[58:59], 0, v[134:135]
	global_load_lds_dwordx4 v[172:173], off
	v_lshl_add_u64 v[172:173], s[62:63], 0, v[132:133]
	s_mov_b32 m0, s97
	s_nop 0
	global_load_lds_dwordx4 v[172:173], off
	v_lshl_add_u64 v[172:173], s[58:59], 0, v[138:139]
	s_mov_b32 m0, s71
	s_nop 0
	global_load_lds_dwordx4 v[172:173], off
	s_mov_b32 m0, s75
	s_nop 0
	global_load_lds_dwordx4 v[212:213], off
	s_waitcnt vmcnt(8)
	s_waitcnt lgkmcnt(0)
	s_setprio 1
	s_barrier
; #define PG8_STAGE(bufoff, gbase, voff) do { _Pragma("unroll") for (int _i = 0; _i < 2; ++_i) \
;         __builtin_amdgcn_global_load_lds((const unsigned*)((const char*)(gbase) + (voff)[_i]), (PG8_LAS unsigned*)(lds + (bufoff) + ldsw + _i * 8192), 16, 0, AUX_A); } while (0)
; #define PG8_LDA(dst, b, h) do { _Pragma("unroll") for (int m = 0; m < 4; ++m) _Pragma("unroll") for (int k = 0; k < 2; ++k) dst[m][k] = *(const PG8_LAS bf16x8*)(lds + PG8_SA(b, h) + aoff + m * 2048 + k * 1024); } while (0)
; #define PG8_LDB(dst, b, h) do { _Pragma("unroll") for (int n = 0; n < 2; ++n) _Pragma("unroll") for (int k = 0; k < 2; ++k) dst[n][k] = *(const PG8_LAS bf16x8*)(lds + PG8_SB(b, h) + boff + n * 2048 + k * 1024); } while (0)
; #define PG8_MMA(ai, bj, At, Bt) do { __builtin_amdgcn_s_setprio(1); _Pragma("unroll") for (int m = 0; m < 4; ++m) _Pragma("unroll") for (int n = 0; n < 2; ++n) _Pragma("unroll") for (int k = 0; k < 2; ++k) \
;         acc[ai][bj][m][n] = __builtin_amdgcn_mfma_f32_16x16x32_bf16(Bt[n][k], At[m][k], acc[ai][bj][m][n], 0, 0, 0); __builtin_amdgcn_s_setprio(0); } while (0)
; #define PG8_WAIT_V(n) asm volatile("s_waitcnt vmcnt(" #n ")" ::: "memory")
; #define PG8_WAIT_L(n) asm volatile("s_waitcnt lgkmcnt(" #n ")" ::: "memory")
; #define PG8_BAR __builtin_amdgcn_s_barrier()
; #define PG8_SCHED __builtin_amdgcn_sched_barrier(0)
; template <class Epi, class Sched, bool ALIGN_EPI = false, bool SP2 = false>
; __device__ __forceinline__ void gemm_phase(PG8_LAS unsigned char* lds, const Gemm g, const Sched& S, const Epi& E) {
;     ...
;             PG8_WAIT_V(8); PG8_WAIT_L(0); PG8_BAR; PG8_MMA(1, 0, At, B0); PG8_MMA(1, 1, At, B1); PG8_BAR; PG8_SCHED;
;             PG8_LDB(B0, 1, 0); PG8_LDB(B1, 1, 1); PG8_SCHED; PG8_LDA(At, 1, 0); PG8_STAGE(PG8_SA(0, 1), a2 + hstep, voffA);
;             PG8_WAIT_V(8); PG8_WAIT_L(0); PG8_BAR; PG8_MMA(0, 0, At, B0); PG8_MMA(0, 1, At, B1); PG8_BAR; PG8_SCHED;
	v_mfma_f32_16x16x32_bf16 v[62:65], v[152:155], v[196:199], v[62:65]
	v_mfma_f32_16x16x32_bf16 v[62:65], v[156:159], v[200:203], v[62:65]
	v_mfma_f32_16x16x32_bf16 v[58:61], v[160:163], v[196:199], v[58:61]
	v_mfma_f32_16x16x32_bf16 v[58:61], v[164:167], v[200:203], v[58:61]
	v_mfma_f32_16x16x32_bf16 v[46:49], v[152:155], v[222:225], v[46:49]
	v_mfma_f32_16x16x32_bf16 v[46:49], v[156:159], v[226:229], v[46:49]
	v_mfma_f32_16x16x32_bf16 v[42:45], v[160:163], v[222:225], v[42:45]
	v_mfma_f32_16x16x32_bf16 v[42:45], v[164:167], v[226:229], v[42:45]
	v_mfma_f32_16x16x32_bf16 v[30:33], v[152:155], v[230:233], v[30:33]
	v_mfma_f32_16x16x32_bf16 v[30:33], v[156:159], v[234:237], v[30:33]
	v_mfma_f32_16x16x32_bf16 v[26:29], v[160:163], v[230:233], v[26:29]
	v_mfma_f32_16x16x32_bf16 v[26:29], v[164:167], v[234:237], v[26:29]
	v_mfma_f32_16x16x32_bf16 v[14:17], v[152:155], v[238:241], v[14:17]
	v_mfma_f32_16x16x32_bf16 v[14:17], v[156:159], v[242:245], v[14:17]
	v_mfma_f32_16x16x32_bf16 v[10:13], v[160:163], v[238:241], v[10:13]
	v_mfma_f32_16x16x32_bf16 v[10:13], v[164:167], v[242:245], v[10:13]
	s_setprio 0
	s_setprio 1
	v_mfma_f32_16x16x32_bf16 v[54:57], v[180:183], v[196:199], v[54:57]
	v_mfma_f32_16x16x32_bf16 v[54:57], v[184:187], v[200:203], v[54:57]
	v_mfma_f32_16x16x32_bf16 v[50:53], v[188:191], v[196:199], v[50:53]
	v_mfma_f32_16x16x32_bf16 v[50:53], v[192:195], v[200:203], v[50:53]
	v_mfma_f32_16x16x32_bf16 v[38:41], v[180:183], v[222:225], v[38:41]
	v_mfma_f32_16x16x32_bf16 v[38:41], v[184:187], v[226:229], v[38:41]
	v_mfma_f32_16x16x32_bf16 v[34:37], v[188:191], v[222:225], v[34:37]
	v_mfma_f32_16x16x32_bf16 v[34:37], v[192:195], v[226:229], v[34:37]
	v_mfma_f32_16x16x32_bf16 v[22:25], v[180:183], v[230:233], v[22:25]
	v_mfma_f32_16x16x32_bf16 v[22:25], v[184:187], v[234:237], v[22:25]
	v_mfma_f32_16x16x32_bf16 v[18:21], v[188:191], v[230:233], v[18:21]
	v_mfma_f32_16x16x32_bf16 v[18:21], v[192:195], v[234:237], v[18:21]
	v_mfma_f32_16x16x32_bf16 v[6:9], v[180:183], v[238:241], v[6:9]
	v_mfma_f32_16x16x32_bf16 v[6:9], v[184:187], v[242:245], v[6:9]
	s_setprio 2
	s_barrier
	v_mfma_f32_16x16x32_bf16 v[2:5], v[188:191], v[238:241], v[2:5]
	v_mfma_f32_16x16x32_bf16 v[2:5], v[192:195], v[242:245], v[2:5]
	s_setprio 0
	v_add_u32_e32 v164, vcc_lo, v99
	v_add_u32_e32 v192, vcc_hi, v99
	ds_read_b128 v[152:155], v164
	ds_read_b128 v[156:159], v164 offset:1024
	ds_read_b128 v[160:163], v164 offset:2048
	ds_read_b128 v[164:167], v164 offset:3072
	ds_read_b128 v[180:183], v192
	ds_read_b128 v[184:187], v192 offset:1024
	ds_read_b128 v[188:191], v192 offset:2048
	ds_read_b128 v[192:195], v192 offset:3072
	s_mov_b32 m0, s78
	v_lshl_add_u64 v[246:247], s[56:57], 0, v[138:139]
	ds_read_b128 v[196:199], v151 offset:32768
	ds_read_b128 v[200:203], v151 offset:33792
	ds_read_b128 v[222:225], v151 offset:34816
	ds_read_b128 v[226:229], v151 offset:35840
	ds_read_b128 v[230:233], v151 offset:36864
	ds_read_b128 v[234:237], v151 offset:37888
	ds_read_b128 v[238:241], v151 offset:38912
	ds_read_b128 v[242:245], v151 offset:39936
	global_load_lds_dwordx4 v[246:247], off
	v_lshl_add_u64 v[246:247], s[56:57], 0, v[134:135]
	s_mov_b32 m0, s82
	s_nop 0
	global_load_lds_dwordx4 v[246:247], off
	s_waitcnt vmcnt(8)
	s_waitcnt lgkmcnt(0)
	s_setprio 1
	s_barrier
	v_mfma_f32_16x16x32_bf16 v[128:131], v[152:155], v[196:199], v[128:131]
	v_mfma_f32_16x16x32_bf16 v[128:131], v[156:159], v[200:203], v[128:131]
	v_mfma_f32_16x16x32_bf16 v[124:127], v[160:163], v[196:199], v[124:127]
	v_mfma_f32_16x16x32_bf16 v[124:127], v[164:167], v[200:203], v[124:127]
	v_mfma_f32_16x16x32_bf16 v[112:115], v[152:155], v[222:225], v[112:115]
	v_mfma_f32_16x16x32_bf16 v[112:115], v[156:159], v[226:229], v[112:115]
	v_mfma_f32_16x16x32_bf16 v[108:111], v[160:163], v[222:225], v[108:111]
	v_mfma_f32_16x16x32_bf16 v[108:111], v[164:167], v[226:229], v[108:111]
	v_mfma_f32_16x16x32_bf16 v[94:97], v[152:155], v[230:233], v[94:97]
	v_mfma_f32_16x16x32_bf16 v[94:97], v[156:159], v[234:237], v[94:97]
	v_mfma_f32_16x16x32_bf16 v[90:93], v[160:163], v[230:233], v[90:93]
	v_mfma_f32_16x16x32_bf16 v[90:93], v[164:167], v[234:237], v[90:93]
	v_mfma_f32_16x16x32_bf16 v[78:81], v[152:155], v[238:241], v[78:81]
	v_mfma_f32_16x16x32_bf16 v[78:81], v[156:159], v[242:245], v[78:81]
	v_mfma_f32_16x16x32_bf16 v[74:77], v[160:163], v[238:241], v[74:77]
	v_mfma_f32_16x16x32_bf16 v[74:77], v[164:167], v[242:245], v[74:77]
	s_setprio 0
	s_setprio 1
	v_mfma_f32_16x16x32_bf16 v[120:123], v[180:183], v[196:199], v[120:123]
	v_mfma_f32_16x16x32_bf16 v[120:123], v[184:187], v[200:203], v[120:123]
	v_mfma_f32_16x16x32_bf16 v[116:119], v[188:191], v[196:199], v[116:119]
	v_mfma_f32_16x16x32_bf16 v[116:119], v[192:195], v[200:203], v[116:119]
	v_mfma_f32_16x16x32_bf16 v[104:107], v[180:183], v[222:225], v[104:107]
	v_mfma_f32_16x16x32_bf16 v[104:107], v[184:187], v[226:229], v[104:107]
	v_mfma_f32_16x16x32_bf16 v[100:103], v[188:191], v[222:225], v[100:103]
	v_mfma_f32_16x16x32_bf16 v[100:103], v[192:195], v[226:229], v[100:103]
	v_mfma_f32_16x16x32_bf16 v[86:89], v[180:183], v[230:233], v[86:89]
	v_mfma_f32_16x16x32_bf16 v[86:89], v[184:187], v[234:237], v[86:89]
	v_mfma_f32_16x16x32_bf16 v[82:85], v[188:191], v[230:233], v[82:85]
	v_mfma_f32_16x16x32_bf16 v[82:85], v[192:195], v[234:237], v[82:85]
	v_mfma_f32_16x16x32_bf16 v[70:73], v[180:183], v[238:241], v[70:73]
	v_mfma_f32_16x16x32_bf16 v[70:73], v[184:187], v[242:245], v[70:73]
	s_setprio 2
	s_barrier
; #define PG8_STAGE(bufoff, gbase, voff) do { _Pragma("unroll") for (int _i = 0; _i < 2; ++_i) \
;         __builtin_amdgcn_global_load_lds((const unsigned*)((const char*)(gbase) + (voff)[_i]), (PG8_LAS unsigned*)(lds + (bufoff) + ldsw + _i * 8192), 16, 0, AUX_A); } while (0)
; #define PG8_STAGEB(bufoff, gbase, voff) do { _Pragma("unroll") for (int _i = 0; _i < 2; ++_i) \
;         __builtin_amdgcn_global_load_lds((const unsigned*)((const char*)(gbase) + (voff)[_i]), (PG8_LAS unsigned*)(lds + (bufoff) + ldsw + _i * 8192), 16, 0, AUX_B); } while (0)
; #define PG8_LDA(dst, b, h) do { _Pragma("unroll") for (int m = 0; m < 4; ++m) _Pragma("unroll") for (int k = 0; k < 2; ++k) dst[m][k] = *(const PG8_LAS bf16x8*)(lds + PG8_SA(b, h) + aoff + m * 2048 + k * 1024); } while (0)
; #define PG8_MMA(ai, bj, At, Bt) do { __builtin_amdgcn_s_setprio(1); _Pragma("unroll") for (int m = 0; m < 4; ++m) _Pragma("unroll") for (int n = 0; n < 2; ++n) _Pragma("unroll") for (int k = 0; k < 2; ++k) \
;         acc[ai][bj][m][n] = __builtin_amdgcn_mfma_f32_16x16x32_bf16(Bt[n][k], At[m][k], acc[ai][bj][m][n], 0, 0, 0); __builtin_amdgcn_s_setprio(0); } while (0)
; #define PG8_WAIT_V(n) asm volatile("s_waitcnt vmcnt(" #n ")" ::: "memory")
; #define PG8_WAIT_L(n) asm volatile("s_waitcnt lgkmcnt(" #n ")" ::: "memory")
; #define PG8_BAR __builtin_amdgcn_s_barrier()
; #define PG8_SCHED __builtin_amdgcn_sched_barrier(0)
; template <class Epi, class Sched, bool ALIGN_EPI = false, bool SP2 = false>
; __device__ __forceinline__ void gemm_phase(PG8_LAS unsigned char* lds, const Gemm g, const Sched& S, const Epi& E) {
;     ...
;             PG8_WAIT_V(8); PG8_WAIT_L(0); PG8_BAR; PG8_MMA(0, 0, At, B0); PG8_MMA(0, 1, At, B1); PG8_BAR; PG8_SCHED;
;             PG8_LDA(At, 1, 1); PG8_STAGEB(PG8_SB(1, 0), b3, voffB); PG8_STAGEB(PG8_SB(1, 1), b3 + hstep, voffB); PG8_STAGE(PG8_SA(1, 0), a3, voffA);
;             PG8_WAIT_V(8); PG8_WAIT_L(0); PG8_BAR; PG8_MMA(1, 0, At, B0); PG8_MMA(1, 1, At, B1); PG8_BAR; PG8_SCHED;
	v_mfma_f32_16x16x32_bf16 v[66:69], v[188:191], v[238:241], v[66:69]
	v_mfma_f32_16x16x32_bf16 v[66:69], v[192:195], v[242:245], v[66:69]
	s_setprio 0
	s_mov_b32 m0, s1
	v_lshl_add_u64 v[148:149], v[148:149], 0, s[76:77]
	ds_read_b128 v[196:199], v151 offset:49152
	ds_read_b128 v[200:203], v151 offset:50176
	ds_read_b128 v[222:225], v151 offset:51200
	ds_read_b128 v[226:229], v151 offset:52224
	ds_read_b128 v[230:233], v151 offset:53248
	ds_read_b128 v[234:237], v151 offset:54272
	ds_read_b128 v[238:241], v151 offset:55296
	ds_read_b128 v[242:245], v151 offset:56320
	global_load_lds_dwordx4 v[148:149], off
	v_lshl_add_u64 v[148:149], v[168:169], 0, s[76:77]
	s_mov_b32 m0, s0
	s_nop 0
	global_load_lds_dwordx4 v[148:149], off
	v_lshl_add_u64 v[148:149], s[54:55], 0, v[136:137]
	s_mov_b32 m0, s47
	s_nop 0
	global_load_lds_dwordx4 v[148:149], off
	v_lshl_add_u64 v[148:149], s[54:55], 0, v[132:133]
	s_mov_b32 m0, s46
	s_nop 0
	global_load_lds_dwordx4 v[148:149], off
	v_lshl_add_u64 v[148:149], v[172:173], 0, s[76:77]
	s_mov_b32 m0, s83
	s_nop 0
	global_load_lds_dwordx4 v[148:149], off
	v_lshl_add_u64 v[148:149], v[212:213], 0, s[76:77]
	s_mov_b32 m0, s88
	s_nop 0
	global_load_lds_dwordx4 v[148:149], off
	s_waitcnt vmcnt(8)
	s_waitcnt lgkmcnt(0)
	s_setprio 1
	s_barrier
	v_mfma_f32_16x16x32_bf16 v[62:65], v[152:155], v[196:199], v[62:65]
	v_mfma_f32_16x16x32_bf16 v[62:65], v[156:159], v[200:203], v[62:65]
	v_mfma_f32_16x16x32_bf16 v[58:61], v[160:163], v[196:199], v[58:61]
	v_mfma_f32_16x16x32_bf16 v[58:61], v[164:167], v[200:203], v[58:61]
	v_mfma_f32_16x16x32_bf16 v[46:49], v[152:155], v[222:225], v[46:49]
	v_mfma_f32_16x16x32_bf16 v[46:49], v[156:159], v[226:229], v[46:49]
	v_mfma_f32_16x16x32_bf16 v[42:45], v[160:163], v[222:225], v[42:45]
	v_mfma_f32_16x16x32_bf16 v[42:45], v[164:167], v[226:229], v[42:45]
	v_mfma_f32_16x16x32_bf16 v[30:33], v[152:155], v[230:233], v[30:33]
	v_mfma_f32_16x16x32_bf16 v[30:33], v[156:159], v[234:237], v[30:33]
	v_mfma_f32_16x16x32_bf16 v[26:29], v[160:163], v[230:233], v[26:29]
	v_mfma_f32_16x16x32_bf16 v[26:29], v[164:167], v[234:237], v[26:29]
	v_mfma_f32_16x16x32_bf16 v[14:17], v[152:155], v[238:241], v[14:17]
	v_mfma_f32_16x16x32_bf16 v[14:17], v[156:159], v[242:245], v[14:17]
	v_mfma_f32_16x16x32_bf16 v[10:13], v[160:163], v[238:241], v[10:13]
	v_mfma_f32_16x16x32_bf16 v[10:13], v[164:167], v[242:245], v[10:13]
	s_setprio 0
	s_setprio 1
	v_mfma_f32_16x16x32_bf16 v[54:57], v[180:183], v[196:199], v[54:57]
	v_mfma_f32_16x16x32_bf16 v[54:57], v[184:187], v[200:203], v[54:57]
	v_mfma_f32_16x16x32_bf16 v[50:53], v[188:191], v[196:199], v[50:53]
	v_mfma_f32_16x16x32_bf16 v[50:53], v[192:195], v[200:203], v[50:53]
	v_mfma_f32_16x16x32_bf16 v[38:41], v[180:183], v[222:225], v[38:41]
	v_mfma_f32_16x16x32_bf16 v[38:41], v[184:187], v[226:229], v[38:41]
	v_mfma_f32_16x16x32_bf16 v[34:37], v[188:191], v[222:225], v[34:37]
	v_mfma_f32_16x16x32_bf16 v[34:37], v[192:195], v[226:229], v[34:37]
	v_mfma_f32_16x16x32_bf16 v[22:25], v[180:183], v[230:233], v[22:25]
	v_mfma_f32_16x16x32_bf16 v[22:25], v[184:187], v[234:237], v[22:25]
	v_mfma_f32_16x16x32_bf16 v[18:21], v[188:191], v[230:233], v[18:21]
	v_mfma_f32_16x16x32_bf16 v[18:21], v[192:195], v[234:237], v[18:21]
	v_mfma_f32_16x16x32_bf16 v[6:9], v[180:183], v[238:241], v[6:9]
	v_mfma_f32_16x16x32_bf16 v[6:9], v[184:187], v[242:245], v[6:9]
	s_setprio 2
	s_barrier
	v_mfma_f32_16x16x32_bf16 v[2:5], v[188:191], v[238:241], v[2:5]
	v_mfma_f32_16x16x32_bf16 v[2:5], v[192:195], v[242:245], v[2:5]
	s_setprio 0
	v_lshl_add_u64 v[144:145], v[144:145], 0, s[86:87]
	v_lshl_add_u64 v[146:147], v[146:147], 0, s[86:87]
	s_mov_b32 s29, s81
	s_cbranch_scc0 .LBB0_1067
	s_and_b64 vcc, exec, s[12:13]
	s_cbranch_vccz .LBB0_1070
	s_barrier

; #define PG8_STAGE(bufoff, gbase, voff) do { _Pragma("unroll") for (int _i = 0; _i < 2; ++_i) \
;         __builtin_amdgcn_global_load_lds((const unsigned*)((const char*)(gbase) + (voff)[_i]), (PG8_LAS unsigned*)(lds + (bufoff) + ldsw + _i * 8192), 16, 0, AUX_A); } while (0)
; #define PG8_STAGEB(bufoff, gbase, voff) do { _Pragma("unroll") for (int _i = 0; _i < 2; ++_i) \
;         __builtin_amdgcn_global_load_lds((const unsigned*)((const char*)(gbase) + (voff)[_i]), (PG8_LAS unsigned*)(lds + (bufoff) + ldsw + _i * 8192), 16, 0, AUX_B); } while (0)
; #define PG8_LDA(dst, b, h) do { _Pragma("unroll") for (int m = 0; m < 4; ++m) _Pragma("unroll") for (int k = 0; k < 2; ++k) dst[m][k] = *(const PG8_LAS bf16x8*)(lds + PG8_SA(b, h) + aoff + m * 2048 + k * 1024); } while (0)
; #define PG8_LDB(dst, b, h) do { _Pragma("unroll") for (int n = 0; n < 2; ++n) _Pragma("unroll") for (int k = 0; k < 2; ++k) dst[n][k] = *(const PG8_LAS bf16x8*)(lds + PG8_SB(b, h) + boff + n * 2048 + k * 1024); } while (0)
; #define PG8_WAIT_V(n) asm volatile("s_waitcnt vmcnt(" #n ")" ::: "memory")
; #define PG8_WAIT_L(n) asm volatile("s_waitcnt lgkmcnt(" #n ")" ::: "memory")
; #define PG8_BAR __builtin_amdgcn_s_barrier()
; #define PG8_SCHED __builtin_amdgcn_sched_barrier(0)
; template <class Epi, class Sched, bool ALIGN_EPI = false, bool SP2 = false>
; __device__ __forceinline__ void gemm_phase(PG8_LAS unsigned char* lds, const Gemm g, const Sched& S, const Epi& E) {
;     ...
;         for (int t = 0; t < nt; t += 2) {
;             const bool last = (t == nt - 2);
;             const char* a1 = PG8_KP(cA, t + 1, rot, nt);
;             const char* a2 = last ? nAr : PG8_KP(cA, t + 2, rot, nt); const char* b2 = last ? nBr : PG8_KP(cB, t + 2, rot, nt);
;             const char* a3 = a2 + kstep; const char* b3 = b2 + kstep;
;             if (last && has_next) S.a_ready(nxt);
;             if constexpr (SP2) {
;             PG8_LDB(B0, 0, 0); PG8_LDB(B1, 0, 1); PG8_SCHED; PG8_LDA(At, 0, 0); PG8_STAGE(PG8_SA(1, 1), a1 + hstep, voffA);
;             PG8_WAIT_V(8); PG8_WAIT_L(0); PG8_BAR; PG8_MMA(0, 0, At, B0); PG8_MMA(0, 1, At, B1); PG8_BAR; PG8_SCHED;
;             PG8_LDA(At, 0, 1); PG8_STAGEB(PG8_SB(0, 0), b2, voffB); PG8_STAGEB(PG8_SB(0, 1), b2 + hstep, voffB); PG8_STAGE(PG8_SA(0, 0), a2, voffA);
.LBB0_1157:
	s_add_i32 s81, s29, 2
	s_cmp_lt_u32 s29, 14
	s_cselect_b32 s0, 0, -16
	s_add_i32 s0, s81, s0
	s_ashr_i32 s1, s0, 31
	s_lshl_b64 s[0:1], s[0:1], 7
	s_add_u32 s2, s52, s0
	s_addc_u32 s46, s53, s1
	s_add_u32 s0, s50, s0
	s_addc_u32 s1, s51, s1
	s_cmp_eq_u32 s29, 14
	s_cselect_b32 s59, s19, s46
	s_cselect_b32 s58, s39, s2
	s_cselect_b32 s61, s92, s1
	s_cselect_b32 s60, s93, s0
	s_add_i32 s2, 0, 0x10000
	s_add_i32 s94, s2, s70
	s_add_i32 s46, 0, 0x14000
	s_add_i32 m0, s71, 0xc000
	s_add_i32 s84, s71, 0xe000
	s_add_i32 s95, s94, 0x2000
	s_add_u32 s62, s60, 0x40000
	s_addc_u32 s63, s61, 0
	s_add_i32 s96, s46, s70
	v_add_u32_e32 v162, s2, v99
	v_add_u32_e32 v166, s46, v99
	s_add_i32 s97, s96, 0x2000
	s_add_i32 vcc_lo, 0, 0x18000
	s_add_i32 vcc_hi, 0, 0x1c000
	ds_read_b128 v[148:151], v162
	ds_read_b128 v[154:157], v162 offset:1024
	ds_read_b128 v[158:161], v162 offset:2048
	ds_read_b128 v[162:165], v162 offset:3072
	ds_read_b128 v[180:183], v166
	ds_read_b128 v[184:187], v166 offset:1024
	ds_read_b128 v[188:191], v166 offset:2048
	ds_read_b128 v[192:195], v166 offset:3072
	s_add_u32 s56, s58, 0x40000
	s_addc_u32 s57, s59, 0
	s_add_i32 s1, vcc_lo, s70
	s_add_i32 s0, s1, 0x2000
	s_add_u32 s54, s60, 0x40080
	s_addc_u32 s55, s61, 0
	s_add_i32 s47, vcc_hi, s70
	s_add_i32 s46, s47, 0x2000
	s_cmp_gt_u32 s29, 13
	ds_read_b128 v[196:199], v153
	ds_read_b128 v[200:203], v153 offset:1024
	ds_read_b128 v[222:225], v153 offset:2048
	ds_read_b128 v[226:229], v153 offset:3072
	ds_read_b128 v[230:233], v153 offset:4096
	ds_read_b128 v[234:237], v153 offset:5120
	ds_read_b128 v[238:241], v153 offset:6144
	ds_read_b128 v[242:245], v153 offset:7168
	global_load_lds_dwordx4 v[146:147], off
	s_mov_b32 m0, s84
	s_nop 0
	global_load_lds_dwordx4 v[144:145], off
	s_waitcnt vmcnt(8)
	s_waitcnt lgkmcnt(0)
	s_setprio 1
	s_barrier
	v_mfma_f32_16x16x32_bf16 v[128:131], v[148:151], v[196:199], v[128:131]
	v_mfma_f32_16x16x32_bf16 v[128:131], v[154:157], v[200:203], v[128:131]
	v_mfma_f32_16x16x32_bf16 v[124:127], v[158:161], v[196:199], v[124:127]
	v_mfma_f32_16x16x32_bf16 v[124:127], v[162:165], v[200:203], v[124:127]
	v_mfma_f32_16x16x32_bf16 v[112:115], v[148:151], v[222:225], v[112:115]
	v_mfma_f32_16x16x32_bf16 v[112:115], v[154:157], v[226:229], v[112:115]
	v_mfma_f32_16x16x32_bf16 v[108:111], v[158:161], v[222:225], v[108:111]
	v_mfma_f32_16x16x32_bf16 v[108:111], v[162:165], v[226:229], v[108:111]
	v_mfma_f32_16x16x32_bf16 v[94:97], v[148:151], v[230:233], v[94:97]
	v_mfma_f32_16x16x32_bf16 v[94:97], v[154:157], v[234:237], v[94:97]
	v_mfma_f32_16x16x32_bf16 v[90:93], v[158:161], v[230:233], v[90:93]
	v_mfma_f32_16x16x32_bf16 v[90:93], v[162:165], v[234:237], v[90:93]
	v_mfma_f32_16x16x32_bf16 v[78:81], v[148:151], v[238:241], v[78:81]
	v_mfma_f32_16x16x32_bf16 v[78:81], v[154:157], v[242:245], v[78:81]
	v_mfma_f32_16x16x32_bf16 v[74:77], v[158:161], v[238:241], v[74:77]
	v_mfma_f32_16x16x32_bf16 v[74:77], v[162:165], v[242:245], v[74:77]
	s_setprio 0
	s_setprio 1
	v_mfma_f32_16x16x32_bf16 v[120:123], v[180:183], v[196:199], v[120:123]
	v_mfma_f32_16x16x32_bf16 v[120:123], v[184:187], v[200:203], v[120:123]
	v_mfma_f32_16x16x32_bf16 v[116:119], v[188:191], v[196:199], v[116:119]
	v_mfma_f32_16x16x32_bf16 v[116:119], v[192:195], v[200:203], v[116:119]
	v_mfma_f32_16x16x32_bf16 v[104:107], v[180:183], v[222:225], v[104:107]
	v_mfma_f32_16x16x32_bf16 v[104:107], v[184:187], v[226:229], v[104:107]
	v_mfma_f32_16x16x32_bf16 v[100:103], v[188:191], v[222:225], v[100:103]
	v_mfma_f32_16x16x32_bf16 v[100:103], v[192:195], v[226:229], v[100:103]
	v_mfma_f32_16x16x32_bf16 v[86:89], v[180:183], v[230:233], v[86:89]
	v_mfma_f32_16x16x32_bf16 v[86:89], v[184:187], v[234:237], v[86:89]
	v_mfma_f32_16x16x32_bf16 v[82:85], v[188:191], v[230:233], v[82:85]
	v_mfma_f32_16x16x32_bf16 v[82:85], v[192:195], v[234:237], v[82:85]
	v_mfma_f32_16x16x32_bf16 v[70:73], v[180:183], v[238:241], v[70:73]
	v_mfma_f32_16x16x32_bf16 v[70:73], v[184:187], v[242:245], v[70:73]
	s_setprio 2
	s_barrier
	v_mfma_f32_16x16x32_bf16 v[66:69], v[188:191], v[238:241], v[66:69]
	v_mfma_f32_16x16x32_bf16 v[66:69], v[192:195], v[242:245], v[66:69]
	s_setprio 0
	s_mov_b32 m0, s94
	v_lshl_add_u64 v[166:167], s[60:61], 0, v[136:137]
	ds_read_b128 v[196:199], v153 offset:16384
	ds_read_b128 v[200:203], v153 offset:17408
	ds_read_b128 v[222:225], v153 offset:18432
	ds_read_b128 v[226:229], v153 offset:19456
	ds_read_b128 v[230:233], v153 offset:20480
	ds_read_b128 v[234:237], v153 offset:21504
	ds_read_b128 v[238:241], v153 offset:22528
	ds_read_b128 v[242:245], v153 offset:23552
	global_load_lds_dwordx4 v[166:167], off
	v_lshl_add_u64 v[168:169], s[60:61], 0, v[132:133]
	s_mov_b32 m0, s95
	v_lshl_add_u64 v[172:173], s[62:63], 0, v[136:137]
	global_load_lds_dwordx4 v[168:169], off
	s_mov_b32 m0, s96
	v_lshl_add_u64 v[212:213], s[58:59], 0, v[134:135]
	global_load_lds_dwordx4 v[172:173], off
	v_lshl_add_u64 v[172:173], s[62:63], 0, v[132:133]
	s_mov_b32 m0, s97
	s_nop 0
	global_load_lds_dwordx4 v[172:173], off
	v_lshl_add_u64 v[172:173], s[58:59], 0, v[138:139]
	s_mov_b32 m0, s71
	s_nop 0
	global_load_lds_dwordx4 v[172:173], off
	s_mov_b32 m0, s75
	s_nop 0
	global_load_lds_dwordx4 v[212:213], off
	s_waitcnt vmcnt(8)
	s_waitcnt lgkmcnt(0)
	s_setprio 1
	s_barrier
; #define PG8_STAGE(bufoff, gbase, voff) do { _Pragma("unroll") for (int _i = 0; _i < 2; ++_i) \
;         __builtin_amdgcn_global_load_lds((const unsigned*)((const char*)(gbase) + (voff)[_i]), (PG8_LAS unsigned*)(lds + (bufoff) + ldsw + _i * 8192), 16, 0, AUX_A); } while (0)
; #define PG8_LDA(dst, b, h) do { _Pragma("unroll") for (int m = 0; m < 4; ++m) _Pragma("unroll") for (int k = 0; k < 2; ++k) dst[m][k] = *(const PG8_LAS bf16x8*)(lds + PG8_SA(b, h) + aoff + m * 2048 + k * 1024); } while (0)
; #define PG8_LDB(dst, b, h) do { _Pragma("unroll") for (int n = 0; n < 2; ++n) _Pragma("unroll") for (int k = 0; k < 2; ++k) dst[n][k] = *(const PG8_LAS bf16x8*)(lds + PG8_SB(b, h) + boff + n * 2048 + k * 1024); } while (0)
; #define PG8_MMA(ai, bj, At, Bt) do { __builtin_amdgcn_s_setprio(1); _Pragma("unroll") for (int m = 0; m < 4; ++m) _Pragma("unroll") for (int n = 0; n < 2; ++n) _Pragma("unroll") for (int k = 0; k < 2; ++k) \
;         acc[ai][bj][m][n] = __builtin_amdgcn_mfma_f32_16x16x32_bf16(Bt[n][k], At[m][k], acc[ai][bj][m][n], 0, 0, 0); __builtin_amdgcn_s_setprio(0); } while (0)
; #define PG8_WAIT_V(n) asm volatile("s_waitcnt vmcnt(" #n ")" ::: "memory")
; #define PG8_WAIT_L(n) asm volatile("s_waitcnt lgkmcnt(" #n ")" ::: "memory")
; #define PG8_BAR __builtin_amdgcn_s_barrier()
; #define PG8_SCHED __builtin_amdgcn_sched_barrier(0)
; template <class Epi, class Sched, bool ALIGN_EPI = false, bool SP2 = false>
; __device__ __forceinline__ void gemm_phase(PG8_LAS unsigned char* lds, const Gemm g, const Sched& S, const Epi& E) {
;     ...
;             PG8_WAIT_V(8); PG8_WAIT_L(0); PG8_BAR; PG8_MMA(1, 0, At, B0); PG8_MMA(1, 1, At, B1); PG8_BAR; PG8_SCHED;
;             PG8_LDB(B0, 1, 0); PG8_LDB(B1, 1, 1); PG8_SCHED; PG8_LDA(At, 1, 0); PG8_STAGE(PG8_SA(0, 1), a2 + hstep, voffA);
;             PG8_WAIT_V(8); PG8_WAIT_L(0); PG8_BAR; PG8_MMA(0, 0, At, B0); PG8_MMA(0, 1, At, B1); PG8_BAR; PG8_SCHED;
	v_mfma_f32_16x16x32_bf16 v[62:65], v[148:151], v[196:199], v[62:65]
	v_mfma_f32_16x16x32_bf16 v[62:65], v[154:157], v[200:203], v[62:65]
	v_mfma_f32_16x16x32_bf16 v[58:61], v[158:161], v[196:199], v[58:61]
	v_mfma_f32_16x16x32_bf16 v[58:61], v[162:165], v[200:203], v[58:61]
	v_mfma_f32_16x16x32_bf16 v[46:49], v[148:151], v[222:225], v[46:49]
	v_mfma_f32_16x16x32_bf16 v[46:49], v[154:157], v[226:229], v[46:49]
	v_mfma_f32_16x16x32_bf16 v[42:45], v[158:161], v[222:225], v[42:45]
	v_mfma_f32_16x16x32_bf16 v[42:45], v[162:165], v[226:229], v[42:45]
	v_mfma_f32_16x16x32_bf16 v[30:33], v[148:151], v[230:233], v[30:33]
	v_mfma_f32_16x16x32_bf16 v[30:33], v[154:157], v[234:237], v[30:33]
	v_mfma_f32_16x16x32_bf16 v[26:29], v[158:161], v[230:233], v[26:29]
	v_mfma_f32_16x16x32_bf16 v[26:29], v[162:165], v[234:237], v[26:29]
	v_mfma_f32_16x16x32_bf16 v[14:17], v[148:151], v[238:241], v[14:17]
	v_mfma_f32_16x16x32_bf16 v[14:17], v[154:157], v[242:245], v[14:17]
	v_mfma_f32_16x16x32_bf16 v[10:13], v[158:161], v[238:241], v[10:13]
	v_mfma_f32_16x16x32_bf16 v[10:13], v[162:165], v[242:245], v[10:13]
	s_setprio 0
	s_setprio 1
	v_mfma_f32_16x16x32_bf16 v[54:57], v[180:183], v[196:199], v[54:57]
	v_mfma_f32_16x16x32_bf16 v[54:57], v[184:187], v[200:203], v[54:57]
	v_mfma_f32_16x16x32_bf16 v[50:53], v[188:191], v[196:199], v[50:53]
	v_mfma_f32_16x16x32_bf16 v[50:53], v[192:195], v[200:203], v[50:53]
	v_mfma_f32_16x16x32_bf16 v[38:41], v[180:183], v[222:225], v[38:41]
	v_mfma_f32_16x16x32_bf16 v[38:41], v[184:187], v[226:229], v[38:41]
	v_mfma_f32_16x16x32_bf16 v[34:37], v[188:191], v[222:225], v[34:37]
	v_mfma_f32_16x16x32_bf16 v[34:37], v[192:195], v[226:229], v[34:37]
	v_mfma_f32_16x16x32_bf16 v[22:25], v[180:183], v[230:233], v[22:25]
	v_mfma_f32_16x16x32_bf16 v[22:25], v[184:187], v[234:237], v[22:25]
	v_mfma_f32_16x16x32_bf16 v[18:21], v[188:191], v[230:233], v[18:21]
	v_mfma_f32_16x16x32_bf16 v[18:21], v[192:195], v[234:237], v[18:21]
	v_mfma_f32_16x16x32_bf16 v[6:9], v[180:183], v[238:241], v[6:9]
	v_mfma_f32_16x16x32_bf16 v[6:9], v[184:187], v[242:245], v[6:9]
	s_setprio 2
	s_barrier
	v_mfma_f32_16x16x32_bf16 v[2:5], v[188:191], v[238:241], v[2:5]
	v_mfma_f32_16x16x32_bf16 v[2:5], v[192:195], v[242:245], v[2:5]
	s_setprio 0
	v_add_u32_e32 v162, vcc_lo, v99
	v_add_u32_e32 v192, vcc_hi, v99
	ds_read_b128 v[148:151], v162
	ds_read_b128 v[154:157], v162 offset:1024
	ds_read_b128 v[158:161], v162 offset:2048
	ds_read_b128 v[162:165], v162 offset:3072
	ds_read_b128 v[180:183], v192
	ds_read_b128 v[184:187], v192 offset:1024
	ds_read_b128 v[188:191], v192 offset:2048
	ds_read_b128 v[192:195], v192 offset:3072
	s_mov_b32 m0, s78
	v_lshl_add_u64 v[246:247], s[56:57], 0, v[138:139]
	ds_read_b128 v[196:199], v153 offset:32768
	ds_read_b128 v[200:203], v153 offset:33792
	ds_read_b128 v[222:225], v153 offset:34816
	ds_read_b128 v[226:229], v153 offset:35840
	ds_read_b128 v[230:233], v153 offset:36864
	ds_read_b128 v[234:237], v153 offset:37888
	ds_read_b128 v[238:241], v153 offset:38912
	ds_read_b128 v[242:245], v153 offset:39936
	global_load_lds_dwordx4 v[246:247], off
	v_lshl_add_u64 v[246:247], s[56:57], 0, v[134:135]
	s_mov_b32 m0, s82
	s_nop 0
	global_load_lds_dwordx4 v[246:247], off
	s_waitcnt vmcnt(8)
	s_waitcnt lgkmcnt(0)
	s_setprio 1
	s_barrier
	v_mfma_f32_16x16x32_bf16 v[128:131], v[148:151], v[196:199], v[128:131]
	v_mfma_f32_16x16x32_bf16 v[128:131], v[154:157], v[200:203], v[128:131]
	v_mfma_f32_16x16x32_bf16 v[124:127], v[158:161], v[196:199], v[124:127]
	v_mfma_f32_16x16x32_bf16 v[124:127], v[162:165], v[200:203], v[124:127]
	v_mfma_f32_16x16x32_bf16 v[112:115], v[148:151], v[222:225], v[112:115]
	v_mfma_f32_16x16x32_bf16 v[112:115], v[154:157], v[226:229], v[112:115]
	v_mfma_f32_16x16x32_bf16 v[108:111], v[158:161], v[222:225], v[108:111]
	v_mfma_f32_16x16x32_bf16 v[108:111], v[162:165], v[226:229], v[108:111]
	v_mfma_f32_16x16x32_bf16 v[94:97], v[148:151], v[230:233], v[94:97]
	v_mfma_f32_16x16x32_bf16 v[94:97], v[154:157], v[234:237], v[94:97]
	v_mfma_f32_16x16x32_bf16 v[90:93], v[158:161], v[230:233], v[90:93]
	v_mfma_f32_16x16x32_bf16 v[90:93], v[162:165], v[234:237], v[90:93]
	v_mfma_f32_16x16x32_bf16 v[78:81], v[148:151], v[238:241], v[78:81]
	v_mfma_f32_16x16x32_bf16 v[78:81], v[154:157], v[242:245], v[78:81]
	v_mfma_f32_16x16x32_bf16 v[74:77], v[158:161], v[238:241], v[74:77]
	v_mfma_f32_16x16x32_bf16 v[74:77], v[162:165], v[242:245], v[74:77]
	s_setprio 0
	s_setprio 1
	v_mfma_f32_16x16x32_bf16 v[120:123], v[180:183], v[196:199], v[120:123]
	v_mfma_f32_16x16x32_bf16 v[120:123], v[184:187], v[200:203], v[120:123]
	v_mfma_f32_16x16x32_bf16 v[116:119], v[188:191], v[196:199], v[116:119]
	v_mfma_f32_16x16x32_bf16 v[116:119], v[192:195], v[200:203], v[116:119]
	v_mfma_f32_16x16x32_bf16 v[104:107], v[180:183], v[222:225], v[104:107]
	v_mfma_f32_16x16x32_bf16 v[104:107], v[184:187], v[226:229], v[104:107]
	v_mfma_f32_16x16x32_bf16 v[100:103], v[188:191], v[222:225], v[100:103]
	v_mfma_f32_16x16x32_bf16 v[100:103], v[192:195], v[226:229], v[100:103]
	v_mfma_f32_16x16x32_bf16 v[86:89], v[180:183], v[230:233], v[86:89]
	v_mfma_f32_16x16x32_bf16 v[86:89], v[184:187], v[234:237], v[86:89]
	v_mfma_f32_16x16x32_bf16 v[82:85], v[188:191], v[230:233], v[82:85]
	v_mfma_f32_16x16x32_bf16 v[82:85], v[192:195], v[234:237], v[82:85]
	v_mfma_f32_16x16x32_bf16 v[70:73], v[180:183], v[238:241], v[70:73]
	v_mfma_f32_16x16x32_bf16 v[70:73], v[184:187], v[242:245], v[70:73]
	s_setprio 2
	s_barrier
; #define PG8_STAGE(bufoff, gbase, voff) do { _Pragma("unroll") for (int _i = 0; _i < 2; ++_i) \
;         __builtin_amdgcn_global_load_lds((const unsigned*)((const char*)(gbase) + (voff)[_i]), (PG8_LAS unsigned*)(lds + (bufoff) + ldsw + _i * 8192), 16, 0, AUX_A); } while (0)
; #define PG8_STAGEB(bufoff, gbase, voff) do { _Pragma("unroll") for (int _i = 0; _i < 2; ++_i) \
;         __builtin_amdgcn_global_load_lds((const unsigned*)((const char*)(gbase) + (voff)[_i]), (PG8_LAS unsigned*)(lds + (bufoff) + ldsw + _i * 8192), 16, 0, AUX_B); } while (0)
; #define PG8_LDA(dst, b, h) do { _Pragma("unroll") for (int m = 0; m < 4; ++m) _Pragma("unroll") for (int k = 0; k < 2; ++k) dst[m][k] = *(const PG8_LAS bf16x8*)(lds + PG8_SA(b, h) + aoff + m * 2048 + k * 1024); } while (0)
; #define PG8_MMA(ai, bj, At, Bt) do { __builtin_amdgcn_s_setprio(1); _Pragma("unroll") for (int m = 0; m < 4; ++m) _Pragma("unroll") for (int n = 0; n < 2; ++n) _Pragma("unroll") for (int k = 0; k < 2; ++k) \
;         acc[ai][bj][m][n] = __builtin_amdgcn_mfma_f32_16x16x32_bf16(Bt[n][k], At[m][k], acc[ai][bj][m][n], 0, 0, 0); __builtin_amdgcn_s_setprio(0); } while (0)
; #define PG8_WAIT_V(n) asm volatile("s_waitcnt vmcnt(" #n ")" ::: "memory")
; #define PG8_WAIT_L(n) asm volatile("s_waitcnt lgkmcnt(" #n ")" ::: "memory")
; #define PG8_BAR __builtin_amdgcn_s_barrier()
; #define PG8_SCHED __builtin_amdgcn_sched_barrier(0)
; template <class Epi, class Sched, bool ALIGN_EPI = false, bool SP2 = false>
; __device__ __forceinline__ void gemm_phase(PG8_LAS unsigned char* lds, const Gemm g, const Sched& S, const Epi& E) {
;     ...
;             PG8_WAIT_V(8); PG8_WAIT_L(0); PG8_BAR; PG8_MMA(0, 0, At, B0); PG8_MMA(0, 1, At, B1); PG8_BAR; PG8_SCHED;
;             PG8_LDA(At, 1, 1); PG8_STAGEB(PG8_SB(1, 0), b3, voffB); PG8_STAGEB(PG8_SB(1, 1), b3 + hstep, voffB); PG8_STAGE(PG8_SA(1, 0), a3, voffA);
;             PG8_WAIT_V(8); PG8_WAIT_L(0); PG8_BAR; PG8_MMA(1, 0, At, B0); PG8_MMA(1, 1, At, B1); PG8_BAR; PG8_SCHED;
	v_mfma_f32_16x16x32_bf16 v[66:69], v[188:191], v[238:241], v[66:69]
	v_mfma_f32_16x16x32_bf16 v[66:69], v[192:195], v[242:245], v[66:69]
	s_setprio 0
	s_mov_b32 m0, s1
	v_lshl_add_u64 v[166:167], v[166:167], 0, s[76:77]
	ds_read_b128 v[196:199], v153 offset:49152
	ds_read_b128 v[200:203], v153 offset:50176
	ds_read_b128 v[222:225], v153 offset:51200
	ds_read_b128 v[226:229], v153 offset:52224
	ds_read_b128 v[230:233], v153 offset:53248
	ds_read_b128 v[234:237], v153 offset:54272
	ds_read_b128 v[238:241], v153 offset:55296
	ds_read_b128 v[242:245], v153 offset:56320
	global_load_lds_dwordx4 v[166:167], off
	v_lshl_add_u64 v[166:167], v[168:169], 0, s[76:77]
	s_mov_b32 m0, s0
	s_nop 0
	global_load_lds_dwordx4 v[166:167], off
	v_lshl_add_u64 v[166:167], s[54:55], 0, v[136:137]
	s_mov_b32 m0, s47
	s_nop 0
	global_load_lds_dwordx4 v[166:167], off
	v_lshl_add_u64 v[166:167], s[54:55], 0, v[132:133]
	s_mov_b32 m0, s46
	s_nop 0
	global_load_lds_dwordx4 v[166:167], off
	v_lshl_add_u64 v[166:167], v[172:173], 0, s[76:77]
	s_mov_b32 m0, s83
	s_nop 0
	global_load_lds_dwordx4 v[166:167], off
	v_lshl_add_u64 v[166:167], v[212:213], 0, s[76:77]
	s_mov_b32 m0, s88
	s_nop 0
	global_load_lds_dwordx4 v[166:167], off
	s_waitcnt vmcnt(8)
	s_waitcnt lgkmcnt(0)
	s_setprio 1
	s_barrier
	v_mfma_f32_16x16x32_bf16 v[62:65], v[148:151], v[196:199], v[62:65]
	v_mfma_f32_16x16x32_bf16 v[62:65], v[154:157], v[200:203], v[62:65]
	v_mfma_f32_16x16x32_bf16 v[58:61], v[158:161], v[196:199], v[58:61]
	v_mfma_f32_16x16x32_bf16 v[58:61], v[162:165], v[200:203], v[58:61]
	v_mfma_f32_16x16x32_bf16 v[46:49], v[148:151], v[222:225], v[46:49]
	v_mfma_f32_16x16x32_bf16 v[46:49], v[154:157], v[226:229], v[46:49]
	v_mfma_f32_16x16x32_bf16 v[42:45], v[158:161], v[222:225], v[42:45]
	v_mfma_f32_16x16x32_bf16 v[42:45], v[162:165], v[226:229], v[42:45]
	v_mfma_f32_16x16x32_bf16 v[30:33], v[148:151], v[230:233], v[30:33]
	v_mfma_f32_16x16x32_bf16 v[30:33], v[154:157], v[234:237], v[30:33]
	v_mfma_f32_16x16x32_bf16 v[26:29], v[158:161], v[230:233], v[26:29]
	v_mfma_f32_16x16x32_bf16 v[26:29], v[162:165], v[234:237], v[26:29]
	v_mfma_f32_16x16x32_bf16 v[14:17], v[148:151], v[238:241], v[14:17]
	v_mfma_f32_16x16x32_bf16 v[14:17], v[154:157], v[242:245], v[14:17]
	v_mfma_f32_16x16x32_bf16 v[10:13], v[158:161], v[238:241], v[10:13]
	v_mfma_f32_16x16x32_bf16 v[10:13], v[162:165], v[242:245], v[10:13]
	s_setprio 0
	s_setprio 1
	v_mfma_f32_16x16x32_bf16 v[54:57], v[180:183], v[196:199], v[54:57]
	v_mfma_f32_16x16x32_bf16 v[54:57], v[184:187], v[200:203], v[54:57]
	v_mfma_f32_16x16x32_bf16 v[50:53], v[188:191], v[196:199], v[50:53]
	v_mfma_f32_16x16x32_bf16 v[50:53], v[192:195], v[200:203], v[50:53]
	v_mfma_f32_16x16x32_bf16 v[38:41], v[180:183], v[222:225], v[38:41]
	v_mfma_f32_16x16x32_bf16 v[38:41], v[184:187], v[226:229], v[38:41]
	v_mfma_f32_16x16x32_bf16 v[34:37], v[188:191], v[222:225], v[34:37]
	v_mfma_f32_16x16x32_bf16 v[34:37], v[192:195], v[226:229], v[34:37]
	v_mfma_f32_16x16x32_bf16 v[22:25], v[180:183], v[230:233], v[22:25]
	v_mfma_f32_16x16x32_bf16 v[22:25], v[184:187], v[234:237], v[22:25]
	v_mfma_f32_16x16x32_bf16 v[18:21], v[188:191], v[230:233], v[18:21]
	v_mfma_f32_16x16x32_bf16 v[18:21], v[192:195], v[234:237], v[18:21]
	v_mfma_f32_16x16x32_bf16 v[6:9], v[180:183], v[238:241], v[6:9]
	v_mfma_f32_16x16x32_bf16 v[6:9], v[184:187], v[242:245], v[6:9]
	s_setprio 2
	s_barrier
	v_mfma_f32_16x16x32_bf16 v[2:5], v[188:191], v[238:241], v[2:5]
	v_mfma_f32_16x16x32_bf16 v[2:5], v[192:195], v[242:245], v[2:5]
	s_setprio 0
	v_lshl_add_u64 v[144:145], v[144:145], 0, s[86:87]
	v_lshl_add_u64 v[146:147], v[146:147], 0, s[86:87]
	s_mov_b32 s29, s81
	s_cbranch_scc0 .LBB0_1157
	s_and_b64 vcc, exec, s[16:17]
	s_cbranch_vccz .LBB0_1160
	s_barrier

; #define PG8_STAGE(bufoff, gbase, voff) do { _Pragma("unroll") for (int _i = 0; _i < 2; ++_i) \
;         __builtin_amdgcn_global_load_lds((const unsigned*)((const char*)(gbase) + (voff)[_i]), (PG8_LAS unsigned*)(lds + (bufoff) + ldsw + _i * 8192), 16, 0, AUX_A); } while (0)
; #define PG8_STAGEB(bufoff, gbase, voff) do { _Pragma("unroll") for (int _i = 0; _i < 2; ++_i) \
;         __builtin_amdgcn_global_load_lds((const unsigned*)((const char*)(gbase) + (voff)[_i]), (PG8_LAS unsigned*)(lds + (bufoff) + ldsw + _i * 8192), 16, 0, AUX_B); } while (0)
; #define PG8_LDA(dst, b, h) do { _Pragma("unroll") for (int m = 0; m < 4; ++m) _Pragma("unroll") for (int k = 0; k < 2; ++k) dst[m][k] = *(const PG8_LAS bf16x8*)(lds + PG8_SA(b, h) + aoff + m * 2048 + k * 1024); } while (0)
; #define PG8_LDB(dst, b, h) do { _Pragma("unroll") for (int n = 0; n < 2; ++n) _Pragma("unroll") for (int k = 0; k < 2; ++k) dst[n][k] = *(const PG8_LAS bf16x8*)(lds + PG8_SB(b, h) + boff + n * 2048 + k * 1024); } while (0)
; #define PG8_WAIT_V(n) asm volatile("s_waitcnt vmcnt(" #n ")" ::: "memory")
; #define PG8_WAIT_L(n) asm volatile("s_waitcnt lgkmcnt(" #n ")" ::: "memory")
; #define PG8_BAR __builtin_amdgcn_s_barrier()
; #define PG8_SCHED __builtin_amdgcn_sched_barrier(0)
; template <class Epi, class Sched, bool ALIGN_EPI = false, bool SP2 = false>
; __device__ __forceinline__ void gemm_phase(PG8_LAS unsigned char* lds, const Gemm g, const Sched& S, const Epi& E) {
;     ...
;         for (int t = 0; t < nt; t += 2) {
;             const bool last = (t == nt - 2);
;             const char* a1 = PG8_KP(cA, t + 1, rot, nt);
;             const char* a2 = last ? nAr : PG8_KP(cA, t + 2, rot, nt); const char* b2 = last ? nBr : PG8_KP(cB, t + 2, rot, nt);
;             const char* a3 = a2 + kstep; const char* b3 = b2 + kstep;
;             if (last && has_next) S.a_ready(nxt);
;             if constexpr (SP2) {
;             PG8_LDB(B0, 0, 0); PG8_LDB(B1, 0, 1); PG8_SCHED; PG8_LDA(At, 0, 0); PG8_STAGE(PG8_SA(1, 1), a1 + hstep, voffA);
;             PG8_WAIT_V(8); PG8_WAIT_L(0); PG8_BAR; PG8_MMA(0, 0, At, B0); PG8_MMA(0, 1, At, B1); PG8_BAR; PG8_SCHED;
;             PG8_LDA(At, 0, 1); PG8_STAGEB(PG8_SB(0, 0), b2, voffB); PG8_STAGEB(PG8_SB(0, 1), b2 + hstep, voffB); PG8_STAGE(PG8_SA(0, 0), a2, voffA);
.LBB0_1308:
	s_or_b32 s0, s11, 1
	s_cmp_ge_i32 s0, s71
	s_cselect_b32 s2, s71, 0
	s_add_i32 s11, s11, 2
	s_cmp_ge_i32 s11, s71
	s_cselect_b32 s0, s71, 0
	s_sub_i32 s0, s13, s0
	s_ashr_i32 s1, s0, 31
	s_lshl_b64 s[0:1], s[0:1], 7
	s_add_u32 s15, s40, s0
	s_addc_u32 s29, s41, s1
	s_add_u32 s0, s34, s0
	s_addc_u32 s1, s35, s1
	s_cmp_eq_u32 s71, s13
	s_cselect_b32 s45, s43, s29
	s_cselect_b32 s44, s42, s15
	s_cselect_b32 s37, s19, s1
	s_cselect_b32 s36, s18, s0
	s_add_i32 s15, 0, 0x10000
	s_add_i32 s29, 0, 0x14000
	v_add_u32_e32 v148, s15, v99
	v_add_u32_e32 v168, s29, v99
	ds_read_b128 v[136:139], v148
	ds_read_b128 v[140:143], v148 offset:1024
	ds_read_b128 v[144:147], v148 offset:2048
	ds_read_b128 v[148:151], v148 offset:3072
	ds_read_b128 v[164:167], v168
	ds_read_b128 v[182:185], v168 offset:1024
	ds_read_b128 v[186:189], v168 offset:2048
	ds_read_b128 v[190:193], v168 offset:3072
	v_mad_i64_i32 v[168:169], s[0:1], s2, v220, v[134:135]
	s_add_i32 m0, s50, 0xc000
	ds_read_b128 v[194:197], v181
	ds_read_b128 v[198:201], v181 offset:1024
	ds_read_b128 v[222:225], v181 offset:2048
	ds_read_b128 v[226:229], v181 offset:3072
	ds_read_b128 v[230:233], v181 offset:4096
	ds_read_b128 v[234:237], v181 offset:5120
	ds_read_b128 v[238:241], v181 offset:6144
	ds_read_b128 v[242:245], v181 offset:7168
	global_load_lds_dwordx4 v[168:169], off
	v_mad_i64_i32 v[168:169], s[0:1], s2, v220, v[132:133]
	s_add_i32 m0, s50, 0xe000
	s_nop 0
	global_load_lds_dwordx4 v[168:169], off
	s_waitcnt vmcnt(8)
	s_waitcnt lgkmcnt(0)
	s_setprio 1
	s_barrier
	v_mfma_f32_16x16x32_bf16 v[128:131], v[136:139], v[194:197], v[128:131]
	v_mfma_f32_16x16x32_bf16 v[128:131], v[140:143], v[198:201], v[128:131]
	v_mfma_f32_16x16x32_bf16 v[124:127], v[144:147], v[194:197], v[124:127]
	v_mfma_f32_16x16x32_bf16 v[124:127], v[148:151], v[198:201], v[124:127]
	v_mfma_f32_16x16x32_bf16 v[120:123], v[136:139], v[222:225], v[120:123]
	v_mfma_f32_16x16x32_bf16 v[120:123], v[140:143], v[226:229], v[120:123]
	v_mfma_f32_16x16x32_bf16 v[112:115], v[144:147], v[222:225], v[112:115]
	v_mfma_f32_16x16x32_bf16 v[112:115], v[148:151], v[226:229], v[112:115]
	v_mfma_f32_16x16x32_bf16 v[104:107], v[136:139], v[230:233], v[104:107]
	v_mfma_f32_16x16x32_bf16 v[104:107], v[140:143], v[234:237], v[104:107]
	v_mfma_f32_16x16x32_bf16 v[94:97], v[144:147], v[230:233], v[94:97]
	v_mfma_f32_16x16x32_bf16 v[94:97], v[148:151], v[234:237], v[94:97]
	v_mfma_f32_16x16x32_bf16 v[86:89], v[136:139], v[238:241], v[86:89]
	v_mfma_f32_16x16x32_bf16 v[86:89], v[140:143], v[242:245], v[86:89]
	v_mfma_f32_16x16x32_bf16 v[78:81], v[144:147], v[238:241], v[78:81]
	v_mfma_f32_16x16x32_bf16 v[78:81], v[148:151], v[242:245], v[78:81]
	s_setprio 0
	s_setprio 1
	v_mfma_f32_16x16x32_bf16 v[116:119], v[164:167], v[194:197], v[116:119]
	v_mfma_f32_16x16x32_bf16 v[116:119], v[182:185], v[198:201], v[116:119]
	v_mfma_f32_16x16x32_bf16 v[108:111], v[186:189], v[194:197], v[108:111]
	v_mfma_f32_16x16x32_bf16 v[108:111], v[190:193], v[198:201], v[108:111]
	v_mfma_f32_16x16x32_bf16 v[100:103], v[164:167], v[222:225], v[100:103]
	v_mfma_f32_16x16x32_bf16 v[100:103], v[182:185], v[226:229], v[100:103]
	v_mfma_f32_16x16x32_bf16 v[90:93], v[186:189], v[222:225], v[90:93]
	v_mfma_f32_16x16x32_bf16 v[90:93], v[190:193], v[226:229], v[90:93]
	v_mfma_f32_16x16x32_bf16 v[82:85], v[164:167], v[230:233], v[82:85]
	v_mfma_f32_16x16x32_bf16 v[82:85], v[182:185], v[234:237], v[82:85]
	v_mfma_f32_16x16x32_bf16 v[74:77], v[186:189], v[230:233], v[74:77]
	v_mfma_f32_16x16x32_bf16 v[74:77], v[190:193], v[234:237], v[74:77]
	v_mfma_f32_16x16x32_bf16 v[70:73], v[164:167], v[238:241], v[70:73]
	v_mfma_f32_16x16x32_bf16 v[70:73], v[182:185], v[242:245], v[70:73]
	s_setprio 2
	s_barrier
	v_mfma_f32_16x16x32_bf16 v[66:69], v[186:189], v[238:241], v[66:69]
	v_mfma_f32_16x16x32_bf16 v[66:69], v[190:193], v[242:245], v[66:69]
	s_setprio 0
	s_add_i32 s0, s15, s49
	v_lshl_add_u64 v[168:169], s[36:37], 0, v[156:157]
	s_mov_b32 m0, s0
	ds_read_b128 v[194:197], v181 offset:16384
	ds_read_b128 v[198:201], v181 offset:17408
	ds_read_b128 v[222:225], v181 offset:18432
	ds_read_b128 v[226:229], v181 offset:19456
	ds_read_b128 v[230:233], v181 offset:20480
	ds_read_b128 v[234:237], v181 offset:21504
	ds_read_b128 v[238:241], v181 offset:22528
	ds_read_b128 v[242:245], v181 offset:23552
	global_load_lds_dwordx4 v[168:169], off
	s_add_i32 m0, s0, 0x2000
	s_add_u32 s0, s36, 0x80000
	v_lshl_add_u64 v[172:173], s[36:37], 0, v[152:153]
	s_addc_u32 s1, s37, 0
	s_add_i32 s2, s29, s49
	global_load_lds_dwordx4 v[172:173], off
	v_lshl_add_u64 v[202:203], s[0:1], 0, v[156:157]
	s_mov_b32 m0, s2
	v_lshl_add_u64 v[212:213], s[44:45], 0, v[154:155]
	global_load_lds_dwordx4 v[202:203], off
	v_lshl_add_u64 v[202:203], s[0:1], 0, v[152:153]
	s_add_i32 m0, s2, 0x2000
	s_nop 0
	global_load_lds_dwordx4 v[202:203], off
	v_lshl_add_u64 v[202:203], s[44:45], 0, v[158:159]
	s_mov_b32 m0, s50
	s_nop 0
	global_load_lds_dwordx4 v[202:203], off
	s_mov_b32 m0, s51
	s_nop 0
	global_load_lds_dwordx4 v[212:213], off
	s_waitcnt vmcnt(8)
	s_waitcnt lgkmcnt(0)
	s_setprio 1
	s_barrier
; #define PG8_STAGE(bufoff, gbase, voff) do { _Pragma("unroll") for (int _i = 0; _i < 2; ++_i) \
;         __builtin_amdgcn_global_load_lds((const unsigned*)((const char*)(gbase) + (voff)[_i]), (PG8_LAS unsigned*)(lds + (bufoff) + ldsw + _i * 8192), 16, 0, AUX_A); } while (0)
; #define PG8_STAGEB(bufoff, gbase, voff) do { _Pragma("unroll") for (int _i = 0; _i < 2; ++_i) \
;         __builtin_amdgcn_global_load_lds((const unsigned*)((const char*)(gbase) + (voff)[_i]), (PG8_LAS unsigned*)(lds + (bufoff) + ldsw + _i * 8192), 16, 0, AUX_B); } while (0)
; #define PG8_LDA(dst, b, h) do { _Pragma("unroll") for (int m = 0; m < 4; ++m) _Pragma("unroll") for (int k = 0; k < 2; ++k) dst[m][k] = *(const PG8_LAS bf16x8*)(lds + PG8_SA(b, h) + aoff + m * 2048 + k * 1024); } while (0)
; #define PG8_LDB(dst, b, h) do { _Pragma("unroll") for (int n = 0; n < 2; ++n) _Pragma("unroll") for (int k = 0; k < 2; ++k) dst[n][k] = *(const PG8_LAS bf16x8*)(lds + PG8_SB(b, h) + boff + n * 2048 + k * 1024); } while (0)
; #define PG8_MMA(ai, bj, At, Bt) do { __builtin_amdgcn_s_setprio(1); _Pragma("unroll") for (int m = 0; m < 4; ++m) _Pragma("unroll") for (int n = 0; n < 2; ++n) _Pragma("unroll") for (int k = 0; k < 2; ++k) \
;         acc[ai][bj][m][n] = __builtin_amdgcn_mfma_f32_16x16x32_bf16(Bt[n][k], At[m][k], acc[ai][bj][m][n], 0, 0, 0); __builtin_amdgcn_s_setprio(0); } while (0)
; #define PG8_WAIT_V(n) asm volatile("s_waitcnt vmcnt(" #n ")" ::: "memory")
; #define PG8_WAIT_L(n) asm volatile("s_waitcnt lgkmcnt(" #n ")" ::: "memory")
; #define PG8_BAR __builtin_amdgcn_s_barrier()
; #define PG8_SCHED __builtin_amdgcn_sched_barrier(0)
; template <class Epi, class Sched, bool ALIGN_EPI = false, bool SP2 = false>
; __device__ __forceinline__ void gemm_phase(PG8_LAS unsigned char* lds, const Gemm g, const Sched& S, const Epi& E) {
;     ...
;             PG8_LDA(At, 0, 1); PG8_STAGEB(PG8_SB(0, 0), b2, voffB); PG8_STAGEB(PG8_SB(0, 1), b2 + hstep, voffB); PG8_STAGE(PG8_SA(0, 0), a2, voffA);
;             PG8_WAIT_V(8); PG8_WAIT_L(0); PG8_BAR; PG8_MMA(1, 0, At, B0); PG8_MMA(1, 1, At, B1); PG8_BAR; PG8_SCHED;
;             PG8_LDB(B0, 1, 0); PG8_LDB(B1, 1, 1); PG8_SCHED; PG8_LDA(At, 1, 0); PG8_STAGE(PG8_SA(0, 1), a2 + hstep, voffA);
;             PG8_WAIT_V(8); PG8_WAIT_L(0); PG8_BAR; PG8_MMA(0, 0, At, B0); PG8_MMA(0, 1, At, B1); PG8_BAR; PG8_SCHED;
	v_mfma_f32_16x16x32_bf16 v[62:65], v[136:139], v[194:197], v[62:65]
	v_mfma_f32_16x16x32_bf16 v[62:65], v[140:143], v[198:201], v[62:65]
	v_mfma_f32_16x16x32_bf16 v[58:61], v[144:147], v[194:197], v[58:61]
	v_mfma_f32_16x16x32_bf16 v[58:61], v[148:151], v[198:201], v[58:61]
	v_mfma_f32_16x16x32_bf16 v[54:57], v[136:139], v[222:225], v[54:57]
	v_mfma_f32_16x16x32_bf16 v[54:57], v[140:143], v[226:229], v[54:57]
	v_mfma_f32_16x16x32_bf16 v[46:49], v[144:147], v[222:225], v[46:49]
	v_mfma_f32_16x16x32_bf16 v[46:49], v[148:151], v[226:229], v[46:49]
	v_mfma_f32_16x16x32_bf16 v[38:41], v[136:139], v[230:233], v[38:41]
	v_mfma_f32_16x16x32_bf16 v[38:41], v[140:143], v[234:237], v[38:41]
	v_mfma_f32_16x16x32_bf16 v[30:33], v[144:147], v[230:233], v[30:33]
	v_mfma_f32_16x16x32_bf16 v[30:33], v[148:151], v[234:237], v[30:33]
	v_mfma_f32_16x16x32_bf16 v[22:25], v[136:139], v[238:241], v[22:25]
	v_mfma_f32_16x16x32_bf16 v[22:25], v[140:143], v[242:245], v[22:25]
	v_mfma_f32_16x16x32_bf16 v[14:17], v[144:147], v[238:241], v[14:17]
	v_mfma_f32_16x16x32_bf16 v[14:17], v[148:151], v[242:245], v[14:17]
	s_setprio 0
	s_setprio 1
	v_mfma_f32_16x16x32_bf16 v[50:53], v[164:167], v[194:197], v[50:53]
	v_mfma_f32_16x16x32_bf16 v[50:53], v[182:185], v[198:201], v[50:53]
	v_mfma_f32_16x16x32_bf16 v[42:45], v[186:189], v[194:197], v[42:45]
	v_mfma_f32_16x16x32_bf16 v[42:45], v[190:193], v[198:201], v[42:45]
	v_mfma_f32_16x16x32_bf16 v[34:37], v[164:167], v[222:225], v[34:37]
	v_mfma_f32_16x16x32_bf16 v[34:37], v[182:185], v[226:229], v[34:37]
	v_mfma_f32_16x16x32_bf16 v[26:29], v[186:189], v[222:225], v[26:29]
	v_mfma_f32_16x16x32_bf16 v[26:29], v[190:193], v[226:229], v[26:29]
	v_mfma_f32_16x16x32_bf16 v[18:21], v[164:167], v[230:233], v[18:21]
	v_mfma_f32_16x16x32_bf16 v[18:21], v[182:185], v[234:237], v[18:21]
	v_mfma_f32_16x16x32_bf16 v[10:13], v[186:189], v[230:233], v[10:13]
	v_mfma_f32_16x16x32_bf16 v[10:13], v[190:193], v[234:237], v[10:13]
	v_mfma_f32_16x16x32_bf16 v[6:9], v[164:167], v[238:241], v[6:9]
	v_mfma_f32_16x16x32_bf16 v[6:9], v[182:185], v[242:245], v[6:9]
	s_setprio 2
	s_barrier
	v_mfma_f32_16x16x32_bf16 v[2:5], v[186:189], v[238:241], v[2:5]
	v_mfma_f32_16x16x32_bf16 v[2:5], v[190:193], v[242:245], v[2:5]
	s_setprio 0
	s_add_i32 s2, 0, 0x18000
	s_add_i32 s15, 0, 0x1c000
	v_add_u32_e32 v148, s2, v99
	v_add_u32_e32 v190, s15, v99
	ds_read_b128 v[136:139], v148
	ds_read_b128 v[140:143], v148 offset:1024
	ds_read_b128 v[144:147], v148 offset:2048
	ds_read_b128 v[148:151], v148 offset:3072
	ds_read_b128 v[164:167], v190
	ds_read_b128 v[182:185], v190 offset:1024
	ds_read_b128 v[186:189], v190 offset:2048
	ds_read_b128 v[190:193], v190 offset:3072
	s_add_u32 s0, s44, 0x80000
	s_addc_u32 s1, s45, 0
	s_mov_b32 m0, s52
	v_lshl_add_u64 v[246:247], s[0:1], 0, v[158:159]
	ds_read_b128 v[194:197], v181 offset:32768
	ds_read_b128 v[198:201], v181 offset:33792
	ds_read_b128 v[222:225], v181 offset:34816
	ds_read_b128 v[226:229], v181 offset:35840
	ds_read_b128 v[230:233], v181 offset:36864
	ds_read_b128 v[234:237], v181 offset:37888
	ds_read_b128 v[238:241], v181 offset:38912
	ds_read_b128 v[242:245], v181 offset:39936
	global_load_lds_dwordx4 v[246:247], off
	v_lshl_add_u64 v[246:247], s[0:1], 0, v[154:155]
	s_mov_b32 m0, s53
	s_nop 0
	global_load_lds_dwordx4 v[246:247], off
	s_waitcnt vmcnt(8)
	s_waitcnt lgkmcnt(0)
	s_setprio 1
	s_barrier
	v_mfma_f32_16x16x32_bf16 v[128:131], v[136:139], v[194:197], v[128:131]
	v_mfma_f32_16x16x32_bf16 v[128:131], v[140:143], v[198:201], v[128:131]
	v_mfma_f32_16x16x32_bf16 v[124:127], v[144:147], v[194:197], v[124:127]
	v_mfma_f32_16x16x32_bf16 v[124:127], v[148:151], v[198:201], v[124:127]
	v_mfma_f32_16x16x32_bf16 v[120:123], v[136:139], v[222:225], v[120:123]
	v_mfma_f32_16x16x32_bf16 v[120:123], v[140:143], v[226:229], v[120:123]
	v_mfma_f32_16x16x32_bf16 v[112:115], v[144:147], v[222:225], v[112:115]
	v_mfma_f32_16x16x32_bf16 v[112:115], v[148:151], v[226:229], v[112:115]
	v_mfma_f32_16x16x32_bf16 v[104:107], v[136:139], v[230:233], v[104:107]
	v_mfma_f32_16x16x32_bf16 v[104:107], v[140:143], v[234:237], v[104:107]
	v_mfma_f32_16x16x32_bf16 v[94:97], v[144:147], v[230:233], v[94:97]
	v_mfma_f32_16x16x32_bf16 v[94:97], v[148:151], v[234:237], v[94:97]
	v_mfma_f32_16x16x32_bf16 v[86:89], v[136:139], v[238:241], v[86:89]
	v_mfma_f32_16x16x32_bf16 v[86:89], v[140:143], v[242:245], v[86:89]
	v_mfma_f32_16x16x32_bf16 v[78:81], v[144:147], v[238:241], v[78:81]
	v_mfma_f32_16x16x32_bf16 v[78:81], v[148:151], v[242:245], v[78:81]
	s_setprio 0
	s_setprio 1
	v_mfma_f32_16x16x32_bf16 v[116:119], v[164:167], v[194:197], v[116:119]
	v_mfma_f32_16x16x32_bf16 v[116:119], v[182:185], v[198:201], v[116:119]
	v_mfma_f32_16x16x32_bf16 v[108:111], v[186:189], v[194:197], v[108:111]
	v_mfma_f32_16x16x32_bf16 v[108:111], v[190:193], v[198:201], v[108:111]
	v_mfma_f32_16x16x32_bf16 v[100:103], v[164:167], v[222:225], v[100:103]
	v_mfma_f32_16x16x32_bf16 v[100:103], v[182:185], v[226:229], v[100:103]
	v_mfma_f32_16x16x32_bf16 v[90:93], v[186:189], v[222:225], v[90:93]
	v_mfma_f32_16x16x32_bf16 v[90:93], v[190:193], v[226:229], v[90:93]
	v_mfma_f32_16x16x32_bf16 v[82:85], v[164:167], v[230:233], v[82:85]
	v_mfma_f32_16x16x32_bf16 v[82:85], v[182:185], v[234:237], v[82:85]
	v_mfma_f32_16x16x32_bf16 v[74:77], v[186:189], v[230:233], v[74:77]
	v_mfma_f32_16x16x32_bf16 v[74:77], v[190:193], v[234:237], v[74:77]
	v_mfma_f32_16x16x32_bf16 v[70:73], v[164:167], v[238:241], v[70:73]
	v_mfma_f32_16x16x32_bf16 v[70:73], v[182:185], v[242:245], v[70:73]
	s_setprio 2
	s_barrier
; #define PG8_STAGE(bufoff, gbase, voff) do { _Pragma("unroll") for (int _i = 0; _i < 2; ++_i) \
;         __builtin_amdgcn_global_load_lds((const unsigned*)((const char*)(gbase) + (voff)[_i]), (PG8_LAS unsigned*)(lds + (bufoff) + ldsw + _i * 8192), 16, 0, AUX_A); } while (0)
; #define PG8_STAGEB(bufoff, gbase, voff) do { _Pragma("unroll") for (int _i = 0; _i < 2; ++_i) \
;         __builtin_amdgcn_global_load_lds((const unsigned*)((const char*)(gbase) + (voff)[_i]), (PG8_LAS unsigned*)(lds + (bufoff) + ldsw + _i * 8192), 16, 0, AUX_B); } while (0)
; #define PG8_LDA(dst, b, h) do { _Pragma("unroll") for (int m = 0; m < 4; ++m) _Pragma("unroll") for (int k = 0; k < 2; ++k) dst[m][k] = *(const PG8_LAS bf16x8*)(lds + PG8_SA(b, h) + aoff + m * 2048 + k * 1024); } while (0)
; #define PG8_LDB(dst, b, h) do { _Pragma("unroll") for (int n = 0; n < 2; ++n) _Pragma("unroll") for (int k = 0; k < 2; ++k) dst[n][k] = *(const PG8_LAS bf16x8*)(lds + PG8_SB(b, h) + boff + n * 2048 + k * 1024); } while (0)
; #define PG8_MMA(ai, bj, At, Bt) do { __builtin_amdgcn_s_setprio(1); _Pragma("unroll") for (int m = 0; m < 4; ++m) _Pragma("unroll") for (int n = 0; n < 2; ++n) _Pragma("unroll") for (int k = 0; k < 2; ++k) \
;         acc[ai][bj][m][n] = __builtin_amdgcn_mfma_f32_16x16x32_bf16(Bt[n][k], At[m][k], acc[ai][bj][m][n], 0, 0, 0); __builtin_amdgcn_s_setprio(0); } while (0)
; #define PG8_WAIT_V(n) asm volatile("s_waitcnt vmcnt(" #n ")" ::: "memory")
; #define PG8_WAIT_L(n) asm volatile("s_waitcnt lgkmcnt(" #n ")" ::: "memory")
; #define PG8_BAR __builtin_amdgcn_s_barrier()
; #define PG8_SCHED __builtin_amdgcn_sched_barrier(0)
; template <class Epi, class Sched, bool ALIGN_EPI = false, bool SP2 = false>
; __device__ __forceinline__ void gemm_phase(PG8_LAS unsigned char* lds, const Gemm g, const Sched& S, const Epi& E) {
;     ...
;             PG8_LDB(B0, 1, 0); PG8_LDB(B1, 1, 1); PG8_SCHED; PG8_LDA(At, 1, 0); PG8_STAGE(PG8_SA(0, 1), a2 + hstep, voffA);
;             PG8_WAIT_V(8); PG8_WAIT_L(0); PG8_BAR; PG8_MMA(0, 0, At, B0); PG8_MMA(0, 1, At, B1); PG8_BAR; PG8_SCHED;
;             PG8_LDA(At, 1, 1); PG8_STAGEB(PG8_SB(1, 0), b3, voffB); PG8_STAGEB(PG8_SB(1, 1), b3 + hstep, voffB); PG8_STAGE(PG8_SA(1, 0), a3, voffA);
;             PG8_WAIT_V(8); PG8_WAIT_L(0); PG8_BAR; PG8_MMA(1, 0, At, B0); PG8_MMA(1, 1, At, B1); PG8_BAR; PG8_SCHED;
	v_mfma_f32_16x16x32_bf16 v[66:69], v[186:189], v[238:241], v[66:69]
	v_mfma_f32_16x16x32_bf16 v[66:69], v[190:193], v[242:245], v[66:69]
	s_setprio 0
	s_add_i32 s0, s2, s49
	v_lshl_add_u64 v[168:169], v[168:169], 0, s[76:77]
	s_mov_b32 m0, s0
	ds_read_b128 v[194:197], v181 offset:49152
	ds_read_b128 v[198:201], v181 offset:50176
	ds_read_b128 v[222:225], v181 offset:51200
	ds_read_b128 v[226:229], v181 offset:52224
	ds_read_b128 v[230:233], v181 offset:53248
	ds_read_b128 v[234:237], v181 offset:54272
	ds_read_b128 v[238:241], v181 offset:55296
	ds_read_b128 v[242:245], v181 offset:56320
	global_load_lds_dwordx4 v[168:169], off
	s_add_i32 m0, s0, 0x2000
	s_add_u32 s0, s36, 0x80080
	v_lshl_add_u64 v[168:169], v[172:173], 0, s[76:77]
	s_addc_u32 s1, s37, 0
	s_add_i32 s2, s15, s49
	global_load_lds_dwordx4 v[168:169], off
	v_lshl_add_u64 v[168:169], s[0:1], 0, v[156:157]
	s_mov_b32 m0, s2
	s_nop 0
	global_load_lds_dwordx4 v[168:169], off
	v_lshl_add_u64 v[168:169], s[0:1], 0, v[152:153]
	s_add_i32 m0, s2, 0x2000
	s_nop 0
	global_load_lds_dwordx4 v[168:169], off
	v_lshl_add_u64 v[168:169], v[202:203], 0, s[76:77]
	s_mov_b32 m0, s59
	s_nop 0
	global_load_lds_dwordx4 v[168:169], off
	v_lshl_add_u64 v[168:169], v[212:213], 0, s[76:77]
	s_mov_b32 m0, s60
	s_nop 0
	global_load_lds_dwordx4 v[168:169], off
	s_waitcnt vmcnt(8)
	s_waitcnt lgkmcnt(0)
	s_setprio 1
	s_barrier
	v_mfma_f32_16x16x32_bf16 v[62:65], v[136:139], v[194:197], v[62:65]
	v_mfma_f32_16x16x32_bf16 v[62:65], v[140:143], v[198:201], v[62:65]
	v_mfma_f32_16x16x32_bf16 v[58:61], v[144:147], v[194:197], v[58:61]
	v_mfma_f32_16x16x32_bf16 v[58:61], v[148:151], v[198:201], v[58:61]
	v_mfma_f32_16x16x32_bf16 v[54:57], v[136:139], v[222:225], v[54:57]
	v_mfma_f32_16x16x32_bf16 v[54:57], v[140:143], v[226:229], v[54:57]
	v_mfma_f32_16x16x32_bf16 v[46:49], v[144:147], v[222:225], v[46:49]
	v_mfma_f32_16x16x32_bf16 v[46:49], v[148:151], v[226:229], v[46:49]
	v_mfma_f32_16x16x32_bf16 v[38:41], v[136:139], v[230:233], v[38:41]
	v_mfma_f32_16x16x32_bf16 v[38:41], v[140:143], v[234:237], v[38:41]
	v_mfma_f32_16x16x32_bf16 v[30:33], v[144:147], v[230:233], v[30:33]
	v_mfma_f32_16x16x32_bf16 v[30:33], v[148:151], v[234:237], v[30:33]
	v_mfma_f32_16x16x32_bf16 v[22:25], v[136:139], v[238:241], v[22:25]
	v_mfma_f32_16x16x32_bf16 v[22:25], v[140:143], v[242:245], v[22:25]
	v_mfma_f32_16x16x32_bf16 v[14:17], v[144:147], v[238:241], v[14:17]
	v_mfma_f32_16x16x32_bf16 v[14:17], v[148:151], v[242:245], v[14:17]
	s_setprio 0
	s_setprio 1
	v_mfma_f32_16x16x32_bf16 v[50:53], v[164:167], v[194:197], v[50:53]
	v_mfma_f32_16x16x32_bf16 v[50:53], v[182:185], v[198:201], v[50:53]
	v_mfma_f32_16x16x32_bf16 v[42:45], v[186:189], v[194:197], v[42:45]
	v_mfma_f32_16x16x32_bf16 v[42:45], v[190:193], v[198:201], v[42:45]
	v_mfma_f32_16x16x32_bf16 v[34:37], v[164:167], v[222:225], v[34:37]
	v_mfma_f32_16x16x32_bf16 v[34:37], v[182:185], v[226:229], v[34:37]
	v_mfma_f32_16x16x32_bf16 v[26:29], v[186:189], v[222:225], v[26:29]
	v_mfma_f32_16x16x32_bf16 v[26:29], v[190:193], v[226:229], v[26:29]
	v_mfma_f32_16x16x32_bf16 v[18:21], v[164:167], v[230:233], v[18:21]
	v_mfma_f32_16x16x32_bf16 v[18:21], v[182:185], v[234:237], v[18:21]
	v_mfma_f32_16x16x32_bf16 v[10:13], v[186:189], v[230:233], v[10:13]
	v_mfma_f32_16x16x32_bf16 v[10:13], v[190:193], v[234:237], v[10:13]
	v_mfma_f32_16x16x32_bf16 v[6:9], v[164:167], v[238:241], v[6:9]
	v_mfma_f32_16x16x32_bf16 v[6:9], v[182:185], v[242:245], v[6:9]
	s_setprio 2
	s_barrier
	v_mfma_f32_16x16x32_bf16 v[2:5], v[186:189], v[238:241], v[2:5]
	v_mfma_f32_16x16x32_bf16 v[2:5], v[190:193], v[242:245], v[2:5]
	s_setprio 0
	s_add_i32 s0, s13, 2
	v_lshl_add_u64 v[132:133], v[132:133], 0, s[86:87]
	v_lshl_add_u64 v[134:135], v[134:135], 0, s[86:87]
	s_cmp_ge_i32 s13, s71
	s_mov_b32 s13, s0
	s_cbranch_scc0 .LBB0_1308
	s_and_b64 vcc, exec, s[8:9]
	s_cbranch_vccz .LBB0_1311
	s_barrier

; #define PG8_STAGE(bufoff, gbase, voff) do { _Pragma("unroll") for (int _i = 0; _i < 2; ++_i) \
;         __builtin_amdgcn_global_load_lds((const unsigned*)((const char*)(gbase) + (voff)[_i]), (PG8_LAS unsigned*)(lds + (bufoff) + ldsw + _i * 8192), 16, 0, AUX_A); } while (0)
; #define PG8_STAGEB(bufoff, gbase, voff) do { _Pragma("unroll") for (int _i = 0; _i < 2; ++_i) \
;         __builtin_amdgcn_global_load_lds((const unsigned*)((const char*)(gbase) + (voff)[_i]), (PG8_LAS unsigned*)(lds + (bufoff) + ldsw + _i * 8192), 16, 0, AUX_B); } while (0)
; #define PG8_WAIT_V(n) asm volatile("s_waitcnt vmcnt(" #n ")" ::: "memory")
; #define PG8_BAR __builtin_amdgcn_s_barrier()
; template <class Epi, class Sched, bool ALIGN_EPI = false, bool SP2 = false>
; __device__ __forceinline__ void gemm_phase(PG8_LAS unsigned char* lds, const Gemm g, const Sched& S, const Epi& E) {
;     ...
;     const int aoff = lds_byte(wr * 64 + fr, fq * 8), boff = lds_byte(wc * 32 + fr, fq * 8);
;     ...
;         PG8_WAIT_V(2); PG8_BAR;
;         PG8_STAGEB(PG8_SB(1, 0), sB1, voffB); PG8_STAGE(PG8_SA(1, 0), sA1, voffA); PG8_STAGEB(PG8_SB(1, 1), sB1 + hstep, voffB);
;         PG8_WAIT_V(6); PG8_BAR;
.LBB0_1452:
	s_add_u32 s8, s4, 0x2f580000
	v_lshrrev_b32_e32 v18, 1, v16
	s_addc_u32 s9, s5, 0
	v_and_b32_e32 v18, 24, v18
	s_lshl_b32 s0, s0, 5
	v_and_b32_e32 v17, 15, v16
	v_lshlrev_b32_e32 v19, 1, v18
	v_lshlrev_b32_e32 v16, 2, v16
	s_and_b32 s2, s0, 0x60
	s_add_i32 m0, s57, 0x18000
	v_lshl_add_u64 v[8:9], v[8:9], 0, s[76:77]
	v_lshl_or_b32 v1, s1, 6, v17
	v_lshl_or_b32 v17, v17, 6, v19
	s_lshl_b32 s1, s1, 13
	v_and_b32_e32 v16, 32, v16
	s_lshl_b32 s0, s2, 7
	s_waitcnt vmcnt(2)
	s_barrier
	global_load_lds_dwordx4 v[8:9], off
	v_lshl_add_u64 v[6:7], v[6:7], 0, s[76:77]
	s_add_i32 m0, s57, 0x1a000
	s_add_i32 s61, s57, 0x8000
	s_add_i32 s62, s57, 0xa000
	v_bitop3_b32 v99, v17, s0, v16 bitop3:0xde
	global_load_lds_dwordx4 v[6:7], off
	s_add_u32 s0, s34, 0x80080
	v_bitop3_b32 v19, v17, s1, v16 bitop3:0xde
	s_addc_u32 s1, s35, 0
	s_add_i32 m0, s57, 0x1c000
	v_lshl_add_u64 v[2:3], s[0:1], 0, v[136:137]
	global_load_lds_dwordx4 v[2:3], off
	v_lshl_add_u64 v[2:3], s[0:1], 0, v[132:133]
	s_add_i32 m0, s57, 0x1e000
	s_cmpk_lt_u32 s10, 0x100
	global_load_lds_dwordx4 v[2:3], off
	v_lshlrev_b32_e32 v2, 15, v10
	v_and_b32_e32 v2, 0xffff0000, v2
	v_lshl_add_u32 v2, v11, 12, v2
	v_and_b32_e32 v3, 1, v10
	v_lshl_or_b32 v2, v3, 6, v2
	v_lshl_add_u32 v140, v12, 1, v2
	v_lshlrev_b32_e32 v2, 15, v14
	v_and_b32_e32 v2, 0xffff0000, v2
	s_waitcnt vmcnt(4)
	v_lshl_add_u32 v2, v13, 12, v2
	v_and_b32_e32 v3, 1, v14
	v_lshl_or_b32 v2, v3, 6, v2
	v_readlane_b32 s0, v252, 37
	s_cselect_b64 s[10:11], -1, 0
	v_or_b32_e32 v148, s2, v18
	v_mov_b32_e32 v141, v98
	v_lshl_add_u32 v142, v15, 1, v2
	v_mov_b32_e32 v143, v98
	s_mov_b32 s63, 0
	v_add_u32_e32 v149, 0, v19
	v_readlane_b32 s69, v253, 6
	s_mov_b32 s70, s0
	s_movk_i32 s3, 0xc7
	s_mov_b32 s64, 0x58000
	s_mov_b32 s65, 0x2c000
	s_mov_b32 s66, 0x84000
	s_barrier
	v_readlane_b32 s1, v252, 38
	s_branch .LBB0_1455

; #define PG8_STAGE(bufoff, gbase, voff) do { _Pragma("unroll") for (int _i = 0; _i < 2; ++_i) \
;         __builtin_amdgcn_global_load_lds((const unsigned*)((const char*)(gbase) + (voff)[_i]), (PG8_LAS unsigned*)(lds + (bufoff) + ldsw + _i * 8192), 16, 0, AUX_A); } while (0)
; #define PG8_STAGEB(bufoff, gbase, voff) do { _Pragma("unroll") for (int _i = 0; _i < 2; ++_i) \
;         __builtin_amdgcn_global_load_lds((const unsigned*)((const char*)(gbase) + (voff)[_i]), (PG8_LAS unsigned*)(lds + (bufoff) + ldsw + _i * 8192), 16, 0, AUX_B); } while (0)
; #define PG8_LDA(dst, b, h) do { _Pragma("unroll") for (int m = 0; m < 4; ++m) _Pragma("unroll") for (int k = 0; k < 2; ++k) dst[m][k] = *(const PG8_LAS bf16x8*)(lds + PG8_SA(b, h) + aoff + m * 2048 + k * 1024); } while (0)
; #define PG8_LDB(dst, b, h) do { _Pragma("unroll") for (int n = 0; n < 2; ++n) _Pragma("unroll") for (int k = 0; k < 2; ++k) dst[n][k] = *(const PG8_LAS bf16x8*)(lds + PG8_SB(b, h) + boff + n * 2048 + k * 1024); } while (0)
; #define PG8_WAIT_V(n) asm volatile("s_waitcnt vmcnt(" #n ")" ::: "memory")
; #define PG8_WAIT_L(n) asm volatile("s_waitcnt lgkmcnt(" #n ")" ::: "memory")
; #define PG8_BAR __builtin_amdgcn_s_barrier()
; template <class Epi, class Sched, bool ALIGN_EPI = false, bool SP2 = false>
; __device__ __forceinline__ void gemm_phase(PG8_LAS unsigned char* lds, const Gemm g, const Sched& S, const Epi& E) {
;     ...
;         for (int t = 0; t < nt; t += 2) {
;             const bool last = (t == nt - 2);
;             const char* a1 = PG8_KP(cA, t + 1, rot, nt);
;             const char* a2 = last ? nAr : PG8_KP(cA, t + 2, rot, nt); const char* b2 = last ? nBr : PG8_KP(cB, t + 2, rot, nt);
;             const char* a3 = a2 + kstep; const char* b3 = b2 + kstep;
;             if (last && has_next) S.a_ready(nxt);
;             if constexpr (SP2) {
;             PG8_LDB(B0, 0, 0); PG8_LDB(B1, 0, 1); PG8_SCHED; PG8_LDA(At, 0, 0); PG8_STAGE(PG8_SA(1, 1), a1 + hstep, voffA);
;             PG8_WAIT_V(8); PG8_WAIT_L(0); PG8_BAR; PG8_MMA(0, 0, At, B0); PG8_MMA(0, 1, At, B1); PG8_BAR; PG8_SCHED;
;             PG8_LDA(At, 0, 1); PG8_STAGEB(PG8_SB(0, 0), b2, voffB); PG8_STAGEB(PG8_SB(0, 1), b2 + hstep, voffB); PG8_STAGE(PG8_SA(0, 0), a2, voffA);
;             PG8_WAIT_V(8); PG8_WAIT_L(0); PG8_BAR; PG8_MMA(1, 0, At, B0); PG8_MMA(1, 1, At, B1); PG8_BAR; PG8_SCHED;
.LBB0_1458:
	s_lshl_b32 s100, s29, 7
	s_add_u32 s100, s40, s100
	s_addc_u32 s101, s41, 0
	s_add_u32 s100, s100, 0x80
	s_addc_u32 s101, s101, 0
	s_add_i32 s30, s29, 2
	s_cmp_lt_u32 s29, 30
	s_cselect_b32 s0, 0, 0xffffffe0
	s_add_i32 s0, s30, s0
	s_ashr_i32 s1, s0, 31
	s_lshl_b64 s[0:1], s[0:1], 7
	s_add_u32 s2, s40, s0
	s_addc_u32 s31, s41, s1
	s_add_u32 s0, s34, s0
	s_addc_u32 s1, s35, s1
	s_cmp_eq_u32 s29, 30
	s_cselect_b32 s45, s13, s31
	s_cselect_b32 s44, s15, s2
	s_cselect_b32 s49, s71, s1
	s_cselect_b32 s48, s75, s0
	s_add_i32 s2, 0, 0x10000
	s_add_i32 s78, s2, s56
	s_add_i32 s31, 0, 0x14000
	s_add_i32 s47, s57, 0xe000
	s_add_i32 s81, s78, 0x2000
	s_add_u32 s50, s48, 0x80000
	s_addc_u32 s51, s49, 0
	s_add_i32 s82, s31, s56
	v_add_u32_e32 v162, s2, v99
	v_add_u32_e32 v166, s31, v99
	s_add_i32 s83, s82, 0x2000
	s_add_i32 s84, 0, 0x18000
	s_add_i32 s88, 0, 0x1c000
	ds_read_b128 v[150:153], v162
	ds_read_b128 v[154:157], v162 offset:1024
	ds_read_b128 v[158:161], v162 offset:2048
	ds_read_b128 v[162:165], v162 offset:3072
	ds_read_b128 v[180:183], v166
	ds_read_b128 v[184:187], v166 offset:1024
	ds_read_b128 v[188:191], v166 offset:2048
	ds_read_b128 v[192:195], v166 offset:3072
	s_add_u32 s42, s44, 0x80000
	s_addc_u32 s43, s45, 0
	s_add_i32 s1, s84, s56
	s_add_i32 s0, s1, 0x2000
	s_add_u32 s36, s48, 0x80080
	s_addc_u32 s37, s49, 0
	s_add_i32 s46, s88, s56
	s_add_i32 s31, s46, 0x2000
	ds_read_b128 v[196:199], v149
	ds_read_b128 v[200:203], v149 offset:1024
	ds_read_b128 v[222:225], v149 offset:2048
	ds_read_b128 v[226:229], v149 offset:3072
	ds_read_b128 v[230:233], v149 offset:4096
	ds_read_b128 v[234:237], v149 offset:5120
	ds_read_b128 v[238:241], v149 offset:6144
	ds_read_b128 v[242:245], v149 offset:7168
	v_lshl_add_u64 v[166:167], s[100:101], 0, v[138:139]
	s_mov_b32 m0, s61
	v_lshl_add_u64 v[168:169], s[100:101], 0, v[134:135]
	global_load_lds_dwordx4 v[166:167], off
	s_mov_b32 m0, s62
	s_nop 0
	global_load_lds_dwordx4 v[168:169], off
	s_add_i32 m0, s57, 0xc000
	s_nop 0
	global_load_lds_dwordx4 v[146:147], off
	s_mov_b32 m0, s47
	s_nop 0
	global_load_lds_dwordx4 v[144:145], off
	s_waitcnt vmcnt(8)
	s_waitcnt lgkmcnt(0)
	s_setprio 1
	s_barrier
	v_mfma_f32_16x16x32_bf16 v[128:131], v[150:153], v[196:199], v[128:131]
	v_mfma_f32_16x16x32_bf16 v[128:131], v[154:157], v[200:203], v[128:131]
	v_mfma_f32_16x16x32_bf16 v[120:123], v[158:161], v[196:199], v[120:123]
	v_mfma_f32_16x16x32_bf16 v[120:123], v[162:165], v[200:203], v[120:123]
	v_mfma_f32_16x16x32_bf16 v[112:115], v[150:153], v[222:225], v[112:115]
	v_mfma_f32_16x16x32_bf16 v[112:115], v[154:157], v[226:229], v[112:115]
	v_mfma_f32_16x16x32_bf16 v[104:107], v[158:161], v[222:225], v[104:107]
	v_mfma_f32_16x16x32_bf16 v[104:107], v[162:165], v[226:229], v[104:107]
	v_mfma_f32_16x16x32_bf16 v[94:97], v[150:153], v[230:233], v[94:97]
	v_mfma_f32_16x16x32_bf16 v[94:97], v[154:157], v[234:237], v[94:97]
	v_mfma_f32_16x16x32_bf16 v[86:89], v[158:161], v[230:233], v[86:89]
	v_mfma_f32_16x16x32_bf16 v[86:89], v[162:165], v[234:237], v[86:89]
	v_mfma_f32_16x16x32_bf16 v[78:81], v[150:153], v[238:241], v[78:81]
	v_mfma_f32_16x16x32_bf16 v[78:81], v[154:157], v[242:245], v[78:81]
	v_mfma_f32_16x16x32_bf16 v[70:73], v[158:161], v[238:241], v[70:73]
	v_mfma_f32_16x16x32_bf16 v[70:73], v[162:165], v[242:245], v[70:73]
	s_setprio 0
	s_setprio 1
	v_mfma_f32_16x16x32_bf16 v[124:127], v[180:183], v[196:199], v[124:127]
	v_mfma_f32_16x16x32_bf16 v[124:127], v[184:187], v[200:203], v[124:127]
	v_mfma_f32_16x16x32_bf16 v[116:119], v[188:191], v[196:199], v[116:119]
	v_mfma_f32_16x16x32_bf16 v[116:119], v[192:195], v[200:203], v[116:119]
	v_mfma_f32_16x16x32_bf16 v[108:111], v[180:183], v[222:225], v[108:111]
	v_mfma_f32_16x16x32_bf16 v[108:111], v[184:187], v[226:229], v[108:111]
	v_mfma_f32_16x16x32_bf16 v[100:103], v[188:191], v[222:225], v[100:103]
	v_mfma_f32_16x16x32_bf16 v[100:103], v[192:195], v[226:229], v[100:103]
	v_mfma_f32_16x16x32_bf16 v[90:93], v[180:183], v[230:233], v[90:93]
	v_mfma_f32_16x16x32_bf16 v[90:93], v[184:187], v[234:237], v[90:93]
	v_mfma_f32_16x16x32_bf16 v[82:85], v[188:191], v[230:233], v[82:85]
	v_mfma_f32_16x16x32_bf16 v[82:85], v[192:195], v[234:237], v[82:85]
	v_mfma_f32_16x16x32_bf16 v[74:77], v[180:183], v[238:241], v[74:77]
	v_mfma_f32_16x16x32_bf16 v[74:77], v[184:187], v[242:245], v[74:77]
	s_setprio 2
	s_barrier
	v_mfma_f32_16x16x32_bf16 v[66:69], v[188:191], v[238:241], v[66:69]
	v_mfma_f32_16x16x32_bf16 v[66:69], v[192:195], v[242:245], v[66:69]
	s_setprio 0
	s_mov_b32 m0, s78
	v_lshl_add_u64 v[166:167], s[48:49], 0, v[136:137]
	ds_read_b128 v[196:199], v149 offset:16384
	ds_read_b128 v[200:203], v149 offset:17408
	ds_read_b128 v[222:225], v149 offset:18432
	ds_read_b128 v[226:229], v149 offset:19456
	ds_read_b128 v[230:233], v149 offset:20480
	ds_read_b128 v[234:237], v149 offset:21504
	ds_read_b128 v[238:241], v149 offset:22528
	ds_read_b128 v[242:245], v149 offset:23552
	global_load_lds_dwordx4 v[166:167], off
	v_lshl_add_u64 v[168:169], s[48:49], 0, v[132:133]
	s_mov_b32 m0, s81
	v_lshl_add_u64 v[172:173], s[50:51], 0, v[136:137]
	global_load_lds_dwordx4 v[168:169], off
	s_mov_b32 m0, s82
	global_load_lds_dwordx4 v[172:173], off
	v_lshl_add_u64 v[172:173], s[50:51], 0, v[132:133]
	s_mov_b32 m0, s83
	s_nop 0
	global_load_lds_dwordx4 v[172:173], off
	s_waitcnt vmcnt(6)
	s_waitcnt lgkmcnt(0)
	s_setprio 1
	s_barrier
; #define PG8_STAGE(bufoff, gbase, voff) do { _Pragma("unroll") for (int _i = 0; _i < 2; ++_i) \
;         __builtin_amdgcn_global_load_lds((const unsigned*)((const char*)(gbase) + (voff)[_i]), (PG8_LAS unsigned*)(lds + (bufoff) + ldsw + _i * 8192), 16, 0, AUX_A); } while (0)
; #define PG8_LDA(dst, b, h) do { _Pragma("unroll") for (int m = 0; m < 4; ++m) _Pragma("unroll") for (int k = 0; k < 2; ++k) dst[m][k] = *(const PG8_LAS bf16x8*)(lds + PG8_SA(b, h) + aoff + m * 2048 + k * 1024); } while (0)
; #define PG8_LDB(dst, b, h) do { _Pragma("unroll") for (int n = 0; n < 2; ++n) _Pragma("unroll") for (int k = 0; k < 2; ++k) dst[n][k] = *(const PG8_LAS bf16x8*)(lds + PG8_SB(b, h) + boff + n * 2048 + k * 1024); } while (0)
; #define PG8_MMA(ai, bj, At, Bt) do { __builtin_amdgcn_s_setprio(1); _Pragma("unroll") for (int m = 0; m < 4; ++m) _Pragma("unroll") for (int n = 0; n < 2; ++n) _Pragma("unroll") for (int k = 0; k < 2; ++k) \
;         acc[ai][bj][m][n] = __builtin_amdgcn_mfma_f32_16x16x32_bf16(Bt[n][k], At[m][k], acc[ai][bj][m][n], 0, 0, 0); __builtin_amdgcn_s_setprio(0); } while (0)
; #define PG8_WAIT_V(n) asm volatile("s_waitcnt vmcnt(" #n ")" ::: "memory")
; #define PG8_WAIT_L(n) asm volatile("s_waitcnt lgkmcnt(" #n ")" ::: "memory")
; #define PG8_BAR __builtin_amdgcn_s_barrier()
; #define PG8_SCHED __builtin_amdgcn_sched_barrier(0)
; template <class Epi, class Sched, bool ALIGN_EPI = false, bool SP2 = false>
; __device__ __forceinline__ void gemm_phase(PG8_LAS unsigned char* lds, const Gemm g, const Sched& S, const Epi& E) {
;     ...
;             PG8_WAIT_V(8); PG8_WAIT_L(0); PG8_BAR; PG8_MMA(1, 0, At, B0); PG8_MMA(1, 1, At, B1); PG8_BAR; PG8_SCHED;
;             PG8_LDB(B0, 1, 0); PG8_LDB(B1, 1, 1); PG8_SCHED; PG8_LDA(At, 1, 0); PG8_STAGE(PG8_SA(0, 1), a2 + hstep, voffA);
;             PG8_WAIT_V(8); PG8_WAIT_L(0); PG8_BAR; PG8_MMA(0, 0, At, B0); PG8_MMA(0, 1, At, B1); PG8_BAR; PG8_SCHED;
	v_mfma_f32_16x16x32_bf16 v[62:65], v[150:153], v[196:199], v[62:65]
	v_mfma_f32_16x16x32_bf16 v[62:65], v[154:157], v[200:203], v[62:65]
	v_mfma_f32_16x16x32_bf16 v[54:57], v[158:161], v[196:199], v[54:57]
	v_mfma_f32_16x16x32_bf16 v[54:57], v[162:165], v[200:203], v[54:57]
	v_mfma_f32_16x16x32_bf16 v[46:49], v[150:153], v[222:225], v[46:49]
	v_mfma_f32_16x16x32_bf16 v[46:49], v[154:157], v[226:229], v[46:49]
	v_mfma_f32_16x16x32_bf16 v[38:41], v[158:161], v[222:225], v[38:41]
	v_mfma_f32_16x16x32_bf16 v[38:41], v[162:165], v[226:229], v[38:41]
	v_mfma_f32_16x16x32_bf16 v[30:33], v[150:153], v[230:233], v[30:33]
	v_mfma_f32_16x16x32_bf16 v[30:33], v[154:157], v[234:237], v[30:33]
	v_mfma_f32_16x16x32_bf16 v[22:25], v[158:161], v[230:233], v[22:25]
	v_mfma_f32_16x16x32_bf16 v[22:25], v[162:165], v[234:237], v[22:25]
	v_mfma_f32_16x16x32_bf16 v[14:17], v[150:153], v[238:241], v[14:17]
	v_mfma_f32_16x16x32_bf16 v[14:17], v[154:157], v[242:245], v[14:17]
	v_mfma_f32_16x16x32_bf16 v[6:9], v[158:161], v[238:241], v[6:9]
	v_mfma_f32_16x16x32_bf16 v[6:9], v[162:165], v[242:245], v[6:9]
	s_setprio 0
	s_setprio 1
	v_mfma_f32_16x16x32_bf16 v[58:61], v[180:183], v[196:199], v[58:61]
	v_mfma_f32_16x16x32_bf16 v[58:61], v[184:187], v[200:203], v[58:61]
	v_mfma_f32_16x16x32_bf16 v[50:53], v[188:191], v[196:199], v[50:53]
	v_mfma_f32_16x16x32_bf16 v[50:53], v[192:195], v[200:203], v[50:53]
	v_mfma_f32_16x16x32_bf16 v[42:45], v[180:183], v[222:225], v[42:45]
	v_mfma_f32_16x16x32_bf16 v[42:45], v[184:187], v[226:229], v[42:45]
	v_mfma_f32_16x16x32_bf16 v[34:37], v[188:191], v[222:225], v[34:37]
	v_mfma_f32_16x16x32_bf16 v[34:37], v[192:195], v[226:229], v[34:37]
	v_mfma_f32_16x16x32_bf16 v[26:29], v[180:183], v[230:233], v[26:29]
	v_mfma_f32_16x16x32_bf16 v[26:29], v[184:187], v[234:237], v[26:29]
	v_mfma_f32_16x16x32_bf16 v[18:21], v[188:191], v[230:233], v[18:21]
	v_mfma_f32_16x16x32_bf16 v[18:21], v[192:195], v[234:237], v[18:21]
	v_mfma_f32_16x16x32_bf16 v[10:13], v[180:183], v[238:241], v[10:13]
	v_mfma_f32_16x16x32_bf16 v[10:13], v[184:187], v[242:245], v[10:13]
	s_setprio 2
	s_barrier
	v_mfma_f32_16x16x32_bf16 v[2:5], v[188:191], v[238:241], v[2:5]
	v_mfma_f32_16x16x32_bf16 v[2:5], v[192:195], v[242:245], v[2:5]
	s_setprio 0
	v_add_u32_e32 v162, s84, v99
	v_add_u32_e32 v192, s88, v99
	ds_read_b128 v[150:153], v162
	ds_read_b128 v[154:157], v162 offset:1024
	ds_read_b128 v[158:161], v162 offset:2048
	ds_read_b128 v[162:165], v162 offset:3072
	ds_read_b128 v[180:183], v192
	ds_read_b128 v[184:187], v192 offset:1024
	ds_read_b128 v[188:191], v192 offset:2048
	ds_read_b128 v[192:195], v192 offset:3072
	s_mov_b32 m0, s59
	v_lshl_add_u64 v[246:247], s[42:43], 0, v[138:139]
	ds_read_b128 v[196:199], v149 offset:32768
	ds_read_b128 v[200:203], v149 offset:33792
	ds_read_b128 v[222:225], v149 offset:34816
	ds_read_b128 v[226:229], v149 offset:35840
	ds_read_b128 v[230:233], v149 offset:36864
	ds_read_b128 v[234:237], v149 offset:37888
	ds_read_b128 v[238:241], v149 offset:38912
	ds_read_b128 v[242:245], v149 offset:39936
	v_lshl_add_u64 v[172:173], s[44:45], 0, v[138:139]
	s_mov_b32 m0, s57
	v_lshl_add_u64 v[212:213], s[44:45], 0, v[134:135]
	global_load_lds_dwordx4 v[172:173], off
	s_mov_b32 m0, s58
	s_nop 0
	global_load_lds_dwordx4 v[212:213], off
	s_mov_b32 m0, s59
	s_nop 0
	global_load_lds_dwordx4 v[246:247], off
	v_lshl_add_u64 v[246:247], s[42:43], 0, v[134:135]
	s_mov_b32 m0, s60
	s_nop 0
	global_load_lds_dwordx4 v[246:247], off
	s_waitcnt vmcnt(8)
	s_waitcnt lgkmcnt(0)
	s_setprio 1
	s_barrier
; #define PG8_STAGE(bufoff, gbase, voff) do { _Pragma("unroll") for (int _i = 0; _i < 2; ++_i) \
;         __builtin_amdgcn_global_load_lds((const unsigned*)((const char*)(gbase) + (voff)[_i]), (PG8_LAS unsigned*)(lds + (bufoff) + ldsw + _i * 8192), 16, 0, AUX_A); } while (0)
; #define PG8_STAGEB(bufoff, gbase, voff) do { _Pragma("unroll") for (int _i = 0; _i < 2; ++_i) \
;         __builtin_amdgcn_global_load_lds((const unsigned*)((const char*)(gbase) + (voff)[_i]), (PG8_LAS unsigned*)(lds + (bufoff) + ldsw + _i * 8192), 16, 0, AUX_B); } while (0)
; #define PG8_LDA(dst, b, h) do { _Pragma("unroll") for (int m = 0; m < 4; ++m) _Pragma("unroll") for (int k = 0; k < 2; ++k) dst[m][k] = *(const PG8_LAS bf16x8*)(lds + PG8_SA(b, h) + aoff + m * 2048 + k * 1024); } while (0)
; #define PG8_MMA(ai, bj, At, Bt) do { __builtin_amdgcn_s_setprio(1); _Pragma("unroll") for (int m = 0; m < 4; ++m) _Pragma("unroll") for (int n = 0; n < 2; ++n) _Pragma("unroll") for (int k = 0; k < 2; ++k) \
;         acc[ai][bj][m][n] = __builtin_amdgcn_mfma_f32_16x16x32_bf16(Bt[n][k], At[m][k], acc[ai][bj][m][n], 0, 0, 0); __builtin_amdgcn_s_setprio(0); } while (0)
; #define PG8_WAIT_V(n) asm volatile("s_waitcnt vmcnt(" #n ")" ::: "memory")
; #define PG8_WAIT_L(n) asm volatile("s_waitcnt lgkmcnt(" #n ")" ::: "memory")
; #define PG8_BAR __builtin_amdgcn_s_barrier()
; #define PG8_SCHED __builtin_amdgcn_sched_barrier(0)
; template <class Epi, class Sched, bool ALIGN_EPI = false, bool SP2 = false>
; __device__ __forceinline__ void gemm_phase(PG8_LAS unsigned char* lds, const Gemm g, const Sched& S, const Epi& E) {
;     ...
;         for (int t = 0; t < nt; t += 2) {
;     ...
;             PG8_WAIT_V(8); PG8_WAIT_L(0); PG8_BAR; PG8_MMA(0, 0, At, B0); PG8_MMA(0, 1, At, B1); PG8_BAR; PG8_SCHED;
;             PG8_LDA(At, 1, 1); PG8_STAGEB(PG8_SB(1, 0), b3, voffB); PG8_STAGEB(PG8_SB(1, 1), b3 + hstep, voffB); PG8_STAGE(PG8_SA(1, 0), a3, voffA);
;             PG8_WAIT_V(8); PG8_WAIT_L(0); PG8_BAR; PG8_MMA(1, 0, At, B0); PG8_MMA(1, 1, At, B1); PG8_BAR; PG8_SCHED;
	v_mfma_f32_16x16x32_bf16 v[128:131], v[150:153], v[196:199], v[128:131]
	v_mfma_f32_16x16x32_bf16 v[128:131], v[154:157], v[200:203], v[128:131]
	v_mfma_f32_16x16x32_bf16 v[120:123], v[158:161], v[196:199], v[120:123]
	v_mfma_f32_16x16x32_bf16 v[120:123], v[162:165], v[200:203], v[120:123]
	v_mfma_f32_16x16x32_bf16 v[112:115], v[150:153], v[222:225], v[112:115]
	v_mfma_f32_16x16x32_bf16 v[112:115], v[154:157], v[226:229], v[112:115]
	v_mfma_f32_16x16x32_bf16 v[104:107], v[158:161], v[222:225], v[104:107]
	v_mfma_f32_16x16x32_bf16 v[104:107], v[162:165], v[226:229], v[104:107]
	v_mfma_f32_16x16x32_bf16 v[94:97], v[150:153], v[230:233], v[94:97]
	v_mfma_f32_16x16x32_bf16 v[94:97], v[154:157], v[234:237], v[94:97]
	v_mfma_f32_16x16x32_bf16 v[86:89], v[158:161], v[230:233], v[86:89]
	v_mfma_f32_16x16x32_bf16 v[86:89], v[162:165], v[234:237], v[86:89]
	v_mfma_f32_16x16x32_bf16 v[78:81], v[150:153], v[238:241], v[78:81]
	v_mfma_f32_16x16x32_bf16 v[78:81], v[154:157], v[242:245], v[78:81]
	v_mfma_f32_16x16x32_bf16 v[70:73], v[158:161], v[238:241], v[70:73]
	v_mfma_f32_16x16x32_bf16 v[70:73], v[162:165], v[242:245], v[70:73]
	s_setprio 0
	s_setprio 1
	v_mfma_f32_16x16x32_bf16 v[124:127], v[180:183], v[196:199], v[124:127]
	v_mfma_f32_16x16x32_bf16 v[124:127], v[184:187], v[200:203], v[124:127]
	v_mfma_f32_16x16x32_bf16 v[116:119], v[188:191], v[196:199], v[116:119]
	v_mfma_f32_16x16x32_bf16 v[116:119], v[192:195], v[200:203], v[116:119]
	v_mfma_f32_16x16x32_bf16 v[108:111], v[180:183], v[222:225], v[108:111]
	v_mfma_f32_16x16x32_bf16 v[108:111], v[184:187], v[226:229], v[108:111]
	v_mfma_f32_16x16x32_bf16 v[100:103], v[188:191], v[222:225], v[100:103]
	v_mfma_f32_16x16x32_bf16 v[100:103], v[192:195], v[226:229], v[100:103]
	v_mfma_f32_16x16x32_bf16 v[90:93], v[180:183], v[230:233], v[90:93]
	v_mfma_f32_16x16x32_bf16 v[90:93], v[184:187], v[234:237], v[90:93]
	v_mfma_f32_16x16x32_bf16 v[82:85], v[188:191], v[230:233], v[82:85]
	v_mfma_f32_16x16x32_bf16 v[82:85], v[192:195], v[234:237], v[82:85]
	v_mfma_f32_16x16x32_bf16 v[74:77], v[180:183], v[238:241], v[74:77]
	v_mfma_f32_16x16x32_bf16 v[74:77], v[184:187], v[242:245], v[74:77]
	s_setprio 2
	s_barrier
	v_mfma_f32_16x16x32_bf16 v[66:69], v[188:191], v[238:241], v[66:69]
	v_mfma_f32_16x16x32_bf16 v[66:69], v[192:195], v[242:245], v[66:69]
	s_setprio 0
	s_mov_b32 m0, s1
	v_lshl_add_u64 v[166:167], v[166:167], 0, s[76:77]
	ds_read_b128 v[196:199], v149 offset:49152
	ds_read_b128 v[200:203], v149 offset:50176
	ds_read_b128 v[222:225], v149 offset:51200
	ds_read_b128 v[226:229], v149 offset:52224
	ds_read_b128 v[230:233], v149 offset:53248
	ds_read_b128 v[234:237], v149 offset:54272
	ds_read_b128 v[238:241], v149 offset:55296
	ds_read_b128 v[242:245], v149 offset:56320
	global_load_lds_dwordx4 v[166:167], off
	v_lshl_add_u64 v[166:167], v[168:169], 0, s[76:77]
	s_mov_b32 m0, s0
	s_nop 0
	global_load_lds_dwordx4 v[166:167], off
	v_lshl_add_u64 v[166:167], s[36:37], 0, v[136:137]
	s_mov_b32 m0, s46
	s_nop 0
	global_load_lds_dwordx4 v[166:167], off
	v_lshl_add_u64 v[166:167], s[36:37], 0, v[132:133]
	s_mov_b32 m0, s31
	s_nop 0
	global_load_lds_dwordx4 v[166:167], off
	s_waitcnt vmcnt(6)
	s_waitcnt lgkmcnt(0)
	s_setprio 1
	s_barrier
	v_mfma_f32_16x16x32_bf16 v[62:65], v[150:153], v[196:199], v[62:65]
	v_mfma_f32_16x16x32_bf16 v[62:65], v[154:157], v[200:203], v[62:65]
	v_mfma_f32_16x16x32_bf16 v[54:57], v[158:161], v[196:199], v[54:57]
	v_mfma_f32_16x16x32_bf16 v[54:57], v[162:165], v[200:203], v[54:57]
	v_mfma_f32_16x16x32_bf16 v[46:49], v[150:153], v[222:225], v[46:49]
	v_mfma_f32_16x16x32_bf16 v[46:49], v[154:157], v[226:229], v[46:49]
	v_mfma_f32_16x16x32_bf16 v[38:41], v[158:161], v[222:225], v[38:41]
	v_mfma_f32_16x16x32_bf16 v[38:41], v[162:165], v[226:229], v[38:41]
	v_mfma_f32_16x16x32_bf16 v[30:33], v[150:153], v[230:233], v[30:33]
	v_mfma_f32_16x16x32_bf16 v[30:33], v[154:157], v[234:237], v[30:33]
	v_mfma_f32_16x16x32_bf16 v[22:25], v[158:161], v[230:233], v[22:25]
	v_mfma_f32_16x16x32_bf16 v[22:25], v[162:165], v[234:237], v[22:25]
	v_mfma_f32_16x16x32_bf16 v[14:17], v[150:153], v[238:241], v[14:17]
	v_mfma_f32_16x16x32_bf16 v[14:17], v[154:157], v[242:245], v[14:17]
	v_mfma_f32_16x16x32_bf16 v[6:9], v[158:161], v[238:241], v[6:9]
	v_mfma_f32_16x16x32_bf16 v[6:9], v[162:165], v[242:245], v[6:9]
	s_setprio 0
	s_setprio 1
	v_mfma_f32_16x16x32_bf16 v[58:61], v[180:183], v[196:199], v[58:61]
	v_mfma_f32_16x16x32_bf16 v[58:61], v[184:187], v[200:203], v[58:61]
	v_mfma_f32_16x16x32_bf16 v[50:53], v[188:191], v[196:199], v[50:53]
	v_mfma_f32_16x16x32_bf16 v[50:53], v[192:195], v[200:203], v[50:53]
	v_mfma_f32_16x16x32_bf16 v[42:45], v[180:183], v[222:225], v[42:45]
	v_mfma_f32_16x16x32_bf16 v[42:45], v[184:187], v[226:229], v[42:45]
	v_mfma_f32_16x16x32_bf16 v[34:37], v[188:191], v[222:225], v[34:37]
	v_mfma_f32_16x16x32_bf16 v[34:37], v[192:195], v[226:229], v[34:37]
	v_mfma_f32_16x16x32_bf16 v[26:29], v[180:183], v[230:233], v[26:29]
	v_mfma_f32_16x16x32_bf16 v[26:29], v[184:187], v[234:237], v[26:29]
	v_mfma_f32_16x16x32_bf16 v[18:21], v[188:191], v[230:233], v[18:21]
	v_mfma_f32_16x16x32_bf16 v[18:21], v[192:195], v[234:237], v[18:21]
	v_mfma_f32_16x16x32_bf16 v[10:13], v[180:183], v[238:241], v[10:13]
	v_mfma_f32_16x16x32_bf16 v[10:13], v[184:187], v[242:245], v[10:13]
	s_setprio 2
	s_barrier
	v_mfma_f32_16x16x32_bf16 v[2:5], v[188:191], v[238:241], v[2:5]
	v_mfma_f32_16x16x32_bf16 v[2:5], v[192:195], v[242:245], v[2:5]
	s_setprio 0
	v_lshl_add_u64 v[144:145], v[144:145], 0, s[86:87]
	v_lshl_add_u64 v[146:147], v[146:147], 0, s[86:87]
	s_cmp_gt_u32 s30, 31
	s_mov_b32 s29, s30
	s_cbranch_scc0 .LBB0_1458
	s_and_b64 vcc, exec, s[10:11]
	s_cbranch_vccz .LBB0_1461
	s_barrier

; #define PG8_STAGE(bufoff, gbase, voff) do { _Pragma("unroll") for (int _i = 0; _i < 2; ++_i) \
;         __builtin_amdgcn_global_load_lds((const unsigned*)((const char*)(gbase) + (voff)[_i]), (PG8_LAS unsigned*)(lds + (bufoff) + ldsw + _i * 8192), 16, 0, AUX_A); } while (0)
; #define PG8_LDA(dst, b, h) do { _Pragma("unroll") for (int m = 0; m < 4; ++m) _Pragma("unroll") for (int k = 0; k < 2; ++k) dst[m][k] = *(const PG8_LAS bf16x8*)(lds + PG8_SA(b, h) + aoff + m * 2048 + k * 1024); } while (0)
; #define PG8_LDB(dst, b, h) do { _Pragma("unroll") for (int n = 0; n < 2; ++n) _Pragma("unroll") for (int k = 0; k < 2; ++k) dst[n][k] = *(const PG8_LAS bf16x8*)(lds + PG8_SB(b, h) + boff + n * 2048 + k * 1024); } while (0)
; #define PG8_WAIT_V(n) asm volatile("s_waitcnt vmcnt(" #n ")" ::: "memory")
; #define PG8_WAIT_L(n) asm volatile("s_waitcnt lgkmcnt(" #n ")" ::: "memory")
; #define PG8_BAR __builtin_amdgcn_s_barrier()
; #define PG8_SCHED __builtin_amdgcn_sched_barrier(0)
; template <class Epi, class Sched, bool ALIGN_EPI = false, bool SP2 = false>
; __device__ __forceinline__ void gemm_phase(PG8_LAS unsigned char* lds, const Gemm g, const Sched& S, const Epi& E) {
;     ...
;         const char* nA = has_next ? (const char*)g.A + (size_t)nxt.pm * tstep + (size_t)nxt.kt0 * kstep : cA; const char* nB = has_next ? (const char*)g.Bt + (size_t)nxt.pn * tstep + (size_t)nxt.kt0 * kstep : cB;
;         const int nt = cur.nkt, rot = cur.krot;
;         const char* nAr = has_next ? nA + (size_t)nxt.krot * kstep : PG8_KP(cA, 0, rot, nt); const char* nBr = has_next ? nB + (size_t)nxt.krot * kstep : PG8_KP(cB, 0, rot, nt);
;         for (int t = 0; t < nt; t += 2) {
;             const bool last = (t == nt - 2);
;             const char* a1 = PG8_KP(cA, t + 1, rot, nt);
;             const char* a2 = last ? nAr : PG8_KP(cA, t + 2, rot, nt); const char* b2 = last ? nBr : PG8_KP(cB, t + 2, rot, nt);
;             const char* a3 = a2 + kstep; const char* b3 = b2 + kstep;
;             if (last && has_next) S.a_ready(nxt);
;             if constexpr (SP2) {
;             PG8_LDB(B0, 0, 0); PG8_LDB(B1, 0, 1); PG8_SCHED; PG8_LDA(At, 0, 0); PG8_STAGE(PG8_SA(1, 1), a1 + hstep, voffA);
;             PG8_WAIT_V(8); PG8_WAIT_L(0); PG8_BAR; PG8_MMA(0, 0, At, B0); PG8_MMA(0, 1, At, B1); PG8_BAR; PG8_SCHED;
.LBB0_1654:
	s_or_b32 s0, s15, 1
	s_cmp_ge_i32 s0, s82
	s_cselect_b32 s2, s82, 0
	s_add_i32 s15, s15, 2
	s_cmp_ge_i32 s15, s82
	s_cselect_b32 s0, s82, 0
	s_sub_i32 s0, s83, s0
	s_ashr_i32 s1, s0, 31
	s_lshl_b64 s[0:1], s[0:1], 7
	s_add_u32 s29, s38, s0
	s_addc_u32 s42, s39, s1
	s_add_u32 s0, s34, s0
	s_addc_u32 s1, s35, s1
	s_cmp_eq_u32 s82, s83
	s_cselect_b32 s45, s41, s42
	s_cselect_b32 s44, s40, s29
	s_cselect_b32 s43, s19, s1
	s_cselect_b32 s42, s18, s0
	s_add_i32 s29, 0, 0x10000
	s_add_i32 s46, 0, 0x14000
	v_add_u32_e32 v148, s29, v99
	v_add_u32_e32 v168, s46, v99
	ds_read_b128 v[136:139], v148
	ds_read_b128 v[140:143], v148 offset:1024
	ds_read_b128 v[144:147], v148 offset:2048
	ds_read_b128 v[148:151], v148 offset:3072
	ds_read_b128 v[152:155], v168
	ds_read_b128 v[180:183], v168 offset:1024
	ds_read_b128 v[184:187], v168 offset:2048
	ds_read_b128 v[190:193], v168 offset:3072
	v_mad_i64_i32 v[168:169], s[0:1], s2, v220, v[134:135]
	s_add_i32 m0, s50, 0xc000
	ds_read_b128 v[194:197], v189
	ds_read_b128 v[198:201], v189 offset:1024
	ds_read_b128 v[222:225], v189 offset:2048
	ds_read_b128 v[226:229], v189 offset:3072
	ds_read_b128 v[230:233], v189 offset:4096
	ds_read_b128 v[234:237], v189 offset:5120
	ds_read_b128 v[238:241], v189 offset:6144
	ds_read_b128 v[242:245], v189 offset:7168
	global_load_lds_dwordx4 v[168:169], off
	v_mad_i64_i32 v[168:169], s[0:1], s2, v220, v[132:133]
	s_add_i32 m0, s50, 0xe000
	s_nop 0
	global_load_lds_dwordx4 v[168:169], off
	s_waitcnt vmcnt(8)
	s_waitcnt lgkmcnt(0)
	s_setprio 1
	s_barrier
	v_mfma_f32_16x16x32_bf16 v[128:131], v[136:139], v[194:197], v[128:131]
	v_mfma_f32_16x16x32_bf16 v[128:131], v[140:143], v[198:201], v[128:131]
	v_mfma_f32_16x16x32_bf16 v[124:127], v[144:147], v[194:197], v[124:127]
	v_mfma_f32_16x16x32_bf16 v[124:127], v[148:151], v[198:201], v[124:127]
	v_mfma_f32_16x16x32_bf16 v[120:123], v[136:139], v[222:225], v[120:123]
	v_mfma_f32_16x16x32_bf16 v[120:123], v[140:143], v[226:229], v[120:123]
	v_mfma_f32_16x16x32_bf16 v[112:115], v[144:147], v[222:225], v[112:115]
	v_mfma_f32_16x16x32_bf16 v[112:115], v[148:151], v[226:229], v[112:115]
	v_mfma_f32_16x16x32_bf16 v[104:107], v[136:139], v[230:233], v[104:107]
	v_mfma_f32_16x16x32_bf16 v[104:107], v[140:143], v[234:237], v[104:107]
	v_mfma_f32_16x16x32_bf16 v[94:97], v[144:147], v[230:233], v[94:97]
	v_mfma_f32_16x16x32_bf16 v[94:97], v[148:151], v[234:237], v[94:97]
	v_mfma_f32_16x16x32_bf16 v[86:89], v[136:139], v[238:241], v[86:89]
	v_mfma_f32_16x16x32_bf16 v[86:89], v[140:143], v[242:245], v[86:89]
	v_mfma_f32_16x16x32_bf16 v[78:81], v[144:147], v[238:241], v[78:81]
	v_mfma_f32_16x16x32_bf16 v[78:81], v[148:151], v[242:245], v[78:81]
	s_setprio 0
	s_setprio 1
	v_mfma_f32_16x16x32_bf16 v[116:119], v[152:155], v[194:197], v[116:119]
	v_mfma_f32_16x16x32_bf16 v[116:119], v[180:183], v[198:201], v[116:119]
	v_mfma_f32_16x16x32_bf16 v[108:111], v[184:187], v[194:197], v[108:111]
	v_mfma_f32_16x16x32_bf16 v[108:111], v[190:193], v[198:201], v[108:111]
	v_mfma_f32_16x16x32_bf16 v[100:103], v[152:155], v[222:225], v[100:103]
	v_mfma_f32_16x16x32_bf16 v[100:103], v[180:183], v[226:229], v[100:103]
	v_mfma_f32_16x16x32_bf16 v[90:93], v[184:187], v[222:225], v[90:93]
	v_mfma_f32_16x16x32_bf16 v[90:93], v[190:193], v[226:229], v[90:93]
	v_mfma_f32_16x16x32_bf16 v[82:85], v[152:155], v[230:233], v[82:85]
	v_mfma_f32_16x16x32_bf16 v[82:85], v[180:183], v[234:237], v[82:85]
	v_mfma_f32_16x16x32_bf16 v[74:77], v[184:187], v[230:233], v[74:77]
	v_mfma_f32_16x16x32_bf16 v[74:77], v[190:193], v[234:237], v[74:77]
	v_mfma_f32_16x16x32_bf16 v[70:73], v[152:155], v[238:241], v[70:73]
	v_mfma_f32_16x16x32_bf16 v[70:73], v[180:183], v[242:245], v[70:73]
	s_setprio 2
	s_barrier
	v_mfma_f32_16x16x32_bf16 v[66:69], v[184:187], v[238:241], v[66:69]
	v_mfma_f32_16x16x32_bf16 v[66:69], v[190:193], v[242:245], v[66:69]
	s_setprio 0
	s_add_i32 s0, s29, s49
	v_lshl_add_u64 v[168:169], s[42:43], 0, v[160:161]
	s_mov_b32 m0, s0
	ds_read_b128 v[194:197], v189 offset:16384
	ds_read_b128 v[198:201], v189 offset:17408
	ds_read_b128 v[222:225], v189 offset:18432
	ds_read_b128 v[226:229], v189 offset:19456
	ds_read_b128 v[230:233], v189 offset:20480
	ds_read_b128 v[234:237], v189 offset:21504
	ds_read_b128 v[238:241], v189 offset:22528
	ds_read_b128 v[242:245], v189 offset:23552
	global_load_lds_dwordx4 v[168:169], off
	s_add_i32 m0, s0, 0x2000
	s_add_u32 s0, s42, 0x160000
	v_lshl_add_u64 v[172:173], s[42:43], 0, v[156:157]
	s_addc_u32 s1, s43, 0
	s_add_i32 s2, s46, s49
	global_load_lds_dwordx4 v[172:173], off
	v_lshl_add_u64 v[202:203], s[0:1], 0, v[160:161]
	s_mov_b32 m0, s2
	v_lshl_add_u64 v[212:213], s[44:45], 0, v[158:159]
	global_load_lds_dwordx4 v[202:203], off
	v_lshl_add_u64 v[202:203], s[0:1], 0, v[156:157]
	s_add_i32 m0, s2, 0x2000
	s_nop 0
	global_load_lds_dwordx4 v[202:203], off
	v_lshl_add_u64 v[202:203], s[44:45], 0, v[162:163]
	s_mov_b32 m0, s50
	s_nop 0
	global_load_lds_dwordx4 v[202:203], off
	s_mov_b32 m0, s51
	s_nop 0
	global_load_lds_dwordx4 v[212:213], off
	s_waitcnt vmcnt(8)
	s_waitcnt lgkmcnt(0)
	s_setprio 1
	s_barrier
; #define PG8_STAGE(bufoff, gbase, voff) do { _Pragma("unroll") for (int _i = 0; _i < 2; ++_i) \
;         __builtin_amdgcn_global_load_lds((const unsigned*)((const char*)(gbase) + (voff)[_i]), (PG8_LAS unsigned*)(lds + (bufoff) + ldsw + _i * 8192), 16, 0, AUX_A); } while (0)
; #define PG8_STAGEB(bufoff, gbase, voff) do { _Pragma("unroll") for (int _i = 0; _i < 2; ++_i) \
;         __builtin_amdgcn_global_load_lds((const unsigned*)((const char*)(gbase) + (voff)[_i]), (PG8_LAS unsigned*)(lds + (bufoff) + ldsw + _i * 8192), 16, 0, AUX_B); } while (0)
; #define PG8_LDA(dst, b, h) do { _Pragma("unroll") for (int m = 0; m < 4; ++m) _Pragma("unroll") for (int k = 0; k < 2; ++k) dst[m][k] = *(const PG8_LAS bf16x8*)(lds + PG8_SA(b, h) + aoff + m * 2048 + k * 1024); } while (0)
; #define PG8_LDB(dst, b, h) do { _Pragma("unroll") for (int n = 0; n < 2; ++n) _Pragma("unroll") for (int k = 0; k < 2; ++k) dst[n][k] = *(const PG8_LAS bf16x8*)(lds + PG8_SB(b, h) + boff + n * 2048 + k * 1024); } while (0)
; #define PG8_MMA(ai, bj, At, Bt) do { __builtin_amdgcn_s_setprio(1); _Pragma("unroll") for (int m = 0; m < 4; ++m) _Pragma("unroll") for (int n = 0; n < 2; ++n) _Pragma("unroll") for (int k = 0; k < 2; ++k) \
;         acc[ai][bj][m][n] = __builtin_amdgcn_mfma_f32_16x16x32_bf16(Bt[n][k], At[m][k], acc[ai][bj][m][n], 0, 0, 0); __builtin_amdgcn_s_setprio(0); } while (0)
; #define PG8_WAIT_V(n) asm volatile("s_waitcnt vmcnt(" #n ")" ::: "memory")
; #define PG8_WAIT_L(n) asm volatile("s_waitcnt lgkmcnt(" #n ")" ::: "memory")
; template <class Epi, class Sched, bool ALIGN_EPI = false, bool SP2 = false>
; __device__ __forceinline__ void gemm_phase(PG8_LAS unsigned char* lds, const Gemm g, const Sched& S, const Epi& E) {
;     ...
;             PG8_WAIT_V(8); PG8_WAIT_L(0); PG8_BAR; PG8_MMA(0, 0, At, B0); PG8_MMA(0, 1, At, B1); PG8_BAR; PG8_SCHED;
;             PG8_LDA(At, 0, 1); PG8_STAGEB(PG8_SB(0, 0), b2, voffB); PG8_STAGEB(PG8_SB(0, 1), b2 + hstep, voffB); PG8_STAGE(PG8_SA(0, 0), a2, voffA);
;             PG8_WAIT_V(8); PG8_WAIT_L(0); PG8_BAR; PG8_MMA(1, 0, At, B0); PG8_MMA(1, 1, At, B1); PG8_BAR; PG8_SCHED;
;             PG8_LDB(B0, 1, 0); PG8_LDB(B1, 1, 1); PG8_SCHED; PG8_LDA(At, 1, 0); PG8_STAGE(PG8_SA(0, 1), a2 + hstep, voffA);
;             PG8_WAIT_V(8); PG8_WAIT_L(0); PG8_BAR; PG8_MMA(0, 0, At, B0); PG8_MMA(0, 1, At, B1); PG8_BAR; PG8_SCHED;
	v_mfma_f32_16x16x32_bf16 v[62:65], v[136:139], v[194:197], v[62:65]
	v_mfma_f32_16x16x32_bf16 v[62:65], v[140:143], v[198:201], v[62:65]
	v_mfma_f32_16x16x32_bf16 v[58:61], v[144:147], v[194:197], v[58:61]
	v_mfma_f32_16x16x32_bf16 v[58:61], v[148:151], v[198:201], v[58:61]
	v_mfma_f32_16x16x32_bf16 v[54:57], v[136:139], v[222:225], v[54:57]
	v_mfma_f32_16x16x32_bf16 v[54:57], v[140:143], v[226:229], v[54:57]
	v_mfma_f32_16x16x32_bf16 v[46:49], v[144:147], v[222:225], v[46:49]
	v_mfma_f32_16x16x32_bf16 v[46:49], v[148:151], v[226:229], v[46:49]
	v_mfma_f32_16x16x32_bf16 v[38:41], v[136:139], v[230:233], v[38:41]
	v_mfma_f32_16x16x32_bf16 v[38:41], v[140:143], v[234:237], v[38:41]
	v_mfma_f32_16x16x32_bf16 v[30:33], v[144:147], v[230:233], v[30:33]
	v_mfma_f32_16x16x32_bf16 v[30:33], v[148:151], v[234:237], v[30:33]
	v_mfma_f32_16x16x32_bf16 v[22:25], v[136:139], v[238:241], v[22:25]
	v_mfma_f32_16x16x32_bf16 v[22:25], v[140:143], v[242:245], v[22:25]
	v_mfma_f32_16x16x32_bf16 v[14:17], v[144:147], v[238:241], v[14:17]
	v_mfma_f32_16x16x32_bf16 v[14:17], v[148:151], v[242:245], v[14:17]
	s_setprio 0
	s_setprio 1
	v_mfma_f32_16x16x32_bf16 v[50:53], v[152:155], v[194:197], v[50:53]
	v_mfma_f32_16x16x32_bf16 v[50:53], v[180:183], v[198:201], v[50:53]
	v_mfma_f32_16x16x32_bf16 v[42:45], v[184:187], v[194:197], v[42:45]
	v_mfma_f32_16x16x32_bf16 v[42:45], v[190:193], v[198:201], v[42:45]
	v_mfma_f32_16x16x32_bf16 v[34:37], v[152:155], v[222:225], v[34:37]
	v_mfma_f32_16x16x32_bf16 v[34:37], v[180:183], v[226:229], v[34:37]
	v_mfma_f32_16x16x32_bf16 v[26:29], v[184:187], v[222:225], v[26:29]
	v_mfma_f32_16x16x32_bf16 v[26:29], v[190:193], v[226:229], v[26:29]
	v_mfma_f32_16x16x32_bf16 v[18:21], v[152:155], v[230:233], v[18:21]
	v_mfma_f32_16x16x32_bf16 v[18:21], v[180:183], v[234:237], v[18:21]
	v_mfma_f32_16x16x32_bf16 v[10:13], v[184:187], v[230:233], v[10:13]
	v_mfma_f32_16x16x32_bf16 v[10:13], v[190:193], v[234:237], v[10:13]
	v_mfma_f32_16x16x32_bf16 v[6:9], v[152:155], v[238:241], v[6:9]
	v_mfma_f32_16x16x32_bf16 v[6:9], v[180:183], v[242:245], v[6:9]
	s_setprio 2
	s_barrier
	v_mfma_f32_16x16x32_bf16 v[2:5], v[184:187], v[238:241], v[2:5]
	v_mfma_f32_16x16x32_bf16 v[2:5], v[190:193], v[242:245], v[2:5]
	s_setprio 0
	s_add_i32 s2, 0, 0x18000
	s_add_i32 s29, 0, 0x1c000
	v_add_u32_e32 v148, s2, v99
	v_add_u32_e32 v190, s29, v99
	ds_read_b128 v[136:139], v148
	ds_read_b128 v[140:143], v148 offset:1024
	ds_read_b128 v[144:147], v148 offset:2048
	ds_read_b128 v[148:151], v148 offset:3072
	ds_read_b128 v[152:155], v190
	ds_read_b128 v[180:183], v190 offset:1024
	ds_read_b128 v[184:187], v190 offset:2048
	ds_read_b128 v[190:193], v190 offset:3072
	s_add_u32 s0, s44, 0x160000
	s_addc_u32 s1, s45, 0
	s_mov_b32 m0, s52
	v_lshl_add_u64 v[246:247], s[0:1], 0, v[162:163]
	ds_read_b128 v[194:197], v189 offset:32768
	ds_read_b128 v[198:201], v189 offset:33792
	ds_read_b128 v[222:225], v189 offset:34816
	ds_read_b128 v[226:229], v189 offset:35840
	ds_read_b128 v[230:233], v189 offset:36864
	ds_read_b128 v[234:237], v189 offset:37888
	ds_read_b128 v[238:241], v189 offset:38912
	ds_read_b128 v[242:245], v189 offset:39936
	global_load_lds_dwordx4 v[246:247], off
	v_lshl_add_u64 v[246:247], s[0:1], 0, v[158:159]
	s_mov_b32 m0, s53
	s_nop 0
	global_load_lds_dwordx4 v[246:247], off
	s_waitcnt vmcnt(8)
	s_waitcnt lgkmcnt(0)
	s_setprio 1
	s_barrier
	v_mfma_f32_16x16x32_bf16 v[128:131], v[136:139], v[194:197], v[128:131]
	v_mfma_f32_16x16x32_bf16 v[128:131], v[140:143], v[198:201], v[128:131]
	v_mfma_f32_16x16x32_bf16 v[124:127], v[144:147], v[194:197], v[124:127]
	v_mfma_f32_16x16x32_bf16 v[124:127], v[148:151], v[198:201], v[124:127]
	v_mfma_f32_16x16x32_bf16 v[120:123], v[136:139], v[222:225], v[120:123]
	v_mfma_f32_16x16x32_bf16 v[120:123], v[140:143], v[226:229], v[120:123]
	v_mfma_f32_16x16x32_bf16 v[112:115], v[144:147], v[222:225], v[112:115]
	v_mfma_f32_16x16x32_bf16 v[112:115], v[148:151], v[226:229], v[112:115]
	v_mfma_f32_16x16x32_bf16 v[104:107], v[136:139], v[230:233], v[104:107]
	v_mfma_f32_16x16x32_bf16 v[104:107], v[140:143], v[234:237], v[104:107]
	v_mfma_f32_16x16x32_bf16 v[94:97], v[144:147], v[230:233], v[94:97]
	v_mfma_f32_16x16x32_bf16 v[94:97], v[148:151], v[234:237], v[94:97]
	v_mfma_f32_16x16x32_bf16 v[86:89], v[136:139], v[238:241], v[86:89]
	v_mfma_f32_16x16x32_bf16 v[86:89], v[140:143], v[242:245], v[86:89]
	v_mfma_f32_16x16x32_bf16 v[78:81], v[144:147], v[238:241], v[78:81]
	v_mfma_f32_16x16x32_bf16 v[78:81], v[148:151], v[242:245], v[78:81]
	s_setprio 0
	s_setprio 1
	v_mfma_f32_16x16x32_bf16 v[116:119], v[152:155], v[194:197], v[116:119]
	v_mfma_f32_16x16x32_bf16 v[116:119], v[180:183], v[198:201], v[116:119]
	v_mfma_f32_16x16x32_bf16 v[108:111], v[184:187], v[194:197], v[108:111]
	v_mfma_f32_16x16x32_bf16 v[108:111], v[190:193], v[198:201], v[108:111]
	v_mfma_f32_16x16x32_bf16 v[100:103], v[152:155], v[222:225], v[100:103]
	v_mfma_f32_16x16x32_bf16 v[100:103], v[180:183], v[226:229], v[100:103]
	v_mfma_f32_16x16x32_bf16 v[90:93], v[184:187], v[222:225], v[90:93]
	v_mfma_f32_16x16x32_bf16 v[90:93], v[190:193], v[226:229], v[90:93]
	v_mfma_f32_16x16x32_bf16 v[82:85], v[152:155], v[230:233], v[82:85]
	v_mfma_f32_16x16x32_bf16 v[82:85], v[180:183], v[234:237], v[82:85]
	v_mfma_f32_16x16x32_bf16 v[74:77], v[184:187], v[230:233], v[74:77]
	v_mfma_f32_16x16x32_bf16 v[74:77], v[190:193], v[234:237], v[74:77]
	v_mfma_f32_16x16x32_bf16 v[70:73], v[152:155], v[238:241], v[70:73]
	v_mfma_f32_16x16x32_bf16 v[70:73], v[180:183], v[242:245], v[70:73]
	s_setprio 2
	s_barrier
; #define PG8_STAGE(bufoff, gbase, voff) do { _Pragma("unroll") for (int _i = 0; _i < 2; ++_i) \
;         __builtin_amdgcn_global_load_lds((const unsigned*)((const char*)(gbase) + (voff)[_i]), (PG8_LAS unsigned*)(lds + (bufoff) + ldsw + _i * 8192), 16, 0, AUX_A); } while (0)
; #define PG8_STAGEB(bufoff, gbase, voff) do { _Pragma("unroll") for (int _i = 0; _i < 2; ++_i) \
;         __builtin_amdgcn_global_load_lds((const unsigned*)((const char*)(gbase) + (voff)[_i]), (PG8_LAS unsigned*)(lds + (bufoff) + ldsw + _i * 8192), 16, 0, AUX_B); } while (0)
; #define PG8_LDA(dst, b, h) do { _Pragma("unroll") for (int m = 0; m < 4; ++m) _Pragma("unroll") for (int k = 0; k < 2; ++k) dst[m][k] = *(const PG8_LAS bf16x8*)(lds + PG8_SA(b, h) + aoff + m * 2048 + k * 1024); } while (0)
; #define PG8_MMA(ai, bj, At, Bt) do { __builtin_amdgcn_s_setprio(1); _Pragma("unroll") for (int m = 0; m < 4; ++m) _Pragma("unroll") for (int n = 0; n < 2; ++n) _Pragma("unroll") for (int k = 0; k < 2; ++k) \
;         acc[ai][bj][m][n] = __builtin_amdgcn_mfma_f32_16x16x32_bf16(Bt[n][k], At[m][k], acc[ai][bj][m][n], 0, 0, 0); __builtin_amdgcn_s_setprio(0); } while (0)
; #define PG8_WAIT_V(n) asm volatile("s_waitcnt vmcnt(" #n ")" ::: "memory")
; #define PG8_WAIT_L(n) asm volatile("s_waitcnt lgkmcnt(" #n ")" ::: "memory")
; #define PG8_BAR __builtin_amdgcn_s_barrier()
; #define PG8_SCHED __builtin_amdgcn_sched_barrier(0)
; template <class Epi, class Sched, bool ALIGN_EPI = false, bool SP2 = false>
; __device__ __forceinline__ void gemm_phase(PG8_LAS unsigned char* lds, const Gemm g, const Sched& S, const Epi& E) {
;     ...
;             PG8_WAIT_V(8); PG8_WAIT_L(0); PG8_BAR; PG8_MMA(0, 0, At, B0); PG8_MMA(0, 1, At, B1); PG8_BAR; PG8_SCHED;
;             PG8_LDA(At, 1, 1); PG8_STAGEB(PG8_SB(1, 0), b3, voffB); PG8_STAGEB(PG8_SB(1, 1), b3 + hstep, voffB); PG8_STAGE(PG8_SA(1, 0), a3, voffA);
;             PG8_WAIT_V(8); PG8_WAIT_L(0); PG8_BAR; PG8_MMA(1, 0, At, B0); PG8_MMA(1, 1, At, B1); PG8_BAR; PG8_SCHED;
	v_mfma_f32_16x16x32_bf16 v[66:69], v[184:187], v[238:241], v[66:69]
	v_mfma_f32_16x16x32_bf16 v[66:69], v[190:193], v[242:245], v[66:69]
	s_setprio 0
	s_add_i32 s0, s2, s49
	v_lshl_add_u64 v[168:169], v[168:169], 0, s[76:77]
	s_mov_b32 m0, s0
	ds_read_b128 v[194:197], v189 offset:49152
	ds_read_b128 v[198:201], v189 offset:50176
	ds_read_b128 v[222:225], v189 offset:51200
	ds_read_b128 v[226:229], v189 offset:52224
	ds_read_b128 v[230:233], v189 offset:53248
	ds_read_b128 v[234:237], v189 offset:54272
	ds_read_b128 v[238:241], v189 offset:55296
	ds_read_b128 v[242:245], v189 offset:56320
	global_load_lds_dwordx4 v[168:169], off
	s_add_i32 m0, s0, 0x2000
	s_add_u32 s0, s42, 0x160080
	v_lshl_add_u64 v[168:169], v[172:173], 0, s[76:77]
	s_addc_u32 s1, s43, 0
	s_add_i32 s2, s29, s49
	global_load_lds_dwordx4 v[168:169], off
	v_lshl_add_u64 v[168:169], s[0:1], 0, v[160:161]
	s_mov_b32 m0, s2
	s_nop 0
	global_load_lds_dwordx4 v[168:169], off
	v_lshl_add_u64 v[168:169], s[0:1], 0, v[156:157]
	s_add_i32 m0, s2, 0x2000
	s_nop 0
	global_load_lds_dwordx4 v[168:169], off
	v_lshl_add_u64 v[168:169], v[202:203], 0, s[76:77]
	s_mov_b32 m0, s60
	s_nop 0
	global_load_lds_dwordx4 v[168:169], off
	v_lshl_add_u64 v[168:169], v[212:213], 0, s[76:77]
	s_mov_b32 m0, s61
	s_nop 0
	global_load_lds_dwordx4 v[168:169], off
	s_waitcnt vmcnt(8)
	s_waitcnt lgkmcnt(0)
	s_setprio 1
	s_barrier
	v_mfma_f32_16x16x32_bf16 v[62:65], v[136:139], v[194:197], v[62:65]
	v_mfma_f32_16x16x32_bf16 v[62:65], v[140:143], v[198:201], v[62:65]
	v_mfma_f32_16x16x32_bf16 v[58:61], v[144:147], v[194:197], v[58:61]
	v_mfma_f32_16x16x32_bf16 v[58:61], v[148:151], v[198:201], v[58:61]
	v_mfma_f32_16x16x32_bf16 v[54:57], v[136:139], v[222:225], v[54:57]
	v_mfma_f32_16x16x32_bf16 v[54:57], v[140:143], v[226:229], v[54:57]
	v_mfma_f32_16x16x32_bf16 v[46:49], v[144:147], v[222:225], v[46:49]
	v_mfma_f32_16x16x32_bf16 v[46:49], v[148:151], v[226:229], v[46:49]
	v_mfma_f32_16x16x32_bf16 v[38:41], v[136:139], v[230:233], v[38:41]
	v_mfma_f32_16x16x32_bf16 v[38:41], v[140:143], v[234:237], v[38:41]
	v_mfma_f32_16x16x32_bf16 v[30:33], v[144:147], v[230:233], v[30:33]
	v_mfma_f32_16x16x32_bf16 v[30:33], v[148:151], v[234:237], v[30:33]
	v_mfma_f32_16x16x32_bf16 v[22:25], v[136:139], v[238:241], v[22:25]
	v_mfma_f32_16x16x32_bf16 v[22:25], v[140:143], v[242:245], v[22:25]
	v_mfma_f32_16x16x32_bf16 v[14:17], v[144:147], v[238:241], v[14:17]
	v_mfma_f32_16x16x32_bf16 v[14:17], v[148:151], v[242:245], v[14:17]
	s_setprio 0
	s_setprio 1
	v_mfma_f32_16x16x32_bf16 v[50:53], v[152:155], v[194:197], v[50:53]
	v_mfma_f32_16x16x32_bf16 v[50:53], v[180:183], v[198:201], v[50:53]
	v_mfma_f32_16x16x32_bf16 v[42:45], v[184:187], v[194:197], v[42:45]
	v_mfma_f32_16x16x32_bf16 v[42:45], v[190:193], v[198:201], v[42:45]
	v_mfma_f32_16x16x32_bf16 v[34:37], v[152:155], v[222:225], v[34:37]
	v_mfma_f32_16x16x32_bf16 v[34:37], v[180:183], v[226:229], v[34:37]
	v_mfma_f32_16x16x32_bf16 v[26:29], v[184:187], v[222:225], v[26:29]
	v_mfma_f32_16x16x32_bf16 v[26:29], v[190:193], v[226:229], v[26:29]
	v_mfma_f32_16x16x32_bf16 v[18:21], v[152:155], v[230:233], v[18:21]
	v_mfma_f32_16x16x32_bf16 v[18:21], v[180:183], v[234:237], v[18:21]
	v_mfma_f32_16x16x32_bf16 v[10:13], v[184:187], v[230:233], v[10:13]
	v_mfma_f32_16x16x32_bf16 v[10:13], v[190:193], v[234:237], v[10:13]
	v_mfma_f32_16x16x32_bf16 v[6:9], v[152:155], v[238:241], v[6:9]
	v_mfma_f32_16x16x32_bf16 v[6:9], v[180:183], v[242:245], v[6:9]
	s_setprio 2
	s_barrier
	v_mfma_f32_16x16x32_bf16 v[2:5], v[184:187], v[238:241], v[2:5]
	v_mfma_f32_16x16x32_bf16 v[2:5], v[190:193], v[242:245], v[2:5]
	s_setprio 0
	s_add_i32 s0, s83, 2
	v_lshl_add_u64 v[132:133], v[132:133], 0, s[86:87]
	v_lshl_add_u64 v[134:135], v[134:135], 0, s[86:87]
	s_cmp_ge_i32 s83, s82
	s_mov_b32 s83, s0
	s_cbranch_scc0 .LBB0_1654
	s_and_b64 vcc, exec, s[12:13]
	s_cbranch_vccz .LBB0_1657
	s_barrier

; __global__ void __launch_bounds__(NWAVES * 64, 2) enc_fwd(Args args) {
	.amdhsa_kernel _Z7enc_fwd4Args
		.amdhsa_group_segment_fixed_size 0
		.amdhsa_private_segment_fixed_size 0
		.amdhsa_kernarg_size 552
		.amdhsa_user_sgpr_count 2
		.amdhsa_user_sgpr_dispatch_ptr 0
		.amdhsa_user_sgpr_queue_ptr 0
		.amdhsa_user_sgpr_kernarg_segment_ptr 1
		.amdhsa_user_sgpr_dispatch_id 0
		.amdhsa_user_sgpr_kernarg_preload_length 0
		.amdhsa_user_sgpr_kernarg_preload_offset 0
		.amdhsa_user_sgpr_private_segment_size 0
		.amdhsa_uses_dynamic_stack 0
		.amdhsa_enable_private_segment 0
		.amdhsa_system_sgpr_workgroup_id_x 1
		.amdhsa_system_sgpr_workgroup_id_y 0
		.amdhsa_system_sgpr_workgroup_id_z 0
		.amdhsa_system_sgpr_workgroup_info 0
		.amdhsa_system_vgpr_workitem_id 0
		.amdhsa_next_free_vgpr 256
		.amdhsa_next_free_sgpr 102
		.amdhsa_accum_offset 256
		.amdhsa_reserve_vcc 1
		.amdhsa_float_round_mode_32 0
		.amdhsa_float_round_mode_16_64 0
		.amdhsa_float_denorm_mode_32 3
		.amdhsa_float_denorm_mode_16_64 3
		.amdhsa_dx10_clamp 1
		.amdhsa_ieee_mode 1
		.amdhsa_fp16_overflow 0
		.amdhsa_tg_split 0
		.amdhsa_exception_fp_ieee_invalid_op 0
		.amdhsa_exception_fp_denorm_src 0
		.amdhsa_exception_fp_ieee_div_zero 0
		.amdhsa_exception_fp_ieee_overflow 0
		.amdhsa_exception_fp_ieee_underflow 0
		.amdhsa_exception_fp_ieee_inexact 0
		.amdhsa_exception_int_div_zero 0
	.end_amdhsa_kernel

; __global__ void __launch_bounds__(NWAVES * 64, 2) enc_fwd(Args args) {
.Lfunc_end0:
	.size	_Z7enc_fwd4Args, .Lfunc_end0-_Z7enc_fwd4Args
	.set _Z7enc_fwd4Args.num_vgpr, 256
	.set _Z7enc_fwd4Args.num_agpr, 0
	.set _Z7enc_fwd4Args.numbered_sgpr, 102
	.set _Z7enc_fwd4Args.num_named_barrier, 0
	.set _Z7enc_fwd4Args.private_seg_size, 0
	.set _Z7enc_fwd4Args.uses_vcc, 1
	.set _Z7enc_fwd4Args.uses_flat_scratch, 0
	.set _Z7enc_fwd4Args.has_dyn_sized_stack, 0
	.set _Z7enc_fwd4Args.has_recursion, 0
	.set _Z7enc_fwd4Args.has_indirect_call, 0

; __global__ void __launch_bounds__(NWAVES * 64, 2) enc_fwd(Args args) {
amdhsa.kernels:
  - .agpr_count:     0
    .args:
      - .offset:         0
        .size:           296
        .value_kind:     by_value
      - .offset:         296
        .size:           4
        .value_kind:     hidden_block_count_x
      - .offset:         300
        .size:           4
        .value_kind:     hidden_block_count_y
      - .offset:         304
        .size:           4
        .value_kind:     hidden_block_count_z
      - .offset:         308
        .size:           2
        .value_kind:     hidden_group_size_x
      - .offset:         310
        .size:           2
        .value_kind:     hidden_group_size_y
      - .offset:         312
        .size:           2
        .value_kind:     hidden_group_size_z
      - .offset:         314
        .size:           2
        .value_kind:     hidden_remainder_x
      - .offset:         316
        .size:           2
        .value_kind:     hidden_remainder_y
      - .offset:         318
        .size:           2
        .value_kind:     hidden_remainder_z
      - .offset:         336
        .size:           8
        .value_kind:     hidden_global_offset_x
      - .offset:         344
        .size:           8
        .value_kind:     hidden_global_offset_y
      - .offset:         352
        .size:           8
        .value_kind:     hidden_global_offset_z
      - .offset:         360
        .size:           2
        .value_kind:     hidden_grid_dims
      - .offset:         416
        .size:           4
        .value_kind:     hidden_dynamic_lds_size
    .group_segment_fixed_size: 0
    .kernarg_segment_align: 8
    .kernarg_segment_size: 552
    .language:       OpenCL C
    .language_version:
      - 2
      - 0
    .max_flat_workgroup_size: 512
    .name:           _Z7enc_fwd4Args
    .private_segment_fixed_size: 0
    .sgpr_count:     108
    .sgpr_spill_count: 429
    .symbol:         _Z7enc_fwd4Args.kd
    .uniform_work_group_size: 1
    .uses_dynamic_stack: false
    .vgpr_count:     256
    .vgpr_spill_count: 0
    .wavefront_size: 64
